# FoX epilogue uses prefetched SiLU-gate rows directly; GEMM2 epilogues batch the serialized sigmoid-gate loads of even-m groups
# speedup vs baseline: 1.0054x; 1.0024x over previous
; __device__ __forceinline__ u16 f2bf(float a) { return (u16)(pk2(a, 0.f) & 0xffffu); }
; __device__ __forceinline__ int a_crow(int r, int hi) { return (r & 3) + 8 * (r >> 2) + 4 * hi; }
; template <int MODE> ...
;     ...
;   if (hi == 0) wsf[32 + r32] = gate / l_reg;
;   asm volatile("s_waitcnt lgkmcnt(0)" ::: "memory");
;   float rli[16];
; #pragma unroll
;   for (int r = 0; r < 16; ++r) rli[r] = wsf[32 + a_crow(r, hi)];
; #pragma unroll
;   for (int r = 0; r < 16; ++r) { const int orow = a_crow(r, hi);
; #pragma unroll
;     for (int d0 = 0; d0 < 2; ++d0) stg[orow * 64 + d0 * 32 + r32] = f2bf(o[d0][r] * rli[r]); }
;   asm volatile("s_waitcnt lgkmcnt(0)\n\ts_barrier" ::: "memory");
; __device__ void pc2_phase(const Params& P, int layer, int chunk, char* smem, int* s_item, const int which) {
;     ...
; #pragma unroll
;       for (int i = 0; i < 4; i++) {
;         const int row = i * 8 + er;
;         const uint4 ov = *(const uint4*)(stg + row * 64 + ec);
;         const uint4 zz = *(const uint4*)(pb_ + (size_t)(q0w + row) * INC + C_ZB + head * 64 + ec);
.LBB0_293:
	s_or_b64 exec, exec, s[0:1]
	s_waitcnt lgkmcnt(0)
	ds_read_b128 v[34:37], v251 offset:49280
	v_lshlrev_b32_e32 v33, 13, v203
	v_lshl_or_b32 v50, v221, 1, v33
	v_lshl_add_u32 v50, v197, 1, v50
	ds_read_b128 v[38:41], v251 offset:49312
	ds_read_b128 v[42:45], v251 offset:49344
	ds_read_b128 v[46:49], v251 offset:49376
	s_waitcnt lgkmcnt(3)
	s_nop 0
	v_mul_f32_e32 v0, v0, v34
	v_cvt_pk_bf16_f32 v0, v0, s0
	ds_write_b16 v50, v0 offset:52288
	v_mul_f32_e32 v0, v17, v35
	v_cvt_pk_bf16_f32 v0, v0, s0
	ds_write_b16 v50, v0 offset:52352
	v_mul_f32_e32 v0, v1, v35
	v_cvt_pk_bf16_f32 v0, v0, s0
	ds_write_b16 v50, v0 offset:52416
	v_mul_f32_e32 v0, v18, v36
	v_cvt_pk_bf16_f32 v0, v0, s0
	ds_write_b16 v50, v0 offset:52480
	v_mul_f32_e32 v0, v2, v36
	v_cvt_pk_bf16_f32 v0, v0, s0
	ds_write_b16 v50, v0 offset:52544
	v_mul_f32_e32 v0, v19, v37
	v_cvt_pk_bf16_f32 v0, v0, s0
	ds_write_b16 v50, v0 offset:52608
	v_mul_f32_e32 v0, v3, v37
	v_cvt_pk_bf16_f32 v0, v0, s0
	ds_write_b16 v50, v0 offset:52672
	s_waitcnt lgkmcnt(9)
	v_mul_f32_e32 v0, v20, v38
	v_cvt_pk_bf16_f32 v0, v0, s0
	ds_write_b16 v50, v0 offset:53248
	v_mul_f32_e32 v0, v4, v38
	v_cvt_pk_bf16_f32 v0, v0, s0
	ds_write_b16 v50, v0 offset:53312
	v_mul_f32_e32 v0, v21, v39
	v_cvt_pk_bf16_f32 v0, v0, s0
	ds_write_b16 v50, v0 offset:53376
	v_mul_f32_e32 v0, v5, v39
	v_cvt_pk_bf16_f32 v0, v0, s0
	ds_write_b16 v50, v0 offset:53440
	v_mul_f32_e32 v0, v22, v40
	v_cvt_pk_bf16_f32 v0, v0, s0
	ds_write_b16 v50, v0 offset:53504
	v_mul_f32_e32 v0, v6, v40
	v_cvt_pk_bf16_f32 v0, v0, s0
	ds_write_b16 v50, v0 offset:53568
	v_mul_f32_e32 v0, v23, v41
	v_cvt_pk_bf16_f32 v0, v0, s0
	ds_write_b16 v50, v0 offset:53632
	v_mul_f32_e32 v0, v7, v41
	v_cvt_pk_bf16_f32 v0, v0, s0
	ds_write_b16 v50, v0 offset:53696
	s_waitcnt lgkmcnt(14)
	v_mul_f32_e32 v0, v24, v42
	v_cvt_pk_bf16_f32 v0, v0, s0
	ds_write_b16 v50, v0 offset:54272
	v_mul_f32_e32 v0, v8, v42
	v_cvt_pk_bf16_f32 v0, v0, s0
	ds_write_b16 v50, v0 offset:54336
	v_mul_f32_e32 v0, v25, v43
	v_cvt_pk_bf16_f32 v0, v0, s0
	ds_write_b16 v50, v0 offset:54400
	v_mul_f32_e32 v0, v9, v43
	v_cvt_pk_bf16_f32 v0, v0, s0
	ds_write_b16 v50, v0 offset:54464
	v_mul_f32_e32 v0, v26, v44
	v_cvt_pk_bf16_f32 v0, v0, s0
	ds_write_b16 v50, v0 offset:54528
	v_mul_f32_e32 v0, v10, v44
	v_cvt_pk_bf16_f32 v0, v0, s0
	ds_write_b16 v50, v0 offset:54592
	v_mul_f32_e32 v0, v27, v45
	v_cvt_pk_bf16_f32 v0, v0, s0
	ds_write_b16 v50, v0 offset:54656
	v_mul_f32_e32 v0, v11, v45
	v_cvt_pk_bf16_f32 v0, v0, s0
	ds_write_b16 v50, v0 offset:54720
	v_mul_f32_e32 v0, v28, v46
	v_cvt_pk_bf16_f32 v0, v0, s0
	ds_write_b16 v50, v0 offset:55296
	v_mul_f32_e32 v0, v12, v46
	v_cvt_pk_bf16_f32 v0, v0, s0
	ds_write_b16 v50, v0 offset:55360
	v_mul_f32_e32 v0, v29, v47
	v_cvt_pk_bf16_f32 v0, v0, s0
	ds_write_b16 v50, v0 offset:55424
	v_mul_f32_e32 v0, v13, v47
	v_cvt_pk_bf16_f32 v0, v0, s0
	ds_write_b16 v50, v0 offset:55488
	v_mul_f32_e32 v0, v30, v48
	v_cvt_pk_bf16_f32 v0, v0, s0
	ds_write_b16 v50, v0 offset:55552
	v_mul_f32_e32 v0, v14, v48
	v_cvt_pk_bf16_f32 v0, v0, s0
	ds_write_b16 v50, v0 offset:55616
	v_mul_f32_e32 v0, v31, v49
	v_cvt_pk_bf16_f32 v0, v0, s0
	ds_write_b16 v50, v0 offset:55680
	v_mul_f32_e32 v0, v15, v49
	v_cvt_pk_bf16_f32 v0, v0, s0
	v_bfe_u32 v32, v199, 3, 3
	ds_write_b16 v50, v0 offset:55744
	v_lshlrev_b32_e32 v0, 1, v201
	v_mul_f32_e32 v16, v16, v34
	v_and_b32_e32 v96, 0x70, v0
	v_or_b32_e32 v0, v206, v32
	v_mov_b64_e32 v[2:3], s[8:9]
	s_movk_i32 s7, 0x4680
	v_readlane_b32 s8, v253, 34
	v_cvt_pk_bf16_f32 v16, v16, s0
	v_mad_i64_i32 v[0:1], s[0:1], v0, s7, v[2:3]
	v_readlane_b32 s9, v253, 35
	s_movk_i32 s6, 0x2000
	ds_write_b16 v50, v16 offset:52224
	v_lshl_add_u64 v[0:1], v[0:1], 0, s[8:9]
	v_lshl_add_u64 v[0:1], v[0:1], 0, v[96:97]
	v_add_co_u32_e32 v0, vcc, s6, v0
	s_waitcnt lgkmcnt(0)
	s_barrier
	v_or_b32_e32 v18, v33, v96
	s_nop 0
	v_addc_co_u32_e32 v1, vcc, 0, v1, vcc
	global_load_dwordx4 v[4:7], v[0:1], off offset:3712
	s_mov_b64 s[100:101], 0x23400
	v_lshl_add_u64 v[112:113], v[0:1], 0, s[100:101]
	global_load_dwordx4 v[100:103], v[112:113], off offset:3712
	v_lshl_add_u64 v[112:113], v[112:113], 0, s[100:101]
	global_load_dwordx4 v[104:107], v[112:113], off offset:3712
	v_lshl_add_u64 v[112:113], v[112:113], 0, s[100:101]
	global_load_dwordx4 v[108:111], v[112:113], off offset:3712
	v_lshl_or_b32 v0, v32, 7, v18
	ds_read_b128 v[8:11], v0 offset:52224
	s_lshl_b64 s[0:1], s[2:3], 11
	v_readlane_b32 s44, v253, 44
	v_readlane_b32 s56, v253, 56
	v_readlane_b32 s57, v253, 57
	s_waitcnt lgkmcnt(0)
	v_lshlrev_b32_e32 v16, 16, v8
	v_and_b32_e32 v17, 0xffff0000, v8
	s_mov_b32 s37, 0x20000
	v_readlane_b32 s45, v253, 45
	v_readlane_b32 s46, v253, 46
	v_readlane_b32 s47, v253, 47
	v_readlane_b32 s48, v253, 48
	v_readlane_b32 s49, v253, 49
	v_readlane_b32 s50, v253, 50
	v_readlane_b32 s51, v253, 51
	v_readlane_b32 s52, v253, 52
	v_readlane_b32 s53, v253, 53
	v_readlane_b32 s54, v253, 54
	v_readlane_b32 s55, v253, 55
	v_readlane_b32 s58, v253, 58
	v_readlane_b32 s59, v253, 59
	s_waitcnt vmcnt(0)
; __device__ __forceinline__ float bflo(unsigned u) { return __uint_as_float(u << 16); }
; __device__ __forceinline__ float bfhi(unsigned u) { return __uint_as_float(u & 0xffff0000u); }
; __device__ __forceinline__ float siluf_(float x) { return x * __builtin_amdgcn_rcpf(1.f + __expf(-x)); }
; __device__ void pc2_phase(const Params& P, int layer, int chunk, char* smem, int* s_item, const int which) {
;     ...
; #pragma unroll
;       for (int i = 0; i < 4; i++) {
;         const int row = i * 8 + er;
;         const uint4 ov = *(const uint4*)(stg + row * 64 + ec);
;         const uint4 zz = *(const uint4*)(pb_ + (size_t)(q0w + row) * INC + C_ZB + head * 64 + ec);
;         uint4 y;
;         y.x = pk2(bflo(ov.x) * siluf_(bflo(zz.x)), bfhi(ov.x) * siluf_(bfhi(zz.x)));
;         y.y = pk2(bflo(ov.y) * siluf_(bflo(zz.y)), bfhi(ov.y) * siluf_(bfhi(zz.y)));
;         y.z = pk2(bflo(ov.z) * siluf_(bflo(zz.z)), bfhi(ov.z) * siluf_(bfhi(zz.z)));
;         y.w = pk2(bflo(ov.w) * siluf_(bflo(zz.w)), bfhi(ov.w) * siluf_(bfhi(zz.w)));
;         *(uint4*)(P.yb + (roww + row) * DM + head * 64 + ec) = y;
;       }
	v_lshlrev_b32_e32 v12, 16, v4
	v_and_b32_e32 v13, 0xffff0000, v4
	v_mul_f32_e32 v1, 0xbfb8aa3b, v12
	v_exp_f32_e32 v1, v1
	v_mul_f32_e32 v4, 0xbfb8aa3b, v13
	v_exp_f32_e32 v4, v4
	v_add_f32_e32 v0, 1.0, v1
	v_rcp_f32_e32 v14, v0
	v_add_f32_e32 v0, 1.0, v4
	v_rcp_f32_e32 v15, v0
	v_lshl_add_u64 v[0:1], s[0:1], 0, v[206:207]
	v_pk_mul_f32 v[12:13], v[14:15], v[12:13]
	v_lshlrev_b32_e32 v14, 16, v5
	v_and_b32_e32 v15, 0xffff0000, v5
	v_mul_f32_e32 v4, 0xbfb8aa3b, v14
	v_exp_f32_e32 v8, v4
	v_mul_f32_e32 v4, 0xbfb8aa3b, v15
	v_exp_f32_e32 v19, v4
	v_pk_mul_f32 v[4:5], v[12:13], v[16:17]
	v_add_f32_e32 v8, 1.0, v8
	v_rcp_f32_e32 v12, v8
	v_add_f32_e32 v8, 1.0, v19
	v_rcp_f32_e32 v13, v8
	v_cvt_pk_bf16_f32 v4, v4, v5
	v_lshlrev_b32_e32 v8, 16, v9
	v_and_b32_e32 v9, 0xffff0000, v9
	v_pk_mul_f32 v[12:13], v[12:13], v[14:15]
	v_lshlrev_b32_e32 v14, 16, v6
	v_and_b32_e32 v15, 0xffff0000, v6
	v_mul_f32_e32 v5, 0xbfb8aa3b, v14
	v_exp_f32_e32 v5, v5
	v_mul_f32_e32 v6, 0xbfb8aa3b, v15
	v_exp_f32_e32 v6, v6
	v_pk_mul_f32 v[8:9], v[12:13], v[8:9]
	v_add_f32_e32 v5, 1.0, v5
	v_rcp_f32_e32 v12, v5
	v_add_f32_e32 v5, 1.0, v6
	v_rcp_f32_e32 v13, v5
	v_cvt_pk_bf16_f32 v5, v8, v9
	v_lshlrev_b32_e32 v8, 16, v10
	v_and_b32_e32 v9, 0xffff0000, v10
	v_pk_mul_f32 v[12:13], v[12:13], v[14:15]
	v_lshlrev_b32_e32 v14, 16, v7
	v_and_b32_e32 v15, 0xffff0000, v7
	v_mul_f32_e32 v6, 0xbfb8aa3b, v14
	v_exp_f32_e32 v10, v6
	v_mul_f32_e32 v6, 0xbfb8aa3b, v15
	v_exp_f32_e32 v16, v6
	v_pk_mul_f32 v[6:7], v[12:13], v[8:9]
	v_add_f32_e32 v8, 1.0, v10
	v_rcp_f32_e32 v8, v8
	v_add_f32_e32 v9, 1.0, v16
	v_rcp_f32_e32 v9, v9
	v_lshlrev_b32_e32 v10, 16, v11
	v_and_b32_e32 v11, 0xffff0000, v11
	v_cvt_pk_bf16_f32 v6, v6, v7
	v_pk_mul_f32 v[8:9], v[8:9], v[14:15]
	v_or_b32_e32 v19, 8, v32
	v_pk_mul_f32 v[8:9], v[8:9], v[10:11]
	s_nop 0
	v_cvt_pk_bf16_f32 v7, v8, v9
	v_or_b32_e32 v8, v0, v32
	v_mov_b32_e32 v9, v1
	v_lshlrev_b64 v[8:9], 11, v[8:9]
	v_lshl_add_u64 v[8:9], s[56:57], 0, v[8:9]
	v_lshl_add_u64 v[8:9], v[8:9], 0, s[8:9]
	v_lshl_add_u64 v[8:9], v[8:9], 0, v[96:97]
	global_store_dwordx4 v[8:9], v[4:7], off
	v_lshl_or_b32 v8, v19, 7, v18
	s_nop 0
	v_or_b32_e32 v4, v206, v19
	v_mad_i64_i32 v[4:5], s[0:1], v4, s7, v[2:3]
	v_lshl_add_u64 v[4:5], v[4:5], 0, s[8:9]
	v_lshl_add_u64 v[4:5], v[4:5], 0, v[96:97]
	v_add_co_u32_e32 v4, vcc, s6, v4
	s_nop 1
	v_addc_co_u32_e32 v5, vcc, 0, v5, vcc
	v_mov_b32_e32 v4, v100
	v_mov_b32_e32 v5, v101
	v_mov_b32_e32 v6, v102
	v_mov_b32_e32 v7, v103
	s_nop 0
	v_lshlrev_b32_e32 v12, 16, v4
	v_and_b32_e32 v13, 0xffff0000, v4
	v_mul_f32_e32 v4, 0xbfb8aa3b, v12
	v_exp_f32_e32 v4, v4
	v_mul_f32_e32 v9, 0xbfb8aa3b, v13
	v_exp_f32_e32 v15, v9
	ds_read_b128 v[8:11], v8 offset:52224
	v_add_f32_e32 v4, 1.0, v4
	v_rcp_f32_e32 v14, v4
	v_add_f32_e32 v4, 1.0, v15
	v_rcp_f32_e32 v15, v4
	s_waitcnt lgkmcnt(0)
	v_lshlrev_b32_e32 v16, 16, v8
	v_and_b32_e32 v17, 0xffff0000, v8
	v_pk_mul_f32 v[12:13], v[14:15], v[12:13]
	v_lshlrev_b32_e32 v14, 16, v5
	v_and_b32_e32 v15, 0xffff0000, v5
	v_mul_f32_e32 v4, 0xbfb8aa3b, v14
	v_exp_f32_e32 v8, v4
	v_mul_f32_e32 v4, 0xbfb8aa3b, v15
	v_exp_f32_e32 v20, v4
	v_pk_mul_f32 v[4:5], v[12:13], v[16:17]
	v_add_f32_e32 v8, 1.0, v8
	v_rcp_f32_e32 v12, v8
	v_add_f32_e32 v8, 1.0, v20
	v_rcp_f32_e32 v13, v8
	v_cvt_pk_bf16_f32 v4, v4, v5
	v_lshlrev_b32_e32 v8, 16, v9
	v_and_b32_e32 v9, 0xffff0000, v9
	v_pk_mul_f32 v[12:13], v[12:13], v[14:15]
	v_lshlrev_b32_e32 v14, 16, v6
	v_and_b32_e32 v15, 0xffff0000, v6
	v_mul_f32_e32 v5, 0xbfb8aa3b, v14
	v_exp_f32_e32 v5, v5
	v_mul_f32_e32 v6, 0xbfb8aa3b, v15
	v_exp_f32_e32 v6, v6
	v_pk_mul_f32 v[8:9], v[12:13], v[8:9]
	v_add_f32_e32 v5, 1.0, v5
	v_rcp_f32_e32 v12, v5
	v_add_f32_e32 v5, 1.0, v6
	v_rcp_f32_e32 v13, v5
	v_cvt_pk_bf16_f32 v5, v8, v9
	v_lshlrev_b32_e32 v8, 16, v10
	v_and_b32_e32 v9, 0xffff0000, v10
	v_pk_mul_f32 v[12:13], v[12:13], v[14:15]
	v_lshlrev_b32_e32 v14, 16, v7
	v_and_b32_e32 v15, 0xffff0000, v7
	v_mul_f32_e32 v6, 0xbfb8aa3b, v14
	v_exp_f32_e32 v10, v6
	v_mul_f32_e32 v6, 0xbfb8aa3b, v15
	v_exp_f32_e32 v16, v6
	v_pk_mul_f32 v[6:7], v[12:13], v[8:9]
	v_add_f32_e32 v8, 1.0, v10
	v_rcp_f32_e32 v8, v8
	v_add_f32_e32 v9, 1.0, v16
	v_rcp_f32_e32 v9, v9
	v_lshlrev_b32_e32 v10, 16, v11
	v_and_b32_e32 v11, 0xffff0000, v11
	v_cvt_pk_bf16_f32 v6, v6, v7
	v_pk_mul_f32 v[8:9], v[8:9], v[14:15]
	s_nop 0
	v_pk_mul_f32 v[8:9], v[8:9], v[10:11]
	s_nop 0
	v_cvt_pk_bf16_f32 v7, v8, v9
	v_or_b32_e32 v8, v0, v19
	v_mov_b32_e32 v9, v1
	v_lshlrev_b64 v[8:9], 11, v[8:9]
	v_lshl_add_u64 v[8:9], s[56:57], 0, v[8:9]
	v_lshl_add_u64 v[8:9], v[8:9], 0, s[8:9]
	v_lshl_add_u64 v[8:9], v[8:9], 0, v[96:97]
	v_or_b32_e32 v19, 16, v32
	global_store_dwordx4 v[8:9], v[4:7], off
	v_lshl_or_b32 v8, v19, 7, v18
	s_nop 0
	v_or_b32_e32 v4, v206, v19
	v_mad_i64_i32 v[4:5], s[0:1], v4, s7, v[2:3]
	v_lshl_add_u64 v[4:5], v[4:5], 0, s[8:9]
	v_lshl_add_u64 v[4:5], v[4:5], 0, v[96:97]
	v_add_co_u32_e32 v4, vcc, s6, v4
	s_nop 1
	v_addc_co_u32_e32 v5, vcc, 0, v5, vcc
	v_mov_b32_e32 v4, v104
	v_mov_b32_e32 v5, v105
	v_mov_b32_e32 v6, v106
	v_mov_b32_e32 v7, v107
	s_nop 0
	v_lshlrev_b32_e32 v12, 16, v4
	v_and_b32_e32 v13, 0xffff0000, v4
	v_mul_f32_e32 v4, 0xbfb8aa3b, v12
	v_exp_f32_e32 v4, v4
	v_mul_f32_e32 v9, 0xbfb8aa3b, v13
	v_exp_f32_e32 v15, v9
	ds_read_b128 v[8:11], v8 offset:52224
	v_add_f32_e32 v4, 1.0, v4
	v_rcp_f32_e32 v14, v4
	v_add_f32_e32 v4, 1.0, v15
	v_rcp_f32_e32 v15, v4
	s_waitcnt lgkmcnt(0)
; __device__ __forceinline__ float bflo(unsigned u) { return __uint_as_float(u << 16); }
; __device__ __forceinline__ float bfhi(unsigned u) { return __uint_as_float(u & 0xffff0000u); }
; __device__ __forceinline__ float siluf_(float x) { return x * __builtin_amdgcn_rcpf(1.f + __expf(-x)); }
; __device__ void pc2_phase(const Params& P, int layer, int chunk, char* smem, int* s_item, const int which) {
;     ...
; #pragma unroll
;       for (int i = 0; i < 4; i++) {
;         const int row = i * 8 + er;
;         const uint4 ov = *(const uint4*)(stg + row * 64 + ec);
;         const uint4 zz = *(const uint4*)(pb_ + (size_t)(q0w + row) * INC + C_ZB + head * 64 + ec);
;         uint4 y;
;         y.x = pk2(bflo(ov.x) * siluf_(bflo(zz.x)), bfhi(ov.x) * siluf_(bfhi(zz.x)));
;         y.y = pk2(bflo(ov.y) * siluf_(bflo(zz.y)), bfhi(ov.y) * siluf_(bfhi(zz.y)));
;         y.z = pk2(bflo(ov.z) * siluf_(bflo(zz.z)), bfhi(ov.z) * siluf_(bfhi(zz.z)));
;         y.w = pk2(bflo(ov.w) * siluf_(bflo(zz.w)), bfhi(ov.w) * siluf_(bfhi(zz.w)));
;         *(uint4*)(P.yb + (roww + row) * DM + head * 64 + ec) = y;
;       }
	v_lshlrev_b32_e32 v16, 16, v8
	v_and_b32_e32 v17, 0xffff0000, v8
	v_pk_mul_f32 v[12:13], v[14:15], v[12:13]
	v_lshlrev_b32_e32 v14, 16, v5
	v_and_b32_e32 v15, 0xffff0000, v5
	v_mul_f32_e32 v4, 0xbfb8aa3b, v14
	v_exp_f32_e32 v8, v4
	v_mul_f32_e32 v4, 0xbfb8aa3b, v15
	v_exp_f32_e32 v20, v4
	v_pk_mul_f32 v[4:5], v[12:13], v[16:17]
	v_add_f32_e32 v8, 1.0, v8
	v_rcp_f32_e32 v12, v8
	v_add_f32_e32 v8, 1.0, v20
	v_rcp_f32_e32 v13, v8
	v_cvt_pk_bf16_f32 v4, v4, v5
	v_lshlrev_b32_e32 v8, 16, v9
	v_and_b32_e32 v9, 0xffff0000, v9
	v_pk_mul_f32 v[12:13], v[12:13], v[14:15]
	v_lshlrev_b32_e32 v14, 16, v6
	v_and_b32_e32 v15, 0xffff0000, v6
	v_mul_f32_e32 v5, 0xbfb8aa3b, v14
	v_exp_f32_e32 v5, v5
	v_mul_f32_e32 v6, 0xbfb8aa3b, v15
	v_exp_f32_e32 v6, v6
	v_pk_mul_f32 v[8:9], v[12:13], v[8:9]
	v_add_f32_e32 v5, 1.0, v5
	v_rcp_f32_e32 v12, v5
	v_add_f32_e32 v5, 1.0, v6
	v_rcp_f32_e32 v13, v5
	v_cvt_pk_bf16_f32 v5, v8, v9
	v_lshlrev_b32_e32 v8, 16, v10
	v_and_b32_e32 v9, 0xffff0000, v10
	v_pk_mul_f32 v[12:13], v[12:13], v[14:15]
	v_lshlrev_b32_e32 v14, 16, v7
	v_and_b32_e32 v15, 0xffff0000, v7
	v_mul_f32_e32 v6, 0xbfb8aa3b, v14
	v_exp_f32_e32 v10, v6
	v_mul_f32_e32 v6, 0xbfb8aa3b, v15
	v_exp_f32_e32 v16, v6
	v_pk_mul_f32 v[6:7], v[12:13], v[8:9]
	v_add_f32_e32 v8, 1.0, v10
	v_rcp_f32_e32 v8, v8
	v_add_f32_e32 v9, 1.0, v16
	v_rcp_f32_e32 v9, v9
	v_lshlrev_b32_e32 v10, 16, v11
	v_and_b32_e32 v11, 0xffff0000, v11
	v_cvt_pk_bf16_f32 v6, v6, v7
	v_pk_mul_f32 v[8:9], v[8:9], v[14:15]
	s_nop 0
	v_pk_mul_f32 v[8:9], v[8:9], v[10:11]
	s_nop 0
	v_cvt_pk_bf16_f32 v7, v8, v9
	v_or_b32_e32 v8, v0, v19
	v_mov_b32_e32 v9, v1
	v_lshlrev_b64 v[8:9], 11, v[8:9]
	v_lshl_add_u64 v[8:9], s[56:57], 0, v[8:9]
	v_lshl_add_u64 v[8:9], v[8:9], 0, s[8:9]
	v_lshl_add_u64 v[8:9], v[8:9], 0, v[96:97]
	v_or_b32_e32 v19, 24, v32
	global_store_dwordx4 v[8:9], v[4:7], off
	v_or_b32_e32 v0, v0, v19
	v_lshlrev_b64 v[0:1], 11, v[0:1]
	v_or_b32_e32 v4, v206, v19
	v_mad_i64_i32 v[2:3], s[0:1], v4, s7, v[2:3]
	v_lshl_add_u64 v[2:3], v[2:3], 0, s[8:9]
	v_lshl_add_u64 v[2:3], v[2:3], 0, v[96:97]
	v_add_co_u32_e32 v2, vcc, s6, v2
	v_lshl_or_b32 v6, v19, 7, v18
	s_nop 0
	v_addc_co_u32_e32 v3, vcc, 0, v3, vcc
	v_mov_b32_e32 v2, v108
	v_mov_b32_e32 v3, v109
	v_mov_b32_e32 v4, v110
	v_mov_b32_e32 v5, v111
	ds_read_b128 v[6:9], v6 offset:52224
	v_lshl_add_u64 v[0:1], s[56:57], 0, v[0:1]
	v_lshl_add_u64 v[0:1], v[0:1], 0, s[8:9]
	v_lshl_add_u64 v[0:1], v[0:1], 0, v[96:97]
	s_waitcnt lgkmcnt(0)
	v_lshlrev_b32_e32 v10, 16, v6
	v_and_b32_e32 v11, 0xffff0000, v6
	s_nop 0
	v_lshlrev_b32_e32 v12, 16, v2
	v_and_b32_e32 v13, 0xffff0000, v2
	v_lshlrev_b32_e32 v14, 16, v3
	v_and_b32_e32 v15, 0xffff0000, v3
	v_mul_f32_e32 v2, 0xbfb8aa3b, v12
	v_mul_f32_e32 v3, 0xbfb8aa3b, v13
	v_exp_f32_e32 v2, v2
	v_exp_f32_e32 v3, v3
	v_mul_f32_e32 v6, 0xbfb8aa3b, v14
	v_mul_f32_e32 v16, 0xbfb8aa3b, v15
	v_add_f32_e32 v2, 1.0, v2
	v_add_f32_e32 v3, 1.0, v3
	v_rcp_f32_e32 v2, v2
	v_rcp_f32_e32 v3, v3
	v_exp_f32_e32 v6, v6
	v_exp_f32_e32 v16, v16
	v_pk_mul_f32 v[2:3], v[2:3], v[12:13]
	s_nop 0
	v_pk_mul_f32 v[2:3], v[2:3], v[10:11]
	v_lshlrev_b32_e32 v12, 16, v4
	v_add_f32_e32 v6, 1.0, v6
	v_add_f32_e32 v17, 1.0, v16
	v_cvt_pk_bf16_f32 v2, v2, v3
	v_and_b32_e32 v13, 0xffff0000, v4
	v_mul_f32_e32 v3, 0xbfb8aa3b, v12
	v_rcp_f32_e32 v16, v6
	v_rcp_f32_e32 v17, v17
	v_exp_f32_e32 v3, v3
	v_mul_f32_e32 v4, 0xbfb8aa3b, v13
	v_exp_f32_e32 v4, v4
	v_lshlrev_b32_e32 v6, 16, v7
	v_and_b32_e32 v7, 0xffff0000, v7
	v_pk_mul_f32 v[10:11], v[16:17], v[14:15]
	v_add_f32_e32 v3, 1.0, v3
	v_pk_mul_f32 v[6:7], v[10:11], v[6:7]
	v_rcp_f32_e32 v10, v3
	v_add_f32_e32 v3, 1.0, v4
	v_rcp_f32_e32 v11, v3
	v_cvt_pk_bf16_f32 v3, v6, v7
	v_lshlrev_b32_e32 v6, 16, v8
	v_and_b32_e32 v7, 0xffff0000, v8
	v_pk_mul_f32 v[10:11], v[10:11], v[12:13]
	v_lshlrev_b32_e32 v12, 16, v5
	v_and_b32_e32 v13, 0xffff0000, v5
	v_mul_f32_e32 v4, 0xbfb8aa3b, v12
	v_exp_f32_e32 v8, v4
	v_mul_f32_e32 v4, 0xbfb8aa3b, v13
	v_exp_f32_e32 v14, v4
	v_pk_mul_f32 v[4:5], v[10:11], v[6:7]
	v_add_f32_e32 v6, 1.0, v8
	v_rcp_f32_e32 v6, v6
	v_add_f32_e32 v7, 1.0, v14
	v_rcp_f32_e32 v7, v7
	v_lshlrev_b32_e32 v8, 16, v9
	v_and_b32_e32 v9, 0xffff0000, v9
	v_cvt_pk_bf16_f32 v4, v4, v5
	v_pk_mul_f32 v[6:7], v[6:7], v[12:13]
	s_nop 0
	v_pk_mul_f32 v[6:7], v[6:7], v[8:9]
	s_nop 0
	v_cvt_pk_bf16_f32 v5, v6, v7
	global_store_dwordx4 v[0:1], v[2:5], off

; __device__ __forceinline__ float bflo(unsigned u) { return __uint_as_float(u << 16); }
; __device__ __forceinline__ float bfhi(unsigned u) { return __uint_as_float(u & 0xffff0000u); }
; __device__ __forceinline__ float sigmoidf_(float x) { return __builtin_amdgcn_rcpf(1.f + __expf(-x)); }
; __device__ __forceinline__ int opaque_tid() { int t = threadIdx.x; asm volatile("" : "+v"(t)); return t; }
; __device__ void gemm2_phase(const Params& P, int layer, char* smem) {
;     ...
;     {
;       const int tid2 = opaque_tid(), wid2 = tid2 >> 6, lane2 = tid2 & 63, wr2 = wid2 >> 2, wc2 = wid2 & 3, fr2 = lane2 & 15, fq2 = lane2 >> 4;
;       const u16* pp = P.proj + (size_t)(u.pm * 256 + wr2 * 128 + fr2) * INC + u.pn * 256 + wc2 * 64 + fq2 * 4;
; #pragma unroll
;       for (int m = 0; m < 8; m++) {
; #pragma unroll
;         for (int n = 0; n < 4; n++) {
;           const uint2 rb = *(const uint2*)(pp + (size_t)(m * 16) * INC + C_RB + n * 16);
;           acc[m][n][0] *= sigmoidf_(bflo(rb.x)); acc[m][n][1] *= sigmoidf_(bfhi(rb.x));
;           acc[m][n][2] *= sigmoidf_(bflo(rb.y)); acc[m][n][3] *= sigmoidf_(bfhi(rb.y));
;         }
;         if (m & 1) __builtin_amdgcn_sched_barrier(0);
;       }
.LBB0_590:
	v_mov_b32_e32 v140, v195
	v_mov_b32_e32 v135, v97
	v_ashrrev_i32_e32 v96, 1, v140
	v_and_b32_e32 v96, 0xffffff80, v96
	v_add_u32_e32 v98, s10, v96
	v_readlane_b32 s8, v253, 27
	v_readlane_b32 s9, v253, 28
	v_and_or_b32 v96, v140, 15, v98
	v_lshrrev_b32_e32 v141, 1, v140
	v_mov_b64_e32 v[132:133], s[8:9]
	s_movk_i32 s8, 0x4680
	v_mad_i64_i32 v[132:133], s[8:9], v96, s8, v[132:133]
	v_and_b32_e32 v96, 0xc0, v140
	v_lshl_add_u64 v[132:133], v[132:133], 0, s[6:7]
	v_lshlrev_b32_e32 v96, 1, v96
	v_lshl_add_u64 v[132:133], v[132:133], 0, v[96:97]
	v_and_b32_e32 v134, 24, v141
	v_lshl_add_u64 v[132:133], v[132:133], 0, v[134:135]
	s_movk_i32 s8, 0x3000
	v_add_co_u32_e32 v134, vcc, s8, v132
	s_mov_b32 s8, 0x4a000
	s_nop 0
	v_addc_co_u32_e32 v135, vcc, 0, v133, vcc
	global_load_dwordx2 v[136:137], v[134:135], off offset:3712
	global_load_dwordx2 v[204:205], v[134:135], off offset:3744
	global_load_dwordx2 v[206:207], v[134:135], off offset:3776
	global_load_dwordx2 v[208:209], v[134:135], off offset:3808
	v_readlane_b32 s10, v253, 29
	v_readlane_b32 s11, v253, 30
	s_waitcnt vmcnt(0)
	v_lshlrev_b32_e32 v99, 16, v136
	v_mul_f32_e32 v99, 0xbfb8aa3b, v99
	v_exp_f32_e32 v99, v99
	s_nop 0
	v_add_f32_e32 v99, 1.0, v99
	v_rcp_f32_e32 v138, v99
	v_and_b32_e32 v99, 0xffff0000, v136
	v_mul_f32_e32 v99, 0xbfb8aa3b, v99
	v_exp_f32_e32 v99, v99
	s_nop 0
	v_add_f32_e32 v99, 1.0, v99
	v_rcp_f32_e32 v139, v99
	v_lshlrev_b32_e32 v99, 16, v137
	v_mul_f32_e32 v99, 0xbfb8aa3b, v99
	v_exp_f32_e32 v99, v99
	v_pk_mul_f32 v[124:125], v[124:125], v[138:139]
	v_add_f32_e32 v99, 1.0, v99
	v_rcp_f32_e32 v136, v99
	v_and_b32_e32 v99, 0xffff0000, v137
	v_mul_f32_e32 v99, 0xbfb8aa3b, v99
	v_exp_f32_e32 v99, v99
	s_nop 0
	v_add_f32_e32 v99, 1.0, v99
	v_rcp_f32_e32 v137, v99
	s_nop 0
	v_pk_mul_f32 v[126:127], v[126:127], v[136:137]
	v_mov_b32_e32 v136, v204
	v_mov_b32_e32 v137, v205
	s_waitcnt vmcnt(0)
	v_lshlrev_b32_e32 v99, 16, v136
	v_mul_f32_e32 v99, 0xbfb8aa3b, v99
	v_exp_f32_e32 v99, v99
	s_nop 0
	v_add_f32_e32 v99, 1.0, v99
	v_rcp_f32_e32 v138, v99
	v_and_b32_e32 v99, 0xffff0000, v136
	v_mul_f32_e32 v99, 0xbfb8aa3b, v99
	v_exp_f32_e32 v99, v99
	s_nop 0
	v_add_f32_e32 v99, 1.0, v99
	v_rcp_f32_e32 v139, v99
	v_lshlrev_b32_e32 v99, 16, v137
	v_mul_f32_e32 v99, 0xbfb8aa3b, v99
	v_exp_f32_e32 v99, v99
	v_pk_mul_f32 v[128:129], v[128:129], v[138:139]
	v_add_f32_e32 v99, 1.0, v99
	v_rcp_f32_e32 v136, v99
	v_and_b32_e32 v99, 0xffff0000, v137
	v_mul_f32_e32 v99, 0xbfb8aa3b, v99
	v_exp_f32_e32 v99, v99
	s_nop 0
	v_add_f32_e32 v99, 1.0, v99
	v_rcp_f32_e32 v137, v99
	s_nop 0
	v_pk_mul_f32 v[130:131], v[130:131], v[136:137]
	v_mov_b32_e32 v136, v206
	v_mov_b32_e32 v137, v207
	s_waitcnt vmcnt(0)
	v_lshlrev_b32_e32 v99, 16, v136
	v_mov_b32_e32 v134, v208
	v_mov_b32_e32 v135, v209
	v_mul_f32_e32 v99, 0xbfb8aa3b, v99
	v_exp_f32_e32 v99, v99
	s_nop 0
	v_add_f32_e32 v99, 1.0, v99
	v_rcp_f32_e32 v138, v99
	v_and_b32_e32 v99, 0xffff0000, v136
	v_mul_f32_e32 v99, 0xbfb8aa3b, v99
	v_exp_f32_e32 v99, v99
	s_nop 0
	v_add_f32_e32 v99, 1.0, v99
	v_rcp_f32_e32 v139, v99
	v_lshlrev_b32_e32 v99, 16, v137
	v_mul_f32_e32 v99, 0xbfb8aa3b, v99
	v_exp_f32_e32 v99, v99
	v_pk_mul_f32 v[120:121], v[120:121], v[138:139]
	v_add_f32_e32 v99, 1.0, v99
	v_rcp_f32_e32 v136, v99
	v_and_b32_e32 v99, 0xffff0000, v137
	v_mul_f32_e32 v99, 0xbfb8aa3b, v99
	v_exp_f32_e32 v99, v99
	s_nop 0
	v_add_f32_e32 v99, 1.0, v99
	v_rcp_f32_e32 v137, v99
	s_waitcnt vmcnt(0)
	v_lshlrev_b32_e32 v99, 16, v134
	v_mul_f32_e32 v99, 0xbfb8aa3b, v99
	v_exp_f32_e32 v99, v99
	v_pk_mul_f32 v[122:123], v[122:123], v[136:137]
	v_add_f32_e32 v99, 1.0, v99
	v_rcp_f32_e32 v136, v99
	v_and_b32_e32 v99, 0xffff0000, v134
	v_mul_f32_e32 v99, 0xbfb8aa3b, v99
	v_exp_f32_e32 v99, v99
	s_nop 0
	v_add_f32_e32 v99, 1.0, v99
	v_rcp_f32_e32 v137, v99
	v_lshlrev_b32_e32 v99, 16, v135
	v_mul_f32_e32 v99, 0xbfb8aa3b, v99
	v_exp_f32_e32 v99, v99
	v_pk_mul_f32 v[116:117], v[116:117], v[136:137]
	v_add_f32_e32 v99, 1.0, v99
	v_rcp_f32_e32 v134, v99
	v_and_b32_e32 v99, 0xffff0000, v135
	v_mul_f32_e32 v99, 0xbfb8aa3b, v99
	v_exp_f32_e32 v99, v99
	s_nop 0
	v_add_f32_e32 v99, 1.0, v99
	v_rcp_f32_e32 v135, v99
	s_nop 0
	v_pk_mul_f32 v[118:119], v[118:119], v[134:135]
	v_add_co_u32_e32 v134, vcc, s8, v132
	s_nop 1
	v_addc_co_u32_e32 v135, vcc, 0, v133, vcc
	global_load_dwordx2 v[136:137], v[134:135], off offset:1728
	global_load_dwordx2 v[138:139], v[134:135], off offset:1696
	global_load_dwordx2 v[142:143], v[134:135], off offset:1664
	s_waitcnt vmcnt(0)
	v_lshlrev_b32_e32 v99, 16, v142
	v_mul_f32_e32 v99, 0xbfb8aa3b, v99
	v_exp_f32_e32 v99, v99
	global_load_dwordx2 v[134:135], v[134:135], off offset:1760
	v_add_f32_e32 v99, 1.0, v99
	v_rcp_f32_e32 v144, v99
	v_and_b32_e32 v99, 0xffff0000, v142
	v_mul_f32_e32 v99, 0xbfb8aa3b, v99
	v_exp_f32_e32 v99, v99
	s_nop 0
	v_add_f32_e32 v99, 1.0, v99
	v_rcp_f32_e32 v145, v99
	v_lshlrev_b32_e32 v99, 16, v143
	v_mul_f32_e32 v99, 0xbfb8aa3b, v99
	v_exp_f32_e32 v99, v99
	v_pk_mul_f32 v[112:113], v[112:113], v[144:145]
	v_add_f32_e32 v99, 1.0, v99
	v_rcp_f32_e32 v142, v99
	v_and_b32_e32 v99, 0xffff0000, v143
	v_mul_f32_e32 v99, 0xbfb8aa3b, v99
	v_exp_f32_e32 v99, v99
	s_nop 0
	v_add_f32_e32 v99, 1.0, v99
	v_rcp_f32_e32 v143, v99
	v_lshlrev_b32_e32 v99, 16, v138
	v_mul_f32_e32 v99, 0xbfb8aa3b, v99
	v_exp_f32_e32 v99, v99
	v_pk_mul_f32 v[114:115], v[114:115], v[142:143]
	v_add_f32_e32 v99, 1.0, v99
	v_rcp_f32_e32 v142, v99
	v_and_b32_e32 v99, 0xffff0000, v138
	v_mul_f32_e32 v99, 0xbfb8aa3b, v99
	v_exp_f32_e32 v99, v99
	s_nop 0
	v_add_f32_e32 v99, 1.0, v99
	v_rcp_f32_e32 v143, v99
	v_lshlrev_b32_e32 v99, 16, v139
	v_mul_f32_e32 v99, 0xbfb8aa3b, v99
	v_exp_f32_e32 v99, v99
	v_pk_mul_f32 v[108:109], v[108:109], v[142:143]
	v_add_f32_e32 v99, 1.0, v99
	v_rcp_f32_e32 v138, v99
	v_and_b32_e32 v99, 0xffff0000, v139
	v_mul_f32_e32 v99, 0xbfb8aa3b, v99
	v_exp_f32_e32 v99, v99
	s_nop 0
	v_add_f32_e32 v99, 1.0, v99
	v_rcp_f32_e32 v139, v99
	v_lshlrev_b32_e32 v99, 16, v136
	v_mul_f32_e32 v99, 0xbfb8aa3b, v99
	v_exp_f32_e32 v99, v99
	v_pk_mul_f32 v[110:111], v[110:111], v[138:139]
	v_add_f32_e32 v99, 1.0, v99
	v_rcp_f32_e32 v138, v99
	v_and_b32_e32 v99, 0xffff0000, v136
	v_mul_f32_e32 v99, 0xbfb8aa3b, v99
	v_exp_f32_e32 v99, v99
	s_nop 0
	v_add_f32_e32 v99, 1.0, v99
	v_rcp_f32_e32 v139, v99
	v_lshlrev_b32_e32 v99, 16, v137
	v_mul_f32_e32 v99, 0xbfb8aa3b, v99
	v_exp_f32_e32 v99, v99
	v_pk_mul_f32 v[104:105], v[104:105], v[138:139]
	v_add_f32_e32 v99, 1.0, v99
	v_rcp_f32_e32 v136, v99
	v_and_b32_e32 v99, 0xffff0000, v137
	v_mul_f32_e32 v99, 0xbfb8aa3b, v99
	v_exp_f32_e32 v99, v99
	s_nop 0
	v_add_f32_e32 v99, 1.0, v99
	v_rcp_f32_e32 v137, v99
	s_waitcnt vmcnt(0)
; __device__ __forceinline__ float bflo(unsigned u) { return __uint_as_float(u << 16); }
; __device__ __forceinline__ float bfhi(unsigned u) { return __uint_as_float(u & 0xffff0000u); }
; __device__ __forceinline__ float sigmoidf_(float x) { return __builtin_amdgcn_rcpf(1.f + __expf(-x)); }
; __device__ __forceinline__ int opaque_tid() { int t = threadIdx.x; asm volatile("" : "+v"(t)); return t; }
; __device__ void gemm2_phase(const Params& P, int layer, char* smem) {
;     ...
;     {
;       const int tid2 = opaque_tid(), wid2 = tid2 >> 6, lane2 = tid2 & 63, wr2 = wid2 >> 2, wc2 = wid2 & 3, fr2 = lane2 & 15, fq2 = lane2 >> 4;
;       const u16* pp = P.proj + (size_t)(u.pm * 256 + wr2 * 128 + fr2) * INC + u.pn * 256 + wc2 * 64 + fq2 * 4;
; #pragma unroll
;       for (int m = 0; m < 8; m++) {
; #pragma unroll
;         for (int n = 0; n < 4; n++) {
;           const uint2 rb = *(const uint2*)(pp + (size_t)(m * 16) * INC + C_RB + n * 16);
;           acc[m][n][0] *= sigmoidf_(bflo(rb.x)); acc[m][n][1] *= sigmoidf_(bfhi(rb.x));
;           acc[m][n][2] *= sigmoidf_(bflo(rb.y)); acc[m][n][3] *= sigmoidf_(bfhi(rb.y));
;         }
;         if (m & 1) __builtin_amdgcn_sched_barrier(0);
;       }
	v_lshlrev_b32_e32 v99, 16, v134
	v_mul_f32_e32 v99, 0xbfb8aa3b, v99
	v_exp_f32_e32 v99, v99
	v_pk_mul_f32 v[106:107], v[106:107], v[136:137]
	v_add_f32_e32 v99, 1.0, v99
	v_rcp_f32_e32 v136, v99
	v_and_b32_e32 v99, 0xffff0000, v134
	v_mul_f32_e32 v99, 0xbfb8aa3b, v99
	v_exp_f32_e32 v99, v99
	s_nop 0
	v_add_f32_e32 v99, 1.0, v99
	v_rcp_f32_e32 v137, v99
	v_lshlrev_b32_e32 v99, 16, v135
	v_mul_f32_e32 v99, 0xbfb8aa3b, v99
	v_exp_f32_e32 v99, v99
	v_pk_mul_f32 v[92:93], v[92:93], v[136:137]
	v_add_f32_e32 v99, 1.0, v99
	v_rcp_f32_e32 v134, v99
	v_and_b32_e32 v99, 0xffff0000, v135
	v_mul_f32_e32 v99, 0xbfb8aa3b, v99
	v_exp_f32_e32 v99, v99
	s_nop 0
	v_add_f32_e32 v99, 1.0, v99
	v_rcp_f32_e32 v135, v99
	s_nop 0
	v_pk_mul_f32 v[94:95], v[94:95], v[134:135]
	s_mov_b32 s8, 0x90000
	v_add_co_u32_e32 v134, vcc, s8, v132
	s_mov_b32 s8, 0xd7000
	s_nop 0
	v_addc_co_u32_e32 v135, vcc, 0, v133, vcc
	global_load_dwordx2 v[136:137], v[134:135], off offset:3712
	global_load_dwordx2 v[204:205], v[134:135], off offset:3744
	global_load_dwordx2 v[206:207], v[134:135], off offset:3776
	global_load_dwordx2 v[208:209], v[134:135], off offset:3808
	s_waitcnt vmcnt(0)
	v_lshlrev_b32_e32 v99, 16, v136
	v_mul_f32_e32 v99, 0xbfb8aa3b, v99
	v_exp_f32_e32 v99, v99
	s_nop 0
	v_add_f32_e32 v99, 1.0, v99
	v_rcp_f32_e32 v138, v99
	v_and_b32_e32 v99, 0xffff0000, v136
	v_mul_f32_e32 v99, 0xbfb8aa3b, v99
	v_exp_f32_e32 v99, v99
	s_nop 0
	v_add_f32_e32 v99, 1.0, v99
	v_rcp_f32_e32 v139, v99
	v_lshlrev_b32_e32 v99, 16, v137
	v_mul_f32_e32 v99, 0xbfb8aa3b, v99
	v_exp_f32_e32 v99, v99
	v_pk_mul_f32 v[100:101], v[100:101], v[138:139]
	v_add_f32_e32 v99, 1.0, v99
	v_rcp_f32_e32 v136, v99
	v_and_b32_e32 v99, 0xffff0000, v137
	v_mul_f32_e32 v99, 0xbfb8aa3b, v99
	v_exp_f32_e32 v99, v99
	s_nop 0
	v_add_f32_e32 v99, 1.0, v99
	v_rcp_f32_e32 v137, v99
	s_nop 0
	v_pk_mul_f32 v[102:103], v[102:103], v[136:137]
	v_mov_b32_e32 v136, v204
	v_mov_b32_e32 v137, v205
	s_waitcnt vmcnt(0)
	v_lshlrev_b32_e32 v99, 16, v136
	v_mul_f32_e32 v99, 0xbfb8aa3b, v99
	v_exp_f32_e32 v99, v99
	s_nop 0
	v_add_f32_e32 v99, 1.0, v99
	v_rcp_f32_e32 v138, v99
	v_and_b32_e32 v99, 0xffff0000, v136
	v_mul_f32_e32 v99, 0xbfb8aa3b, v99
	v_exp_f32_e32 v99, v99
	s_nop 0
	v_add_f32_e32 v99, 1.0, v99
	v_rcp_f32_e32 v139, v99
	v_lshlrev_b32_e32 v99, 16, v137
	v_mul_f32_e32 v99, 0xbfb8aa3b, v99
	v_exp_f32_e32 v99, v99
	v_pk_mul_f32 v[88:89], v[88:89], v[138:139]
	v_add_f32_e32 v99, 1.0, v99
	v_rcp_f32_e32 v136, v99
	v_and_b32_e32 v99, 0xffff0000, v137
	v_mul_f32_e32 v99, 0xbfb8aa3b, v99
	v_exp_f32_e32 v99, v99
	s_nop 0
	v_add_f32_e32 v99, 1.0, v99
	v_rcp_f32_e32 v137, v99
	s_nop 0
	v_pk_mul_f32 v[90:91], v[90:91], v[136:137]
	v_mov_b32_e32 v136, v206
	v_mov_b32_e32 v137, v207
	s_waitcnt vmcnt(0)
	v_lshlrev_b32_e32 v99, 16, v136
	v_mov_b32_e32 v134, v208
	v_mov_b32_e32 v135, v209
	v_mul_f32_e32 v99, 0xbfb8aa3b, v99
	v_exp_f32_e32 v99, v99
	s_nop 0
	v_add_f32_e32 v99, 1.0, v99
	v_rcp_f32_e32 v138, v99
	v_and_b32_e32 v99, 0xffff0000, v136
	v_mul_f32_e32 v99, 0xbfb8aa3b, v99
	v_exp_f32_e32 v99, v99
	s_nop 0
	v_add_f32_e32 v99, 1.0, v99
	v_rcp_f32_e32 v139, v99
	v_lshlrev_b32_e32 v99, 16, v137
	v_mul_f32_e32 v99, 0xbfb8aa3b, v99
	v_exp_f32_e32 v99, v99
	v_pk_mul_f32 v[84:85], v[84:85], v[138:139]
	v_add_f32_e32 v99, 1.0, v99
	v_rcp_f32_e32 v136, v99
	v_and_b32_e32 v99, 0xffff0000, v137
	v_mul_f32_e32 v99, 0xbfb8aa3b, v99
	v_exp_f32_e32 v99, v99
	s_nop 0
	v_add_f32_e32 v99, 1.0, v99
	v_rcp_f32_e32 v137, v99
	s_waitcnt vmcnt(0)
	v_lshlrev_b32_e32 v99, 16, v134
	v_mul_f32_e32 v99, 0xbfb8aa3b, v99
	v_exp_f32_e32 v99, v99
	v_pk_mul_f32 v[86:87], v[86:87], v[136:137]
	v_add_f32_e32 v99, 1.0, v99
	v_rcp_f32_e32 v136, v99
	v_and_b32_e32 v99, 0xffff0000, v134
	v_mul_f32_e32 v99, 0xbfb8aa3b, v99
	v_exp_f32_e32 v99, v99
	s_nop 0
	v_add_f32_e32 v99, 1.0, v99
	v_rcp_f32_e32 v137, v99
	v_lshlrev_b32_e32 v99, 16, v135
	v_mul_f32_e32 v99, 0xbfb8aa3b, v99
	v_exp_f32_e32 v99, v99
	v_pk_mul_f32 v[80:81], v[80:81], v[136:137]
	v_add_f32_e32 v99, 1.0, v99
	v_rcp_f32_e32 v134, v99
	v_and_b32_e32 v99, 0xffff0000, v135
	v_mul_f32_e32 v99, 0xbfb8aa3b, v99
	v_exp_f32_e32 v99, v99
	s_nop 0
	v_add_f32_e32 v99, 1.0, v99
	v_rcp_f32_e32 v135, v99
	s_nop 0
	v_pk_mul_f32 v[82:83], v[82:83], v[134:135]
	v_add_co_u32_e32 v134, vcc, s8, v132
	s_nop 1
	v_addc_co_u32_e32 v135, vcc, 0, v133, vcc
	global_load_dwordx2 v[136:137], v[134:135], off offset:1728
	global_load_dwordx2 v[138:139], v[134:135], off offset:1696
	global_load_dwordx2 v[142:143], v[134:135], off offset:1664
	s_waitcnt vmcnt(0)
; __device__ __forceinline__ float bflo(unsigned u) { return __uint_as_float(u << 16); }
; __device__ __forceinline__ float bfhi(unsigned u) { return __uint_as_float(u & 0xffff0000u); }
; __device__ __forceinline__ float sigmoidf_(float x) { return __builtin_amdgcn_rcpf(1.f + __expf(-x)); }
; __device__ __forceinline__ int opaque_tid() { int t = threadIdx.x; asm volatile("" : "+v"(t)); return t; }
; __device__ void gemm2_phase(const Params& P, int layer, char* smem) {
;     ...
;     {
;       const int tid2 = opaque_tid(), wid2 = tid2 >> 6, lane2 = tid2 & 63, wr2 = wid2 >> 2, wc2 = wid2 & 3, fr2 = lane2 & 15, fq2 = lane2 >> 4;
;       const u16* pp = P.proj + (size_t)(u.pm * 256 + wr2 * 128 + fr2) * INC + u.pn * 256 + wc2 * 64 + fq2 * 4;
; #pragma unroll
;       for (int m = 0; m < 8; m++) {
; #pragma unroll
;         for (int n = 0; n < 4; n++) {
;           const uint2 rb = *(const uint2*)(pp + (size_t)(m * 16) * INC + C_RB + n * 16);
;           acc[m][n][0] *= sigmoidf_(bflo(rb.x)); acc[m][n][1] *= sigmoidf_(bfhi(rb.x));
;           acc[m][n][2] *= sigmoidf_(bflo(rb.y)); acc[m][n][3] *= sigmoidf_(bfhi(rb.y));
;         }
;         if (m & 1) __builtin_amdgcn_sched_barrier(0);
;       }
	v_lshlrev_b32_e32 v99, 16, v142
	v_mul_f32_e32 v99, 0xbfb8aa3b, v99
	v_exp_f32_e32 v99, v99
	s_nop 0
	v_add_f32_e32 v99, 1.0, v99
	v_rcp_f32_e32 v144, v99
	v_and_b32_e32 v99, 0xffff0000, v142
	v_mul_f32_e32 v99, 0xbfb8aa3b, v99
	v_exp_f32_e32 v99, v99
	s_nop 0
	v_add_f32_e32 v99, 1.0, v99
	v_rcp_f32_e32 v145, v99
	v_lshlrev_b32_e32 v99, 16, v143
	v_mul_f32_e32 v99, 0xbfb8aa3b, v99
	v_exp_f32_e32 v99, v99
	v_pk_mul_f32 v[76:77], v[76:77], v[144:145]
	v_add_f32_e32 v99, 1.0, v99
	v_rcp_f32_e32 v142, v99
	v_and_b32_e32 v99, 0xffff0000, v143
	v_mul_f32_e32 v99, 0xbfb8aa3b, v99
	v_exp_f32_e32 v99, v99
	s_nop 0
	v_add_f32_e32 v99, 1.0, v99
	v_rcp_f32_e32 v143, v99
	v_lshlrev_b32_e32 v99, 16, v138
	v_mul_f32_e32 v99, 0xbfb8aa3b, v99
	v_exp_f32_e32 v99, v99
	v_pk_mul_f32 v[78:79], v[78:79], v[142:143]
	v_add_f32_e32 v99, 1.0, v99
	v_rcp_f32_e32 v142, v99
	v_and_b32_e32 v99, 0xffff0000, v138
	v_mul_f32_e32 v99, 0xbfb8aa3b, v99
	v_exp_f32_e32 v99, v99
	s_nop 0
	v_add_f32_e32 v99, 1.0, v99
	v_rcp_f32_e32 v143, v99
	v_lshlrev_b32_e32 v99, 16, v139
	v_mul_f32_e32 v99, 0xbfb8aa3b, v99
	v_exp_f32_e32 v99, v99
	v_pk_mul_f32 v[72:73], v[72:73], v[142:143]
	v_add_f32_e32 v99, 1.0, v99
	v_rcp_f32_e32 v138, v99
	v_and_b32_e32 v99, 0xffff0000, v139
	v_mul_f32_e32 v99, 0xbfb8aa3b, v99
	v_exp_f32_e32 v99, v99
	s_nop 0
	v_add_f32_e32 v99, 1.0, v99
	v_rcp_f32_e32 v139, v99
	v_lshlrev_b32_e32 v99, 16, v136
	v_mul_f32_e32 v99, 0xbfb8aa3b, v99
	v_exp_f32_e32 v99, v99
	v_pk_mul_f32 v[74:75], v[74:75], v[138:139]
	v_add_f32_e32 v99, 1.0, v99
	v_rcp_f32_e32 v138, v99
	v_and_b32_e32 v99, 0xffff0000, v136
	v_mul_f32_e32 v99, 0xbfb8aa3b, v99
	v_exp_f32_e32 v99, v99
	s_nop 0
	v_add_f32_e32 v99, 1.0, v99
	v_rcp_f32_e32 v139, v99
	v_lshlrev_b32_e32 v99, 16, v137
	v_mul_f32_e32 v99, 0xbfb8aa3b, v99
	v_exp_f32_e32 v99, v99
	v_pk_mul_f32 v[68:69], v[68:69], v[138:139]
	v_add_f32_e32 v99, 1.0, v99
	v_rcp_f32_e32 v136, v99
	v_and_b32_e32 v99, 0xffff0000, v137
	v_mul_f32_e32 v99, 0xbfb8aa3b, v99
	v_exp_f32_e32 v99, v99
	s_nop 0
	v_add_f32_e32 v99, 1.0, v99
	v_rcp_f32_e32 v137, v99
	s_nop 0
	v_pk_mul_f32 v[70:71], v[70:71], v[136:137]
	global_load_dwordx2 v[136:137], v[134:135], off offset:1760
	s_waitcnt vmcnt(0)
	v_lshlrev_b32_e32 v99, 16, v136
	v_mul_f32_e32 v99, 0xbfb8aa3b, v99
	v_exp_f32_e32 v99, v99
	s_nop 0
	v_add_f32_e32 v99, 1.0, v99
	v_rcp_f32_e32 v134, v99
	v_and_b32_e32 v99, 0xffff0000, v136
	v_mul_f32_e32 v99, 0xbfb8aa3b, v99
	v_exp_f32_e32 v99, v99
	s_nop 0
	v_add_f32_e32 v99, 1.0, v99
	v_rcp_f32_e32 v135, v99
	s_nop 0
	v_pk_mul_f32 v[134:135], v[60:61], v[134:135]
	v_lshlrev_b32_e32 v60, 16, v137
	v_and_b32_e32 v61, 0xffff0000, v137
	v_mul_f32_e32 v60, 0xbfb8aa3b, v60
	v_mul_f32_e32 v61, 0xbfb8aa3b, v61
	v_exp_f32_e32 v60, v60
	v_exp_f32_e32 v61, v61
	v_add_f32_e32 v60, 1.0, v60
	v_add_f32_e32 v61, 1.0, v61
	v_rcp_f32_e32 v60, v60
	v_rcp_f32_e32 v61, v61
	s_nop 0
	v_pk_mul_f32 v[136:137], v[62:63], v[60:61]
	s_mov_b32 s8, 0x11d000
	v_add_co_u32_e32 v138, vcc, s8, v132
	s_mov_b32 s8, 0x164000
	s_nop 0
	v_addc_co_u32_e32 v139, vcc, 0, v133, vcc
	global_load_dwordx2 v[62:63], v[138:139], off offset:3712
	global_load_dwordx2 v[204:205], v[138:139], off offset:3744
	global_load_dwordx2 v[206:207], v[138:139], off offset:3776
	global_load_dwordx2 v[208:209], v[138:139], off offset:3808
	s_waitcnt vmcnt(0)
	v_lshlrev_b32_e32 v60, 16, v62
	v_and_b32_e32 v61, 0xffff0000, v62
	v_mul_f32_e32 v60, 0xbfb8aa3b, v60
	v_mul_f32_e32 v61, 0xbfb8aa3b, v61
	v_exp_f32_e32 v60, v60
	v_exp_f32_e32 v61, v61
	v_lshlrev_b32_e32 v62, 16, v63
	v_and_b32_e32 v63, 0xffff0000, v63
	v_add_f32_e32 v60, 1.0, v60
	v_add_f32_e32 v61, 1.0, v61
	v_rcp_f32_e32 v60, v60
	v_rcp_f32_e32 v61, v61
	v_mul_f32_e32 v62, 0xbfb8aa3b, v62
	v_mul_f32_e32 v63, 0xbfb8aa3b, v63
	v_exp_f32_e32 v62, v62
	v_pk_mul_f32 v[60:61], v[64:65], v[60:61]
	v_mov_b32_e32 v64, v204
	v_mov_b32_e32 v65, v205
	v_exp_f32_e32 v63, v63
	v_add_f32_e32 v62, 1.0, v62
	v_rcp_f32_e32 v62, v62
	v_add_f32_e32 v63, 1.0, v63
	v_rcp_f32_e32 v63, v63
	s_nop 0
	v_pk_mul_f32 v[62:63], v[66:67], v[62:63]
	s_waitcnt vmcnt(0)
	v_lshlrev_b32_e32 v66, 16, v64
	v_and_b32_e32 v64, 0xffff0000, v64
	v_mul_f32_e32 v64, 0xbfb8aa3b, v64
	v_exp_f32_e32 v64, v64
	v_mul_f32_e32 v66, 0xbfb8aa3b, v66
	v_exp_f32_e32 v66, v66
	v_add_f32_e32 v64, 1.0, v64
	v_rcp_f32_e32 v67, v64
	v_lshlrev_b32_e32 v64, 16, v65
	v_and_b32_e32 v65, 0xffff0000, v65
	v_mul_f32_e32 v64, 0xbfb8aa3b, v64
	v_mul_f32_e32 v65, 0xbfb8aa3b, v65
	v_exp_f32_e32 v64, v64
	v_exp_f32_e32 v65, v65
	v_add_f32_e32 v66, 1.0, v66
	v_rcp_f32_e32 v66, v66
	v_add_f32_e32 v64, 1.0, v64
	v_add_f32_e32 v65, 1.0, v65
	v_rcp_f32_e32 v64, v64
	v_rcp_f32_e32 v65, v65
	v_pk_mul_f32 v[56:57], v[56:57], v[66:67]
	v_pk_mul_f32 v[58:59], v[58:59], v[64:65]
	v_mov_b32_e32 v64, v206
	v_mov_b32_e32 v65, v207
	s_waitcnt vmcnt(0)
	v_lshlrev_b32_e32 v66, 16, v64
	v_and_b32_e32 v64, 0xffff0000, v64
	v_mul_f32_e32 v64, 0xbfb8aa3b, v64
	v_exp_f32_e32 v64, v64
	v_mul_f32_e32 v66, 0xbfb8aa3b, v66
	v_exp_f32_e32 v66, v66
	v_add_f32_e32 v64, 1.0, v64
	v_rcp_f32_e32 v67, v64
	v_lshlrev_b32_e32 v64, 16, v65
	v_and_b32_e32 v65, 0xffff0000, v65
	v_mul_f32_e32 v64, 0xbfb8aa3b, v64
	v_mul_f32_e32 v65, 0xbfb8aa3b, v65
	v_exp_f32_e32 v64, v64
	v_exp_f32_e32 v65, v65
	v_add_f32_e32 v66, 1.0, v66
	v_rcp_f32_e32 v66, v66
	v_add_f32_e32 v64, 1.0, v64
	v_add_f32_e32 v65, 1.0, v65
	v_rcp_f32_e32 v64, v64
	v_rcp_f32_e32 v65, v65
	v_pk_mul_f32 v[52:53], v[52:53], v[66:67]
	v_pk_mul_f32 v[54:55], v[54:55], v[64:65]
	v_mov_b32_e32 v64, v208
	v_mov_b32_e32 v65, v209
	s_waitcnt vmcnt(0)
; __device__ __forceinline__ float bflo(unsigned u) { return __uint_as_float(u << 16); }
; __device__ __forceinline__ float bfhi(unsigned u) { return __uint_as_float(u & 0xffff0000u); }
; __device__ __forceinline__ float sigmoidf_(float x) { return __builtin_amdgcn_rcpf(1.f + __expf(-x)); }
; __device__ __forceinline__ int opaque_tid() { int t = threadIdx.x; asm volatile("" : "+v"(t)); return t; }
; __device__ void gemm2_phase(const Params& P, int layer, char* smem) {
;     ...
;     {
;       const int tid2 = opaque_tid(), wid2 = tid2 >> 6, lane2 = tid2 & 63, wr2 = wid2 >> 2, wc2 = wid2 & 3, fr2 = lane2 & 15, fq2 = lane2 >> 4;
;       const u16* pp = P.proj + (size_t)(u.pm * 256 + wr2 * 128 + fr2) * INC + u.pn * 256 + wc2 * 64 + fq2 * 4;
; #pragma unroll
;       for (int m = 0; m < 8; m++) {
; #pragma unroll
;         for (int n = 0; n < 4; n++) {
;           const uint2 rb = *(const uint2*)(pp + (size_t)(m * 16) * INC + C_RB + n * 16);
;           acc[m][n][0] *= sigmoidf_(bflo(rb.x)); acc[m][n][1] *= sigmoidf_(bfhi(rb.x));
;           acc[m][n][2] *= sigmoidf_(bflo(rb.y)); acc[m][n][3] *= sigmoidf_(bfhi(rb.y));
;         }
;         if (m & 1) __builtin_amdgcn_sched_barrier(0);
;       }
	v_lshlrev_b32_e32 v66, 16, v64
	v_and_b32_e32 v64, 0xffff0000, v64
	v_mul_f32_e32 v64, 0xbfb8aa3b, v64
	v_exp_f32_e32 v64, v64
	v_mul_f32_e32 v66, 0xbfb8aa3b, v66
	v_exp_f32_e32 v66, v66
	v_add_f32_e32 v64, 1.0, v64
	v_rcp_f32_e32 v67, v64
	v_lshlrev_b32_e32 v64, 16, v65
	v_and_b32_e32 v65, 0xffff0000, v65
	v_mul_f32_e32 v64, 0xbfb8aa3b, v64
	v_mul_f32_e32 v65, 0xbfb8aa3b, v65
	v_exp_f32_e32 v64, v64
	v_exp_f32_e32 v65, v65
	v_add_f32_e32 v66, 1.0, v66
	v_rcp_f32_e32 v66, v66
	v_add_f32_e32 v64, 1.0, v64
	v_add_f32_e32 v65, 1.0, v65
	v_rcp_f32_e32 v64, v64
	v_rcp_f32_e32 v65, v65
	v_pk_mul_f32 v[48:49], v[48:49], v[66:67]
	v_pk_mul_f32 v[50:51], v[50:51], v[64:65]
	v_add_co_u32_e32 v64, vcc, s8, v132
	s_nop 1
	v_addc_co_u32_e32 v65, vcc, 0, v133, vcc
	global_load_dwordx2 v[66:67], v[64:65], off offset:1728
	global_load_dwordx2 v[138:139], v[64:65], off offset:1696
	global_load_dwordx2 v[142:143], v[64:65], off offset:1664
	s_waitcnt vmcnt(0)
	v_lshlrev_b32_e32 v99, 16, v142
	global_load_dwordx2 v[64:65], v[64:65], off offset:1760
	v_mul_f32_e32 v99, 0xbfb8aa3b, v99
	v_exp_f32_e32 v99, v99
	s_nop 0
	v_add_f32_e32 v99, 1.0, v99
	v_rcp_f32_e32 v144, v99
	v_and_b32_e32 v99, 0xffff0000, v142
	v_mul_f32_e32 v99, 0xbfb8aa3b, v99
	v_exp_f32_e32 v99, v99
	s_nop 0
	v_add_f32_e32 v99, 1.0, v99
	v_rcp_f32_e32 v145, v99
	v_lshlrev_b32_e32 v99, 16, v143
	v_mul_f32_e32 v99, 0xbfb8aa3b, v99
	v_exp_f32_e32 v99, v99
	v_pk_mul_f32 v[44:45], v[44:45], v[144:145]
	v_add_f32_e32 v99, 1.0, v99
	v_rcp_f32_e32 v142, v99
	v_and_b32_e32 v99, 0xffff0000, v143
	v_mul_f32_e32 v99, 0xbfb8aa3b, v99
	v_exp_f32_e32 v99, v99
	s_nop 0
	v_add_f32_e32 v99, 1.0, v99
	v_rcp_f32_e32 v143, v99
	v_lshlrev_b32_e32 v99, 16, v138
	v_mul_f32_e32 v99, 0xbfb8aa3b, v99
	v_exp_f32_e32 v99, v99
	v_pk_mul_f32 v[46:47], v[46:47], v[142:143]
	v_add_f32_e32 v99, 1.0, v99
	v_rcp_f32_e32 v142, v99
	v_and_b32_e32 v99, 0xffff0000, v138
	v_mul_f32_e32 v99, 0xbfb8aa3b, v99
	v_exp_f32_e32 v99, v99
	s_nop 0
	v_add_f32_e32 v99, 1.0, v99
	v_rcp_f32_e32 v143, v99
	v_lshlrev_b32_e32 v99, 16, v139
	v_mul_f32_e32 v99, 0xbfb8aa3b, v99
	v_exp_f32_e32 v99, v99
	v_pk_mul_f32 v[40:41], v[40:41], v[142:143]
	v_add_f32_e32 v99, 1.0, v99
	v_rcp_f32_e32 v138, v99
	v_and_b32_e32 v99, 0xffff0000, v139
	v_mul_f32_e32 v99, 0xbfb8aa3b, v99
	v_exp_f32_e32 v99, v99
	s_nop 0
	v_add_f32_e32 v99, 1.0, v99
	v_rcp_f32_e32 v139, v99
	v_lshlrev_b32_e32 v99, 16, v66
	v_and_b32_e32 v66, 0xffff0000, v66
	v_mul_f32_e32 v66, 0xbfb8aa3b, v66
	v_exp_f32_e32 v66, v66
	v_pk_mul_f32 v[42:43], v[42:43], v[138:139]
	v_mul_f32_e32 v99, 0xbfb8aa3b, v99
	v_exp_f32_e32 v99, v99
	v_add_f32_e32 v66, 1.0, v66
	v_rcp_f32_e32 v139, v66
	v_lshlrev_b32_e32 v66, 16, v67
	v_and_b32_e32 v67, 0xffff0000, v67
	v_mul_f32_e32 v66, 0xbfb8aa3b, v66
	v_mul_f32_e32 v67, 0xbfb8aa3b, v67
	v_exp_f32_e32 v66, v66
	v_exp_f32_e32 v67, v67
	v_add_f32_e32 v99, 1.0, v99
	v_rcp_f32_e32 v138, v99
	v_add_f32_e32 v66, 1.0, v66
	v_add_f32_e32 v67, 1.0, v67
	v_rcp_f32_e32 v66, v66
	v_rcp_f32_e32 v67, v67
	v_pk_mul_f32 v[36:37], v[36:37], v[138:139]
	v_pk_mul_f32 v[38:39], v[38:39], v[66:67]
	s_waitcnt vmcnt(0)
	v_lshlrev_b32_e32 v66, 16, v64
	v_and_b32_e32 v64, 0xffff0000, v64
	v_mul_f32_e32 v64, 0xbfb8aa3b, v64
	v_exp_f32_e32 v64, v64
	v_mul_f32_e32 v66, 0xbfb8aa3b, v66
	v_exp_f32_e32 v66, v66
	v_add_f32_e32 v64, 1.0, v64
	v_rcp_f32_e32 v67, v64
	v_lshlrev_b32_e32 v64, 16, v65
	v_and_b32_e32 v65, 0xffff0000, v65
	v_mul_f32_e32 v64, 0xbfb8aa3b, v64
	v_mul_f32_e32 v65, 0xbfb8aa3b, v65
	v_exp_f32_e32 v64, v64
	v_exp_f32_e32 v65, v65
	v_add_f32_e32 v66, 1.0, v66
	v_rcp_f32_e32 v66, v66
	v_add_f32_e32 v64, 1.0, v64
	v_add_f32_e32 v65, 1.0, v65
	v_rcp_f32_e32 v64, v64
	v_rcp_f32_e32 v65, v65
	v_pk_mul_f32 v[28:29], v[28:29], v[66:67]
	v_pk_mul_f32 v[30:31], v[30:31], v[64:65]
	s_mov_b32 s8, 0x1aa000
	v_add_co_u32_e32 v64, vcc, s8, v132
	s_mov_b32 s8, 0x1f1000
	s_nop 0
	v_addc_co_u32_e32 v65, vcc, 0, v133, vcc
	global_load_dwordx2 v[66:67], v[64:65], off offset:3712
	global_load_dwordx2 v[204:205], v[64:65], off offset:3744
	global_load_dwordx2 v[206:207], v[64:65], off offset:3776
	global_load_dwordx2 v[208:209], v[64:65], off offset:3808
	s_waitcnt vmcnt(0)
	v_lshlrev_b32_e32 v99, 16, v66
	v_and_b32_e32 v66, 0xffff0000, v66
	v_mul_f32_e32 v66, 0xbfb8aa3b, v66
	v_exp_f32_e32 v66, v66
	v_mul_f32_e32 v99, 0xbfb8aa3b, v99
	v_exp_f32_e32 v99, v99
	v_add_f32_e32 v66, 1.0, v66
	v_rcp_f32_e32 v139, v66
	v_lshlrev_b32_e32 v66, 16, v67
	v_and_b32_e32 v67, 0xffff0000, v67
	v_mul_f32_e32 v66, 0xbfb8aa3b, v66
	v_mul_f32_e32 v67, 0xbfb8aa3b, v67
	v_exp_f32_e32 v66, v66
	v_exp_f32_e32 v67, v67
	v_add_f32_e32 v99, 1.0, v99
	v_rcp_f32_e32 v138, v99
	v_add_f32_e32 v66, 1.0, v66
	v_add_f32_e32 v67, 1.0, v67
	v_rcp_f32_e32 v66, v66
	v_rcp_f32_e32 v67, v67
	v_pk_mul_f32 v[32:33], v[32:33], v[138:139]
	v_pk_mul_f32 v[34:35], v[34:35], v[66:67]
	v_mov_b32_e32 v66, v204
	v_mov_b32_e32 v67, v205
	s_waitcnt vmcnt(0)
	v_lshlrev_b32_e32 v99, 16, v66
	v_and_b32_e32 v66, 0xffff0000, v66
	v_mul_f32_e32 v66, 0xbfb8aa3b, v66
	v_exp_f32_e32 v66, v66
	v_mul_f32_e32 v99, 0xbfb8aa3b, v99
	v_exp_f32_e32 v99, v99
	v_add_f32_e32 v66, 1.0, v66
	v_rcp_f32_e32 v139, v66
	v_lshlrev_b32_e32 v66, 16, v67
	v_and_b32_e32 v67, 0xffff0000, v67
	v_mul_f32_e32 v66, 0xbfb8aa3b, v66
	v_mul_f32_e32 v67, 0xbfb8aa3b, v67
	v_exp_f32_e32 v66, v66
	v_exp_f32_e32 v67, v67
	v_add_f32_e32 v99, 1.0, v99
	v_rcp_f32_e32 v138, v99
	v_add_f32_e32 v66, 1.0, v66
	v_add_f32_e32 v67, 1.0, v67
	v_rcp_f32_e32 v66, v66
	v_rcp_f32_e32 v67, v67
	v_pk_mul_f32 v[24:25], v[24:25], v[138:139]
	v_pk_mul_f32 v[26:27], v[26:27], v[66:67]
	v_mov_b32_e32 v66, v206
	v_mov_b32_e32 v67, v207
	s_waitcnt vmcnt(0)
; __device__ __forceinline__ float bflo(unsigned u) { return __uint_as_float(u << 16); }
; __device__ __forceinline__ float bfhi(unsigned u) { return __uint_as_float(u & 0xffff0000u); }
; __device__ __forceinline__ float sigmoidf_(float x) { return __builtin_amdgcn_rcpf(1.f + __expf(-x)); }
; __device__ __forceinline__ uint2 pk4(f32x4 v) { return make_uint2(pk2(v[0], v[1]), pk2(v[2], v[3])); }
; __device__ __forceinline__ void wave_store_rows(char* wsm, u16* gbase, const size_t ld, const f32x4 (&acc)[8][4], const int lane) {
;     ...
;   for (int hf = 0; hf < 2; hf++) {
; #pragma unroll
;     for (int m = 0; m < 4; m++)
; #pragma unroll
;       for (int n = 0; n < 4; n++) {
;         const int row = m * 16 + fr, chunk = n * 2 + (fq >> 1);
;         *(uint2*)(wsm + row * 128 + ((chunk ^ (fr & 7)) << 4) + (fq & 1) * 8) = pk4(acc[hf * 4 + m][n]);
; __device__ void gemm2_phase(const Params& P, int layer, char* smem) {
;     ...
; #pragma unroll
;       for (int m = 0; m < 8; m++) {
; #pragma unroll
;         for (int n = 0; n < 4; n++) {
;           const uint2 rb = *(const uint2*)(pp + (size_t)(m * 16) * INC + C_RB + n * 16);
;           acc[m][n][0] *= sigmoidf_(bflo(rb.x)); acc[m][n][1] *= sigmoidf_(bfhi(rb.x));
;           acc[m][n][2] *= sigmoidf_(bflo(rb.y)); acc[m][n][3] *= sigmoidf_(bfhi(rb.y));
;         }
;         if (m & 1) __builtin_amdgcn_sched_barrier(0);
;       }
;       wave_store_rows(smem + G_STAGE_B + wid2 * 8192, P.h + (size_t)(u.pm * 256 + wr2 * 128) * DM + u.pn * 256 + wc2 * 64, DM, acc, lane2);
	v_lshlrev_b32_e32 v99, 16, v66
	v_mov_b32_e32 v64, v208
	v_mov_b32_e32 v65, v209
	v_and_b32_e32 v66, 0xffff0000, v66
	v_mul_f32_e32 v66, 0xbfb8aa3b, v66
	v_exp_f32_e32 v66, v66
	v_mul_f32_e32 v99, 0xbfb8aa3b, v99
	v_exp_f32_e32 v99, v99
	v_add_f32_e32 v66, 1.0, v66
	v_rcp_f32_e32 v139, v66
	v_lshlrev_b32_e32 v66, 16, v67
	v_and_b32_e32 v67, 0xffff0000, v67
	v_mul_f32_e32 v66, 0xbfb8aa3b, v66
	v_mul_f32_e32 v67, 0xbfb8aa3b, v67
	v_exp_f32_e32 v66, v66
	v_exp_f32_e32 v67, v67
	v_add_f32_e32 v99, 1.0, v99
	v_rcp_f32_e32 v138, v99
	v_add_f32_e32 v66, 1.0, v66
	v_add_f32_e32 v67, 1.0, v67
	v_rcp_f32_e32 v66, v66
	v_rcp_f32_e32 v67, v67
	v_pk_mul_f32 v[20:21], v[20:21], v[138:139]
	v_pk_mul_f32 v[22:23], v[22:23], v[66:67]
	s_waitcnt vmcnt(0)
	v_lshlrev_b32_e32 v66, 16, v64
	v_and_b32_e32 v64, 0xffff0000, v64
	v_mul_f32_e32 v64, 0xbfb8aa3b, v64
	v_exp_f32_e32 v64, v64
	v_mul_f32_e32 v66, 0xbfb8aa3b, v66
	v_exp_f32_e32 v66, v66
	v_add_f32_e32 v64, 1.0, v64
	v_rcp_f32_e32 v67, v64
	v_lshlrev_b32_e32 v64, 16, v65
	v_and_b32_e32 v65, 0xffff0000, v65
	v_mul_f32_e32 v64, 0xbfb8aa3b, v64
	v_mul_f32_e32 v65, 0xbfb8aa3b, v65
	v_exp_f32_e32 v64, v64
	v_exp_f32_e32 v65, v65
	v_add_f32_e32 v66, 1.0, v66
	v_rcp_f32_e32 v66, v66
	v_add_f32_e32 v64, 1.0, v64
	v_add_f32_e32 v65, 1.0, v65
	v_rcp_f32_e32 v64, v64
	v_rcp_f32_e32 v65, v65
	v_pk_mul_f32 v[4:5], v[4:5], v[66:67]
	v_pk_mul_f32 v[6:7], v[6:7], v[64:65]
	v_add_co_u32_e32 v64, vcc, s8, v132
	s_nop 1
	v_addc_co_u32_e32 v65, vcc, 0, v133, vcc
	global_load_dwordx2 v[66:67], v[64:65], off offset:1728
	global_load_dwordx2 v[132:133], v[64:65], off offset:1696
	global_load_dwordx2 v[138:139], v[64:65], off offset:1664
	s_waitcnt vmcnt(0)
	v_lshlrev_b32_e32 v99, 16, v138
	global_load_dwordx2 v[64:65], v[64:65], off offset:1760
	v_mul_f32_e32 v99, 0xbfb8aa3b, v99
	v_exp_f32_e32 v99, v99
	s_nop 0
	v_add_f32_e32 v99, 1.0, v99
	v_rcp_f32_e32 v142, v99
	v_and_b32_e32 v99, 0xffff0000, v138
	v_mul_f32_e32 v99, 0xbfb8aa3b, v99
	v_exp_f32_e32 v99, v99
	s_nop 0
	v_add_f32_e32 v99, 1.0, v99
	v_rcp_f32_e32 v143, v99
	v_lshlrev_b32_e32 v99, 16, v139
	v_mul_f32_e32 v99, 0xbfb8aa3b, v99
	v_exp_f32_e32 v99, v99
	v_pk_mul_f32 v[16:17], v[16:17], v[142:143]
	v_add_f32_e32 v99, 1.0, v99
	v_rcp_f32_e32 v138, v99
	v_and_b32_e32 v99, 0xffff0000, v139
	v_mul_f32_e32 v99, 0xbfb8aa3b, v99
	v_exp_f32_e32 v99, v99
	s_nop 0
	v_add_f32_e32 v99, 1.0, v99
	v_rcp_f32_e32 v139, v99
	v_lshlrev_b32_e32 v99, 16, v132
	v_mul_f32_e32 v99, 0xbfb8aa3b, v99
	v_exp_f32_e32 v99, v99
	v_pk_mul_f32 v[18:19], v[18:19], v[138:139]
	v_add_f32_e32 v99, 1.0, v99
	v_rcp_f32_e32 v138, v99
	v_and_b32_e32 v99, 0xffff0000, v132
	v_mul_f32_e32 v99, 0xbfb8aa3b, v99
	v_exp_f32_e32 v99, v99
	s_nop 0
	v_add_f32_e32 v99, 1.0, v99
	v_rcp_f32_e32 v139, v99
	v_lshlrev_b32_e32 v99, 16, v133
	v_mul_f32_e32 v99, 0xbfb8aa3b, v99
	v_exp_f32_e32 v99, v99
	v_pk_mul_f32 v[12:13], v[12:13], v[138:139]
	v_add_f32_e32 v99, 1.0, v99
	v_rcp_f32_e32 v132, v99
	v_and_b32_e32 v99, 0xffff0000, v133
	v_mul_f32_e32 v99, 0xbfb8aa3b, v99
	v_exp_f32_e32 v99, v99
	s_nop 0
	v_add_f32_e32 v99, 1.0, v99
	v_rcp_f32_e32 v133, v99
	v_lshlrev_b32_e32 v99, 16, v66
	v_and_b32_e32 v66, 0xffff0000, v66
	v_mul_f32_e32 v66, 0xbfb8aa3b, v66
	v_exp_f32_e32 v66, v66
	v_pk_mul_f32 v[14:15], v[14:15], v[132:133]
	v_mul_f32_e32 v99, 0xbfb8aa3b, v99
	v_exp_f32_e32 v99, v99
	v_add_f32_e32 v66, 1.0, v66
	v_rcp_f32_e32 v133, v66
	v_lshlrev_b32_e32 v66, 16, v67
	v_and_b32_e32 v67, 0xffff0000, v67
	v_mul_f32_e32 v66, 0xbfb8aa3b, v66
	v_mul_f32_e32 v67, 0xbfb8aa3b, v67
	v_exp_f32_e32 v66, v66
	v_exp_f32_e32 v67, v67
	v_add_f32_e32 v99, 1.0, v99
	v_rcp_f32_e32 v132, v99
	v_add_f32_e32 v66, 1.0, v66
	v_add_f32_e32 v67, 1.0, v67
	v_rcp_f32_e32 v66, v66
	v_rcp_f32_e32 v67, v67
	v_pk_mul_f32 v[8:9], v[8:9], v[132:133]
	v_pk_mul_f32 v[10:11], v[10:11], v[66:67]
	s_waitcnt vmcnt(0)
	v_lshlrev_b32_e32 v66, 16, v64
	v_and_b32_e32 v64, 0xffff0000, v64
	v_mul_f32_e32 v64, 0xbfb8aa3b, v64
	v_exp_f32_e32 v64, v64
	v_mul_f32_e32 v66, 0xbfb8aa3b, v66
	v_exp_f32_e32 v66, v66
	v_add_f32_e32 v64, 1.0, v64
	v_rcp_f32_e32 v67, v64
	v_lshlrev_b32_e32 v64, 16, v65
	v_and_b32_e32 v65, 0xffff0000, v65
	v_mul_f32_e32 v64, 0xbfb8aa3b, v64
	v_mul_f32_e32 v65, 0xbfb8aa3b, v65
	v_exp_f32_e32 v64, v64
	v_exp_f32_e32 v65, v65
	v_add_f32_e32 v66, 1.0, v66
	v_rcp_f32_e32 v66, v66
	v_add_f32_e32 v64, 1.0, v64
	v_add_f32_e32 v65, 1.0, v65
	v_rcp_f32_e32 v64, v64
	v_rcp_f32_e32 v65, v65
	v_pk_mul_f32 v[0:1], v[0:1], v[66:67]
	v_pk_mul_f32 v[2:3], v[2:3], v[64:65]
	v_lshlrev_b32_e32 v64, 7, v140
	v_and_b32_e32 v64, 0xffffe000, v64
	v_ashrrev_i32_e32 v99, 31, v98
	v_add_u32_e32 v67, 0x10000, v64
	v_lshlrev_b64 v[64:65], 11, v[98:99]
	v_lshl_add_u64 v[64:65], s[86:87], 0, v[64:65]
	v_lshl_add_u64 v[64:65], v[64:65], 0, s[6:7]
	v_bfe_u32 v132, v140, 3, 3
	v_lshl_add_u64 v[64:65], v[64:65], 0, v[96:97]
	v_and_b32_e32 v133, 7, v140
	v_bitop3_b32 v96, v132, v140, 7 bitop3:0x78
	v_and_b32_e32 v66, 63, v140
	v_bfe_u32 v138, v140, 5, 1
	v_and_or_b32 v139, v141, 8, v67
	v_lshl_or_b32 v141, v96, 4, v67
	v_lshlrev_b32_e32 v96, 4, v133
	v_lshlrev_b32_e32 v66, 7, v66
	v_lshl_add_u64 v[98:99], v[64:65], 0, v[96:97]
	s_movk_i32 s6, 0x780
	v_bitop3_b32 v96, v138, v140, 7 bitop3:0x78
	v_and_or_b32 v67, v66, s6, v139
	v_cvt_pk_bf16_f32 v64, v124, v125
	v_lshlrev_b32_e32 v96, 4, v96
	v_bitop3_b32 v125, v138, v133, 2 bitop3:0x36
	v_cvt_pk_bf16_f32 v65, v126, v127
	v_or_b32_e32 v124, v67, v96
	v_lshlrev_b32_e32 v125, 4, v125
	ds_write_b64 v124, v[64:65]
	v_cvt_pk_bf16_f32 v64, v128, v129
	v_cvt_pk_bf16_f32 v65, v130, v131
	v_or_b32_e32 v126, v67, v125
	ds_write_b64 v126, v[64:65]
; __device__ __forceinline__ uint2 pk4(f32x4 v) { return make_uint2(pk2(v[0], v[1]), pk2(v[2], v[3])); }
; __device__ __forceinline__ void wave_store_rows(char* wsm, u16* gbase, const size_t ld, const f32x4 (&acc)[8][4], const int lane) {
;     ...
;   for (int hf = 0; hf < 2; hf++) {
; #pragma unroll
;     for (int m = 0; m < 4; m++)
; #pragma unroll
;       for (int n = 0; n < 4; n++) {
;         const int row = m * 16 + fr, chunk = n * 2 + (fq >> 1);
;         *(uint2*)(wsm + row * 128 + ((chunk ^ (fr & 7)) << 4) + (fq & 1) * 8) = pk4(acc[hf * 4 + m][n]);
;       }
; #pragma unroll
;     for (int i = 0; i < 8; i++) {
;       const int row = i * 8 + rr;
;       const uint4 v = *(const uint4*)(wsm + row * 128 + ((ch ^ (row & 7)) << 4));
;       __builtin_nontemporal_store(__builtin_bit_cast(u32x4_t, v), (u32x4_t*)(gbase + (size_t)(hf * 64 + row) * ld + ch * 8));
;     }
;   }
; __device__ void gemm2_phase(const Params& P, int layer, char* smem) {
;     ...
;     __syncthreads();
	v_cvt_pk_bf16_f32 v64, v120, v121
	v_bitop3_b32 v120, v138, v133, 4 bitop3:0x36
	v_lshlrev_b32_e32 v120, 4, v120
	v_cvt_pk_bf16_f32 v65, v122, v123
	v_or_b32_e32 v121, v67, v120
	ds_write_b64 v121, v[64:65]
	v_cvt_pk_bf16_f32 v64, v116, v117
	v_bitop3_b32 v116, v138, v133, 6 bitop3:0x36
	v_lshlrev_b32_e32 v116, 4, v116
	v_cvt_pk_bf16_f32 v65, v118, v119
	v_or_b32_e32 v117, v67, v116
	ds_write_b64 v117, v[64:65]
	v_cvt_pk_bf16_f32 v64, v112, v113
	v_cvt_pk_bf16_f32 v65, v114, v115
	ds_write_b64 v124, v[64:65] offset:2048
	v_cvt_pk_bf16_f32 v64, v108, v109
	v_cvt_pk_bf16_f32 v65, v110, v111
	ds_write_b64 v126, v[64:65] offset:2048
	v_cvt_pk_bf16_f32 v64, v104, v105
	v_cvt_pk_bf16_f32 v65, v106, v107
	ds_write_b64 v121, v[64:65] offset:2048
	v_cvt_pk_bf16_f32 v64, v92, v93
	v_cvt_pk_bf16_f32 v65, v94, v95
	ds_write_b64 v117, v[64:65] offset:2048
	v_cvt_pk_bf16_f32 v64, v100, v101
	v_cvt_pk_bf16_f32 v65, v102, v103
	ds_write_b64 v124, v[64:65] offset:4096
	v_cvt_pk_bf16_f32 v64, v88, v89
	v_cvt_pk_bf16_f32 v65, v90, v91
	ds_write_b64 v126, v[64:65] offset:4096
	v_cvt_pk_bf16_f32 v64, v84, v85
	v_cvt_pk_bf16_f32 v65, v86, v87
	s_movk_i32 s6, 0x1800
	ds_write_b64 v121, v[64:65] offset:4096
	v_cvt_pk_bf16_f32 v64, v80, v81
	v_cvt_pk_bf16_f32 v65, v82, v83
	v_or3_b32 v66, v66, v139, s6
	ds_write_b64 v117, v[64:65] offset:4096
	v_cvt_pk_bf16_f32 v64, v76, v77
	v_cvt_pk_bf16_f32 v65, v78, v79
	v_or_b32_e32 v76, v66, v96
	ds_write_b64 v76, v[64:65]
	v_cvt_pk_bf16_f32 v64, v72, v73
	v_cvt_pk_bf16_f32 v65, v74, v75
	v_or_b32_e32 v77, v66, v125
	ds_write_b64 v77, v[64:65]
	v_cvt_pk_bf16_f32 v64, v68, v69
	v_cvt_pk_bf16_f32 v65, v70, v71
	v_or_b32_e32 v78, v66, v120
	v_lshl_or_b32 v142, v132, 7, v141
	ds_write_b64 v78, v[64:65]
	v_cvt_pk_bf16_f32 v64, v134, v135
	v_cvt_pk_bf16_f32 v65, v136, v137
	v_or_b32_e32 v79, v66, v116
	v_or_b32_e32 v74, 8, v132
	ds_write_b64 v79, v[64:65]
	ds_read_b128 v[64:67], v142
	v_lshl_or_b32 v80, v74, 7, v141
	ds_read_b128 v[68:71], v80
	v_lshlrev_b32_e32 v96, 11, v132
	v_lshl_add_u64 v[72:73], v[98:99], 0, v[96:97]
	v_lshlrev_b32_e32 v96, 11, v74
	s_waitcnt lgkmcnt(1)
	global_store_dwordx4 v[72:73], v[64:67], off nt
	v_or_b32_e32 v82, 24, v132
	v_lshl_or_b32 v83, v82, 7, v141
	v_lshl_add_u64 v[64:65], v[98:99], 0, v[96:97]
	s_waitcnt lgkmcnt(0)
	global_store_dwordx4 v[64:65], v[68:71], off nt
	v_or_b32_e32 v84, 40, v132
	v_lshl_or_b32 v85, v84, 7, v141
	v_or_b32_e32 v68, 16, v132
	v_lshl_or_b32 v81, v68, 7, v141
	ds_read_b128 v[64:67], v81
	v_lshlrev_b32_e32 v96, 11, v68
	ds_read_b128 v[68:71], v83
	v_lshl_add_u64 v[74:75], v[98:99], 0, v[96:97]
	v_lshlrev_b32_e32 v96, 11, v82
	s_waitcnt lgkmcnt(1)
	global_store_dwordx4 v[74:75], v[64:67], off nt
	v_or_b32_e32 v86, 56, v132
	v_cvt_pk_bf16_f32 v60, v60, v61
	v_lshl_add_u64 v[64:65], v[98:99], 0, v[96:97]
	s_waitcnt lgkmcnt(0)
	global_store_dwordx4 v[64:65], v[68:71], off nt
	v_cvt_pk_bf16_f32 v61, v62, v63
	v_cvt_pk_bf16_f32 v56, v56, v57
	v_or_b32_e32 v68, 32, v132
	v_lshl_or_b32 v82, v68, 7, v141
	ds_read_b128 v[64:67], v82
	v_lshlrev_b32_e32 v96, 11, v68
	ds_read_b128 v[68:71], v85
	v_lshl_add_u64 v[74:75], v[98:99], 0, v[96:97]
	v_lshlrev_b32_e32 v96, 11, v84
	s_waitcnt lgkmcnt(1)
	global_store_dwordx4 v[74:75], v[64:67], off nt
	v_cvt_pk_bf16_f32 v57, v58, v59
	v_cvt_pk_bf16_f32 v52, v52, v53
	v_lshl_add_u64 v[64:65], v[98:99], 0, v[96:97]
	s_waitcnt lgkmcnt(0)
	global_store_dwordx4 v[64:65], v[68:71], off nt
	v_cvt_pk_bf16_f32 v53, v54, v55
	v_cvt_pk_bf16_f32 v48, v48, v49
	v_or_b32_e32 v68, 48, v132
	v_cvt_pk_bf16_f32 v49, v50, v51
	v_cvt_pk_bf16_f32 v4, v4, v5
	v_cvt_pk_bf16_f32 v5, v6, v7
	v_lshl_or_b32 v84, v68, 7, v141
	v_lshl_or_b32 v87, v86, 7, v141
	ds_write_b64 v124, v[60:61]
	ds_write_b64 v126, v[56:57]
	ds_write_b64 v121, v[52:53]
	ds_write_b64 v117, v[48:49]
	ds_write_b64 v117, v[4:5] offset:4096
	v_cvt_pk_bf16_f32 v4, v16, v17
	v_cvt_pk_bf16_f32 v5, v18, v19
	v_cvt_pk_bf16_f32 v0, v0, v1
	v_cvt_pk_bf16_f32 v1, v2, v3
	ds_read_b128 v[64:67], v84
	v_lshlrev_b32_e32 v96, 11, v68
	ds_read_b128 v[68:71], v87
	ds_write_b64 v76, v[4:5]
	v_cvt_pk_bf16_f32 v4, v12, v13
	v_cvt_pk_bf16_f32 v5, v14, v15
	ds_write_b64 v79, v[0:1]
	ds_read_b128 v[0:3], v142
	ds_write_b64 v77, v[4:5]
	v_cvt_pk_bf16_f32 v4, v8, v9
	v_cvt_pk_bf16_f32 v5, v10, v11
	ds_write_b64 v78, v[4:5]
	s_mov_b32 s37, 0x20000
	ds_read_b128 v[4:7], v80
	v_add_co_u32_e32 v8, vcc, s37, v72
	s_mov_b32 s6, 0x24000
	s_nop 0
	v_addc_co_u32_e32 v9, vcc, 0, v73, vcc
	v_cvt_pk_bf16_f32 v44, v44, v45
	v_cvt_pk_bf16_f32 v45, v46, v47
	v_cvt_pk_bf16_f32 v40, v40, v41
	v_cvt_pk_bf16_f32 v41, v42, v43
	v_cvt_pk_bf16_f32 v36, v36, v37
	v_cvt_pk_bf16_f32 v37, v38, v39
	v_cvt_pk_bf16_f32 v28, v28, v29
	v_cvt_pk_bf16_f32 v29, v30, v31
	s_waitcnt lgkmcnt(3)
	global_store_dwordx4 v[8:9], v[0:3], off nt
	ds_write_b64 v124, v[44:45] offset:2048
	ds_write_b64 v126, v[40:41] offset:2048
	v_add_co_u32_e32 v0, vcc, s6, v72
	ds_write_b64 v121, v[36:37] offset:2048
	ds_write_b64 v117, v[28:29] offset:2048
	v_addc_co_u32_e32 v1, vcc, 0, v73, vcc
	s_waitcnt lgkmcnt(4)
	global_store_dwordx4 v[0:1], v[4:7], off nt
	ds_read_b128 v[0:3], v81
	ds_read_b128 v[4:7], v83
	s_mov_b32 s6, 0x28000
	v_add_co_u32_e32 v8, vcc, s6, v72
	s_mov_b32 s6, 0x2c000
	s_nop 0
	v_addc_co_u32_e32 v9, vcc, 0, v73, vcc
	v_cvt_pk_bf16_f32 v28, v32, v33
	v_cvt_pk_bf16_f32 v29, v34, v35
	v_cvt_pk_bf16_f32 v24, v24, v25
	v_cvt_pk_bf16_f32 v25, v26, v27
	v_cvt_pk_bf16_f32 v20, v20, v21
	v_cvt_pk_bf16_f32 v21, v22, v23
	s_waitcnt lgkmcnt(1)
	global_store_dwordx4 v[8:9], v[0:3], off nt
	ds_write_b64 v124, v[28:29] offset:4096
	ds_write_b64 v126, v[24:25] offset:4096
	v_add_co_u32_e32 v0, vcc, s6, v72
	ds_write_b64 v121, v[20:21] offset:4096
	s_nop 0
	v_addc_co_u32_e32 v1, vcc, 0, v73, vcc
	s_waitcnt lgkmcnt(3)
	global_store_dwordx4 v[0:1], v[4:7], off nt
	ds_read_b128 v[0:3], v82
	ds_read_b128 v[4:7], v85
	s_mov_b32 s6, 0x30000
	v_add_co_u32_e32 v8, vcc, s6, v72
	s_mov_b32 s6, 0x34000
	s_nop 0
	v_addc_co_u32_e32 v9, vcc, 0, v73, vcc
	s_waitcnt lgkmcnt(1)
	global_store_dwordx4 v[8:9], v[0:3], off nt
	v_lshl_add_u64 v[74:75], v[98:99], 0, v[96:97]
	v_lshlrev_b32_e32 v96, 11, v86
	v_add_co_u32_e32 v0, vcc, s6, v72
	global_store_dwordx4 v[74:75], v[64:67], off nt
	s_nop 0
	v_addc_co_u32_e32 v1, vcc, 0, v73, vcc
	s_waitcnt lgkmcnt(0)
	global_store_dwordx4 v[0:1], v[4:7], off nt
	ds_read_b128 v[0:3], v84
	ds_read_b128 v[4:7], v87
	v_add_co_u32_e32 v8, vcc, 0x38000, v72
	v_lshl_add_u64 v[64:65], v[98:99], 0, v[96:97]
	s_nop 0
	v_addc_co_u32_e32 v9, vcc, 0, v73, vcc
	s_waitcnt lgkmcnt(1)
	global_store_dwordx4 v[8:9], v[0:3], off nt
	s_mov_b32 s7, s31
	s_mov_b32 s6, s30
	v_add_co_u32_e32 v0, vcc, 0x3c000, v72
	global_store_dwordx4 v[64:65], v[68:71], off nt
	s_nop 0
	v_addc_co_u32_e32 v1, vcc, 0, v73, vcc
	s_and_b64 vcc, exec, s[2:3]
	s_waitcnt lgkmcnt(0)
	global_store_dwordx4 v[0:1], v[4:7], off nt
	s_barrier
	s_cbranch_vccnz .LBB0_603

; #define G_WAIT_V0() asm volatile("s_waitcnt vmcnt(0)" ::: "memory")
; __device__ __forceinline__ void g_kloop(const u16* __restrict__ Ab, const u16* __restrict__ Bb, const int K, char* smem, ...
;     ...
;     for (int ks = 0; ks < 2; ++ks) {
;       s16x8 At[8], Bf[4];
; #pragma unroll
;       for (int m = 0; m < 8; ++m) At[m] = *(const s16x8*)(sa + g_lds_byte(wr * 128 + m * 16 + fr, ks * 32 + fq * 8));
; #pragma unroll
;       for (int n = 0; n < 4; ++n) Bf[n] = *(const s16x8*)(sb + g_lds_byte(wc * 64 + n * 16 + fr, ks * 32 + fq * 8));
; #pragma unroll
;       for (int m = 0; m < 8; ++m)
; #pragma unroll
;         for (int n = 0; n < 4; ++n)
;           acc[m][n] = __builtin_amdgcn_mfma_f32_16x16x32_bf16(__builtin_bit_cast(bf16x8, Bf[n]), __builtin_bit_cast(bf16x8, At[m]), acc[m][n], 0, 0, 0);
;     }
;     G_WAIT_V0();
;     __syncthreads();
.LBB0_601:
	ds_read_b128 v[132:135], v201
	ds_read_b128 v[160:163], v189
	ds_read_b128 v[164:167], v201 offset:2048
	ds_read_b128 v[168:171], v201 offset:4096
	ds_read_b128 v[172:175], v201 offset:6144
	v_add_u32_e32 v96, v188, v179
	s_waitcnt lgkmcnt(0)
	v_mfma_f32_16x16x32_bf16 v[124:127], v[132:135], v[160:163], v[124:127]
	v_mfma_f32_16x16x32_bf16 v[128:131], v[164:167], v[160:163], v[128:131]
	v_mfma_f32_16x16x32_bf16 v[120:123], v[168:171], v[160:163], v[120:123]
	v_mfma_f32_16x16x32_bf16 v[116:119], v[172:175], v[160:163], v[116:119]
	ds_read_b128 v[160:163], v96
	s_waitcnt lgkmcnt(0)
	v_mfma_f32_16x16x32_bf16 v[112:115], v[132:135], v[160:163], v[112:115]
	v_mfma_f32_16x16x32_bf16 v[108:111], v[164:167], v[160:163], v[108:111]
	v_mfma_f32_16x16x32_bf16 v[104:107], v[168:171], v[160:163], v[104:107]
	v_mfma_f32_16x16x32_bf16 v[92:95], v[172:175], v[160:163], v[92:95]
	ds_read_b128 v[160:163], v190
	s_waitcnt lgkmcnt(0)
	v_mfma_f32_16x16x32_bf16 v[98:101], v[132:135], v[160:163], v[100:103]
	v_mfma_f32_16x16x32_bf16 v[88:91], v[164:167], v[160:163], v[88:91]
	v_mfma_f32_16x16x32_bf16 v[84:87], v[168:171], v[160:163], v[84:87]
	v_mfma_f32_16x16x32_bf16 v[80:83], v[172:175], v[160:163], v[80:83]
	ds_read_b128 v[160:163], v191
	s_waitcnt lgkmcnt(0)
	v_mfma_f32_16x16x32_bf16 v[76:79], v[132:135], v[160:163], v[76:79]
	v_mfma_f32_16x16x32_bf16 v[72:75], v[164:167], v[160:163], v[72:75]
	v_mfma_f32_16x16x32_bf16 v[68:71], v[168:171], v[160:163], v[68:71]
	v_mfma_f32_16x16x32_bf16 v[60:63], v[172:175], v[160:163], v[60:63]
	ds_read_b128 v[160:163], v192
	s_waitcnt lgkmcnt(0)
	v_mfma_f32_16x16x32_bf16 v[64:67], v[132:135], v[160:163], v[64:67]
	v_mfma_f32_16x16x32_bf16 v[56:59], v[164:167], v[160:163], v[56:59]
	v_mfma_f32_16x16x32_bf16 v[52:55], v[168:171], v[160:163], v[52:55]
	v_mfma_f32_16x16x32_bf16 v[48:51], v[172:175], v[160:163], v[48:51]
	ds_read_b128 v[160:163], v193
	s_waitcnt lgkmcnt(0)
	v_mfma_f32_16x16x32_bf16 v[44:47], v[132:135], v[160:163], v[44:47]
	v_mfma_f32_16x16x32_bf16 v[40:43], v[164:167], v[160:163], v[40:43]
	v_mfma_f32_16x16x32_bf16 v[36:39], v[168:171], v[160:163], v[36:39]
	v_mfma_f32_16x16x32_bf16 v[28:31], v[172:175], v[160:163], v[28:31]
	ds_read_b128 v[160:163], v197
	s_waitcnt lgkmcnt(0)
	v_mfma_f32_16x16x32_bf16 v[32:35], v[132:135], v[160:163], v[32:35]
	v_mfma_f32_16x16x32_bf16 v[24:27], v[164:167], v[160:163], v[24:27]
	v_mfma_f32_16x16x32_bf16 v[20:23], v[168:171], v[160:163], v[20:23]
	v_mfma_f32_16x16x32_bf16 v[4:7], v[172:175], v[160:163], v[4:7]
	ds_read_b128 v[160:163], v199
	s_waitcnt lgkmcnt(0)
	v_mfma_f32_16x16x32_bf16 v[16:19], v[132:135], v[160:163], v[16:19]
	ds_read_b128 v[132:135], v201 offset:1024
	v_mfma_f32_16x16x32_bf16 v[12:15], v[164:167], v[160:163], v[12:15]
	ds_read_b128 v[164:167], v201 offset:3072
	v_mfma_f32_16x16x32_bf16 v[8:11], v[168:171], v[160:163], v[8:11]
	ds_read_b128 v[168:171], v201 offset:5120
	v_mfma_f32_16x16x32_bf16 v[0:3], v[172:175], v[160:163], v[0:3]
	ds_read_b128 v[172:175], v201 offset:7168
	ds_read_b128 v[160:163], v189 offset:1024
	s_waitcnt lgkmcnt(0)
	v_mfma_f32_16x16x32_bf16 v[124:127], v[132:135], v[160:163], v[124:127]
	v_mfma_f32_16x16x32_bf16 v[128:131], v[164:167], v[160:163], v[128:131]
	v_mfma_f32_16x16x32_bf16 v[120:123], v[168:171], v[160:163], v[120:123]
	v_mfma_f32_16x16x32_bf16 v[116:119], v[172:175], v[160:163], v[116:119]
	ds_read_b128 v[160:163], v96 offset:1024
	s_waitcnt lgkmcnt(0)
	v_mfma_f32_16x16x32_bf16 v[112:115], v[132:135], v[160:163], v[112:115]
	v_mfma_f32_16x16x32_bf16 v[108:111], v[164:167], v[160:163], v[108:111]
	v_mfma_f32_16x16x32_bf16 v[104:107], v[168:171], v[160:163], v[104:107]
	v_mfma_f32_16x16x32_bf16 v[92:95], v[172:175], v[160:163], v[92:95]
	ds_read_b128 v[160:163], v190 offset:1024
	s_waitcnt lgkmcnt(0)
	v_mfma_f32_16x16x32_bf16 v[100:103], v[132:135], v[160:163], v[98:101]
	v_mfma_f32_16x16x32_bf16 v[88:91], v[164:167], v[160:163], v[88:91]
	v_mfma_f32_16x16x32_bf16 v[84:87], v[168:171], v[160:163], v[84:87]
	v_mfma_f32_16x16x32_bf16 v[80:83], v[172:175], v[160:163], v[80:83]
	ds_read_b128 v[160:163], v191 offset:1024
	s_waitcnt lgkmcnt(0)
	v_mfma_f32_16x16x32_bf16 v[76:79], v[132:135], v[160:163], v[76:79]
	v_mfma_f32_16x16x32_bf16 v[72:75], v[164:167], v[160:163], v[72:75]
	v_mfma_f32_16x16x32_bf16 v[68:71], v[168:171], v[160:163], v[68:71]
	v_mfma_f32_16x16x32_bf16 v[60:63], v[172:175], v[160:163], v[60:63]
	ds_read_b128 v[160:163], v192 offset:1024
	s_waitcnt lgkmcnt(0)
	v_mfma_f32_16x16x32_bf16 v[64:67], v[132:135], v[160:163], v[64:67]
	v_mfma_f32_16x16x32_bf16 v[56:59], v[164:167], v[160:163], v[56:59]
	v_mfma_f32_16x16x32_bf16 v[52:55], v[168:171], v[160:163], v[52:55]
	v_mfma_f32_16x16x32_bf16 v[48:51], v[172:175], v[160:163], v[48:51]
	ds_read_b128 v[160:163], v193 offset:1024
	s_waitcnt lgkmcnt(0)
	v_mfma_f32_16x16x32_bf16 v[44:47], v[132:135], v[160:163], v[44:47]
	v_mfma_f32_16x16x32_bf16 v[40:43], v[164:167], v[160:163], v[40:43]
	v_mfma_f32_16x16x32_bf16 v[36:39], v[168:171], v[160:163], v[36:39]
	v_mfma_f32_16x16x32_bf16 v[28:31], v[172:175], v[160:163], v[28:31]
	ds_read_b128 v[160:163], v197 offset:1024
	s_waitcnt lgkmcnt(0)
	v_mfma_f32_16x16x32_bf16 v[32:35], v[132:135], v[160:163], v[32:35]
	v_mfma_f32_16x16x32_bf16 v[24:27], v[164:167], v[160:163], v[24:27]
	v_mfma_f32_16x16x32_bf16 v[20:23], v[168:171], v[160:163], v[20:23]
	v_mfma_f32_16x16x32_bf16 v[4:7], v[172:175], v[160:163], v[4:7]
	ds_read_b128 v[160:163], v199 offset:1024
	s_waitcnt vmcnt(0)
	s_waitcnt vmcnt(0) lgkmcnt(0)
	v_mfma_f32_16x16x32_bf16 v[16:19], v[132:135], v[160:163], v[16:19]
	s_barrier
; __device__ __forceinline__ float bflo(unsigned u) { return __uint_as_float(u << 16); }
; __device__ __forceinline__ float bfhi(unsigned u) { return __uint_as_float(u & 0xffff0000u); }
; __device__ __forceinline__ int opaque_tid() { int t = threadIdx.x; asm volatile("" : "+v"(t)); return t; }
; __device__ void gemm2_phase(const Params& P, int layer, char* smem) {
;     ...
;       if (pass == 0) {
;         const int tid1 = opaque_tid(), wid1 = tid1 >> 6, lane1 = tid1 & 63, wr1 = wid1 >> 2, wc1 = wid1 & 3, fr1 = lane1 & 15, fq1 = lane1 >> 4;
;         const u16* pp = P.proj + (size_t)(u.pm * 256 + wr1 * 128 + fr1) * INC + u.pn * 256 + wc1 * 64 + fq1 * 4;
; #pragma unroll
;         for (int m = 0; m < 8; m++) {
; #pragma unroll
;           for (int n = 0; n < 4; n++) {
;             const uint2 ra = *(const uint2*)(pp + (size_t)(m * 16) * INC + C_RA + n * 16);
;             const uint2 rb = *(const uint2*)(pp + (size_t)(m * 16) * INC + C_RB + n * 16);
;             acc[m][n][0] *= (1.f + __expf(-bflo(rb.x))) * __builtin_amdgcn_rcpf(1.f + __expf(-bflo(ra.x)));
;             acc[m][n][1] *= (1.f + __expf(-bfhi(rb.x))) * __builtin_amdgcn_rcpf(1.f + __expf(-bfhi(ra.x)));
;             acc[m][n][2] *= (1.f + __expf(-bflo(rb.y))) * __builtin_amdgcn_rcpf(1.f + __expf(-bflo(ra.y)));
;             acc[m][n][3] *= (1.f + __expf(-bfhi(rb.y))) * __builtin_amdgcn_rcpf(1.f + __expf(-bfhi(ra.y)));
;           }
;           if (m & 1) __builtin_amdgcn_sched_barrier(0);
	v_mfma_f32_16x16x32_bf16 v[12:15], v[164:167], v[160:163], v[12:15]
	v_mfma_f32_16x16x32_bf16 v[8:11], v[168:171], v[160:163], v[8:11]
	v_mfma_f32_16x16x32_bf16 v[0:3], v[172:175], v[160:163], v[0:3]
	s_andn2_b64 vcc, exec, s[22:23]
	s_cbranch_vccnz .LBB0_594
	v_mov_b32_e32 v132, v195
	s_movk_i32 s22, 0x4680
	v_ashrrev_i32_e32 v98, 1, v132
	v_and_b32_e32 v98, 0xffffff80, v98
	v_add_u32_e32 v98, s10, v98
	v_and_b32_e32 v96, 0xc0, v132
	v_and_or_b32 v133, v132, 15, v98
	v_mov_b64_e32 v[98:99], s[16:17]
	v_mad_i64_i32 v[98:99], s[22:23], v133, s22, v[98:99]
	v_lshlrev_b32_e32 v96, 1, v96
	v_lshl_add_u64 v[98:99], v[98:99], 0, v[96:97]
	v_lshrrev_b32_e32 v96, 1, v132
	v_and_b32_e32 v96, 24, v96
	v_lshl_add_u64 v[98:99], v[98:99], 0, v[96:97]
	v_add_co_u32_e32 v132, vcc, 0x3000, v98
	s_mov_b32 s22, 0x4a000
	s_nop 0
	v_addc_co_u32_e32 v133, vcc, 0, v99, vcc
	global_load_dwordx2 v[134:135], v[132:133], off offset:1664
	global_load_dwordx2 v[160:161], v[132:133], off offset:3712
	global_load_dwordx2 v[204:205], v[132:133], off offset:1696
	global_load_dwordx2 v[206:207], v[132:133], off offset:3744
	global_load_dwordx2 v[208:209], v[132:133], off offset:1728
	global_load_dwordx2 v[210:211], v[132:133], off offset:3776
	global_load_dwordx2 v[212:213], v[132:133], off offset:1760
	global_load_dwordx2 v[214:215], v[132:133], off offset:3808
	s_waitcnt vmcnt(0)
	v_lshlrev_b32_e32 v96, 16, v160
	v_mul_f32_e32 v96, 0xbfb8aa3b, v96
	v_exp_f32_e32 v162, v96
	v_lshlrev_b32_e32 v96, 16, v134
	v_mul_f32_e32 v96, 0xbfb8aa3b, v96
	v_exp_f32_e32 v96, v96
	s_nop 0
	v_add_f32_e32 v96, 1.0, v96
	v_rcp_f32_e32 v164, v96
	v_and_b32_e32 v96, 0xffff0000, v160
	v_mul_f32_e32 v96, 0xbfb8aa3b, v96
	v_exp_f32_e32 v163, v96
	v_and_b32_e32 v96, 0xffff0000, v134
	v_mul_f32_e32 v96, 0xbfb8aa3b, v96
	v_exp_f32_e32 v96, v96
	v_pk_add_f32 v[162:163], v[162:163], 1.0 op_sel_hi:[1,0]
	v_add_f32_e32 v96, 1.0, v96
	v_rcp_f32_e32 v165, v96
	v_lshlrev_b32_e32 v96, 16, v161
	v_mul_f32_e32 v96, 0xbfb8aa3b, v96
	v_exp_f32_e32 v160, v96
	v_lshlrev_b32_e32 v96, 16, v135
	v_mul_f32_e32 v96, 0xbfb8aa3b, v96
	v_exp_f32_e32 v96, v96
	v_pk_mul_f32 v[162:163], v[164:165], v[162:163]
	v_add_f32_e32 v96, 1.0, v96
	v_rcp_f32_e32 v134, v96
	v_and_b32_e32 v96, 0xffff0000, v161
	v_mul_f32_e32 v96, 0xbfb8aa3b, v96
	v_exp_f32_e32 v161, v96
	v_and_b32_e32 v96, 0xffff0000, v135
	v_mul_f32_e32 v96, 0xbfb8aa3b, v96
	v_exp_f32_e32 v96, v96
	v_pk_add_f32 v[160:161], v[160:161], 1.0 op_sel_hi:[1,0]
	v_pk_mul_f32 v[124:125], v[124:125], v[162:163]
	v_add_f32_e32 v96, 1.0, v96
	v_rcp_f32_e32 v135, v96
	s_nop 0
	v_pk_mul_f32 v[134:135], v[134:135], v[160:161]
	s_nop 0
	v_pk_mul_f32 v[126:127], v[126:127], v[134:135]
	v_mov_b32_e32 v134, v204
	v_mov_b32_e32 v135, v205
	v_mov_b32_e32 v160, v206
	v_mov_b32_e32 v161, v207
	s_waitcnt vmcnt(0)
	v_lshlrev_b32_e32 v96, 16, v160
	v_mul_f32_e32 v96, 0xbfb8aa3b, v96
	v_exp_f32_e32 v162, v96
	v_lshlrev_b32_e32 v96, 16, v134
	v_mul_f32_e32 v96, 0xbfb8aa3b, v96
	v_exp_f32_e32 v96, v96
	s_nop 0
	v_add_f32_e32 v96, 1.0, v96
	v_rcp_f32_e32 v164, v96
	v_and_b32_e32 v96, 0xffff0000, v160
	v_mul_f32_e32 v96, 0xbfb8aa3b, v96
	v_exp_f32_e32 v163, v96
	v_and_b32_e32 v96, 0xffff0000, v134
	v_mul_f32_e32 v96, 0xbfb8aa3b, v96
	v_exp_f32_e32 v96, v96
	v_pk_add_f32 v[162:163], v[162:163], 1.0 op_sel_hi:[1,0]
	v_add_f32_e32 v96, 1.0, v96
	v_rcp_f32_e32 v165, v96
	v_lshlrev_b32_e32 v96, 16, v161
	v_mul_f32_e32 v96, 0xbfb8aa3b, v96
	v_exp_f32_e32 v160, v96
	v_lshlrev_b32_e32 v96, 16, v135
	v_mul_f32_e32 v96, 0xbfb8aa3b, v96
	v_exp_f32_e32 v96, v96
	v_pk_mul_f32 v[162:163], v[164:165], v[162:163]
	v_add_f32_e32 v96, 1.0, v96
	v_rcp_f32_e32 v134, v96
	v_and_b32_e32 v96, 0xffff0000, v161
	v_mul_f32_e32 v96, 0xbfb8aa3b, v96
	v_exp_f32_e32 v161, v96
	v_and_b32_e32 v96, 0xffff0000, v135
	v_mul_f32_e32 v96, 0xbfb8aa3b, v96
	v_exp_f32_e32 v96, v96
	v_pk_add_f32 v[160:161], v[160:161], 1.0 op_sel_hi:[1,0]
	v_pk_mul_f32 v[128:129], v[128:129], v[162:163]
	v_add_f32_e32 v96, 1.0, v96
	v_rcp_f32_e32 v135, v96
	s_nop 0
	v_pk_mul_f32 v[134:135], v[134:135], v[160:161]
	s_nop 0
	v_pk_mul_f32 v[130:131], v[130:131], v[134:135]
	v_mov_b32_e32 v134, v208
	v_mov_b32_e32 v135, v209
	v_mov_b32_e32 v160, v210
	v_mov_b32_e32 v161, v211
	s_waitcnt vmcnt(0)
	v_lshlrev_b32_e32 v96, 16, v160
	v_mul_f32_e32 v96, 0xbfb8aa3b, v96
	v_exp_f32_e32 v162, v96
	v_lshlrev_b32_e32 v96, 16, v134
	v_mul_f32_e32 v96, 0xbfb8aa3b, v96
	v_exp_f32_e32 v96, v96
	s_nop 0
	v_add_f32_e32 v96, 1.0, v96
	v_rcp_f32_e32 v164, v96
	v_and_b32_e32 v96, 0xffff0000, v160
	v_mul_f32_e32 v96, 0xbfb8aa3b, v96
	v_exp_f32_e32 v163, v96
	v_and_b32_e32 v96, 0xffff0000, v134
	v_mul_f32_e32 v96, 0xbfb8aa3b, v96
	v_exp_f32_e32 v96, v96
	v_pk_add_f32 v[162:163], v[162:163], 1.0 op_sel_hi:[1,0]
	v_add_f32_e32 v96, 1.0, v96
	v_rcp_f32_e32 v165, v96
	v_lshlrev_b32_e32 v96, 16, v161
	v_mul_f32_e32 v96, 0xbfb8aa3b, v96
	v_exp_f32_e32 v160, v96
	v_lshlrev_b32_e32 v96, 16, v135
	v_mul_f32_e32 v96, 0xbfb8aa3b, v96
	v_exp_f32_e32 v96, v96
	v_pk_mul_f32 v[162:163], v[164:165], v[162:163]
	v_add_f32_e32 v96, 1.0, v96
	v_rcp_f32_e32 v134, v96
	v_and_b32_e32 v96, 0xffff0000, v161
	v_mul_f32_e32 v96, 0xbfb8aa3b, v96
	v_exp_f32_e32 v161, v96
	v_and_b32_e32 v96, 0xffff0000, v135
	v_mul_f32_e32 v96, 0xbfb8aa3b, v96
	v_exp_f32_e32 v96, v96
	v_pk_add_f32 v[160:161], v[160:161], 1.0 op_sel_hi:[1,0]
	v_pk_mul_f32 v[120:121], v[120:121], v[162:163]
	v_add_f32_e32 v96, 1.0, v96
	v_rcp_f32_e32 v135, v96
	s_nop 0
	v_pk_mul_f32 v[134:135], v[134:135], v[160:161]
	s_nop 0
	v_pk_mul_f32 v[122:123], v[122:123], v[134:135]
	v_mov_b32_e32 v134, v212
	v_mov_b32_e32 v135, v213
	s_nop 0
	v_mov_b32_e32 v132, v214
	v_mov_b32_e32 v133, v215
	s_waitcnt vmcnt(0)
; __device__ __forceinline__ float bflo(unsigned u) { return __uint_as_float(u << 16); }
; __device__ __forceinline__ float bfhi(unsigned u) { return __uint_as_float(u & 0xffff0000u); }
; __device__ void gemm2_phase(const Params& P, int layer, char* smem) {
;     ...
;             const uint2 ra = *(const uint2*)(pp + (size_t)(m * 16) * INC + C_RA + n * 16);
;             const uint2 rb = *(const uint2*)(pp + (size_t)(m * 16) * INC + C_RB + n * 16);
;             acc[m][n][0] *= (1.f + __expf(-bflo(rb.x))) * __builtin_amdgcn_rcpf(1.f + __expf(-bflo(ra.x)));
;             acc[m][n][1] *= (1.f + __expf(-bfhi(rb.x))) * __builtin_amdgcn_rcpf(1.f + __expf(-bfhi(ra.x)));
;             acc[m][n][2] *= (1.f + __expf(-bflo(rb.y))) * __builtin_amdgcn_rcpf(1.f + __expf(-bflo(ra.y)));
;             acc[m][n][3] *= (1.f + __expf(-bfhi(rb.y))) * __builtin_amdgcn_rcpf(1.f + __expf(-bfhi(ra.y)));
;           }
;           if (m & 1) __builtin_amdgcn_sched_barrier(0);
	v_lshlrev_b32_e32 v96, 16, v132
	v_mul_f32_e32 v96, 0xbfb8aa3b, v96
	v_exp_f32_e32 v160, v96
	v_lshlrev_b32_e32 v96, 16, v134
	v_mul_f32_e32 v96, 0xbfb8aa3b, v96
	v_exp_f32_e32 v96, v96
	s_nop 0
	v_add_f32_e32 v96, 1.0, v96
	v_rcp_f32_e32 v162, v96
	v_and_b32_e32 v96, 0xffff0000, v132
	v_mul_f32_e32 v96, 0xbfb8aa3b, v96
	v_exp_f32_e32 v161, v96
	v_and_b32_e32 v96, 0xffff0000, v134
	v_mul_f32_e32 v96, 0xbfb8aa3b, v96
	v_exp_f32_e32 v96, v96
	v_pk_add_f32 v[160:161], v[160:161], 1.0 op_sel_hi:[1,0]
	v_add_f32_e32 v96, 1.0, v96
	v_rcp_f32_e32 v163, v96
	v_lshlrev_b32_e32 v96, 16, v133
	v_mul_f32_e32 v96, 0xbfb8aa3b, v96
	v_exp_f32_e32 v132, v96
	v_lshlrev_b32_e32 v96, 16, v135
	v_mul_f32_e32 v96, 0xbfb8aa3b, v96
	v_exp_f32_e32 v96, v96
	v_pk_mul_f32 v[160:161], v[162:163], v[160:161]
	v_add_f32_e32 v96, 1.0, v96
	v_rcp_f32_e32 v134, v96
	v_and_b32_e32 v96, 0xffff0000, v133
	v_mul_f32_e32 v96, 0xbfb8aa3b, v96
	v_exp_f32_e32 v133, v96
	v_and_b32_e32 v96, 0xffff0000, v135
	v_mul_f32_e32 v96, 0xbfb8aa3b, v96
	v_exp_f32_e32 v96, v96
	v_pk_add_f32 v[132:133], v[132:133], 1.0 op_sel_hi:[1,0]
	v_pk_mul_f32 v[116:117], v[116:117], v[160:161]
	v_add_f32_e32 v96, 1.0, v96
	v_rcp_f32_e32 v135, v96
	s_nop 0
	v_pk_mul_f32 v[132:133], v[134:135], v[132:133]
	s_nop 0
	v_pk_mul_f32 v[118:119], v[118:119], v[132:133]
	v_add_co_u32_e32 v132, vcc, s22, v98
	s_mov_b32 s22, 0x49000
	s_nop 0
	v_addc_co_u32_e32 v133, vcc, 0, v99, vcc
	v_add_co_u32_e32 v134, vcc, s22, v98
	global_load_dwordx2 v[160:161], v[132:133], off offset:1696
	s_nop 0
	v_addc_co_u32_e32 v135, vcc, 0, v99, vcc
	global_load_dwordx2 v[162:163], v[134:135], off offset:3744
	global_load_dwordx2 v[164:165], v[132:133], off offset:1664
	global_load_dwordx2 v[166:167], v[134:135], off offset:3712
	s_waitcnt vmcnt(1)
	v_lshlrev_b32_e32 v96, 16, v164
	v_mul_f32_e32 v96, 0xbfb8aa3b, v96
	v_exp_f32_e32 v168, v96
	s_waitcnt vmcnt(0)
	v_lshlrev_b32_e32 v96, 16, v166
	v_mul_f32_e32 v96, 0xbfb8aa3b, v96
	v_exp_f32_e32 v96, v96
	s_nop 0
	v_add_f32_e32 v96, 1.0, v96
	v_rcp_f32_e32 v170, v96
	v_and_b32_e32 v96, 0xffff0000, v164
	v_mul_f32_e32 v96, 0xbfb8aa3b, v96
	v_exp_f32_e32 v169, v96
	v_and_b32_e32 v96, 0xffff0000, v166
	v_mul_f32_e32 v96, 0xbfb8aa3b, v96
	v_exp_f32_e32 v96, v96
	v_pk_add_f32 v[168:169], v[168:169], 1.0 op_sel_hi:[1,0]
	v_add_f32_e32 v96, 1.0, v96
	v_rcp_f32_e32 v171, v96
	v_lshlrev_b32_e32 v96, 16, v165
	v_mul_f32_e32 v96, 0xbfb8aa3b, v96
	v_exp_f32_e32 v164, v96
	v_lshlrev_b32_e32 v96, 16, v167
	v_mul_f32_e32 v96, 0xbfb8aa3b, v96
	v_exp_f32_e32 v96, v96
	v_pk_mul_f32 v[168:169], v[168:169], v[170:171]
	v_add_f32_e32 v96, 1.0, v96
	v_rcp_f32_e32 v166, v96
	v_and_b32_e32 v96, 0xffff0000, v165
	v_mul_f32_e32 v96, 0xbfb8aa3b, v96
	v_exp_f32_e32 v165, v96
	v_and_b32_e32 v96, 0xffff0000, v167
	v_mul_f32_e32 v96, 0xbfb8aa3b, v96
	v_exp_f32_e32 v96, v96
	v_pk_add_f32 v[164:165], v[164:165], 1.0 op_sel_hi:[1,0]
	v_pk_mul_f32 v[112:113], v[112:113], v[168:169]
	v_add_f32_e32 v96, 1.0, v96
	v_rcp_f32_e32 v167, v96
	v_lshlrev_b32_e32 v96, 16, v160
	v_mul_f32_e32 v96, 0xbfb8aa3b, v96
	v_pk_mul_f32 v[164:165], v[164:165], v[166:167]
	s_nop 0
	v_pk_mul_f32 v[114:115], v[114:115], v[164:165]
	v_exp_f32_e32 v164, v96
	v_lshlrev_b32_e32 v96, 16, v162
	v_mul_f32_e32 v96, 0xbfb8aa3b, v96
	v_exp_f32_e32 v96, v96
	s_nop 0
	v_add_f32_e32 v96, 1.0, v96
	v_rcp_f32_e32 v166, v96
	v_and_b32_e32 v96, 0xffff0000, v160
	v_mul_f32_e32 v96, 0xbfb8aa3b, v96
	v_exp_f32_e32 v165, v96
	v_and_b32_e32 v96, 0xffff0000, v162
	v_mul_f32_e32 v96, 0xbfb8aa3b, v96
	v_exp_f32_e32 v96, v96
	v_pk_add_f32 v[164:165], v[164:165], 1.0 op_sel_hi:[1,0]
	v_add_f32_e32 v96, 1.0, v96
	v_rcp_f32_e32 v167, v96
	v_lshlrev_b32_e32 v96, 16, v161
	v_mul_f32_e32 v96, 0xbfb8aa3b, v96
	v_exp_f32_e32 v160, v96
	v_lshlrev_b32_e32 v96, 16, v163
	v_mul_f32_e32 v96, 0xbfb8aa3b, v96
	v_exp_f32_e32 v96, v96
	v_pk_mul_f32 v[164:165], v[164:165], v[166:167]
	v_add_f32_e32 v96, 1.0, v96
	v_rcp_f32_e32 v162, v96
	v_and_b32_e32 v96, 0xffff0000, v161
	v_mul_f32_e32 v96, 0xbfb8aa3b, v96
	v_exp_f32_e32 v161, v96
	v_and_b32_e32 v96, 0xffff0000, v163
	v_mul_f32_e32 v96, 0xbfb8aa3b, v96
	v_exp_f32_e32 v96, v96
	v_pk_add_f32 v[160:161], v[160:161], 1.0 op_sel_hi:[1,0]
	v_pk_mul_f32 v[108:109], v[108:109], v[164:165]
	v_add_f32_e32 v96, 1.0, v96
	v_rcp_f32_e32 v163, v96
	s_nop 0
	v_pk_mul_f32 v[160:161], v[160:161], v[162:163]
	s_nop 0
	v_pk_mul_f32 v[110:111], v[110:111], v[160:161]
	global_load_dwordx2 v[160:161], v[134:135], off offset:3776
	global_load_dwordx2 v[162:163], v[132:133], off offset:1728
	s_waitcnt vmcnt(0)
	v_lshlrev_b32_e32 v96, 16, v162
	v_mul_f32_e32 v96, 0xbfb8aa3b, v96
	v_exp_f32_e32 v164, v96
	v_lshlrev_b32_e32 v96, 16, v160
	v_mul_f32_e32 v96, 0xbfb8aa3b, v96
	v_exp_f32_e32 v96, v96
	s_nop 0
	v_add_f32_e32 v96, 1.0, v96
	v_rcp_f32_e32 v166, v96
	v_and_b32_e32 v96, 0xffff0000, v162
	v_mul_f32_e32 v96, 0xbfb8aa3b, v96
	v_exp_f32_e32 v165, v96
	v_and_b32_e32 v96, 0xffff0000, v160
	v_mul_f32_e32 v96, 0xbfb8aa3b, v96
	v_exp_f32_e32 v96, v96
	v_pk_add_f32 v[164:165], v[164:165], 1.0 op_sel_hi:[1,0]
	v_add_f32_e32 v96, 1.0, v96
	v_rcp_f32_e32 v167, v96
	v_lshlrev_b32_e32 v96, 16, v163
	v_mul_f32_e32 v96, 0xbfb8aa3b, v96
	v_exp_f32_e32 v162, v96
	v_lshlrev_b32_e32 v96, 16, v161
	v_mul_f32_e32 v96, 0xbfb8aa3b, v96
	v_exp_f32_e32 v96, v96
	v_pk_mul_f32 v[164:165], v[166:167], v[164:165]
	v_add_f32_e32 v96, 1.0, v96
	v_rcp_f32_e32 v160, v96
	v_and_b32_e32 v96, 0xffff0000, v163
	v_mul_f32_e32 v96, 0xbfb8aa3b, v96
	v_exp_f32_e32 v163, v96
	v_and_b32_e32 v96, 0xffff0000, v161
	v_mul_f32_e32 v96, 0xbfb8aa3b, v96
	v_exp_f32_e32 v96, v96
	v_pk_add_f32 v[162:163], v[162:163], 1.0 op_sel_hi:[1,0]
	v_pk_mul_f32 v[104:105], v[104:105], v[164:165]
	v_add_f32_e32 v96, 1.0, v96
	v_rcp_f32_e32 v161, v96
	s_nop 0
	v_pk_mul_f32 v[160:161], v[160:161], v[162:163]
	s_nop 0
	v_pk_mul_f32 v[106:107], v[106:107], v[160:161]
	global_load_dwordx2 v[134:135], v[134:135], off offset:3808
	s_nop 0
	global_load_dwordx2 v[160:161], v[132:133], off offset:1760
	s_waitcnt vmcnt(0)
; __device__ __forceinline__ float bflo(unsigned u) { return __uint_as_float(u << 16); }
; __device__ __forceinline__ float bfhi(unsigned u) { return __uint_as_float(u & 0xffff0000u); }
; __device__ void gemm2_phase(const Params& P, int layer, char* smem) {
;     ...
;             const uint2 ra = *(const uint2*)(pp + (size_t)(m * 16) * INC + C_RA + n * 16);
;             const uint2 rb = *(const uint2*)(pp + (size_t)(m * 16) * INC + C_RB + n * 16);
;             acc[m][n][0] *= (1.f + __expf(-bflo(rb.x))) * __builtin_amdgcn_rcpf(1.f + __expf(-bflo(ra.x)));
;             acc[m][n][1] *= (1.f + __expf(-bfhi(rb.x))) * __builtin_amdgcn_rcpf(1.f + __expf(-bfhi(ra.x)));
;             acc[m][n][2] *= (1.f + __expf(-bflo(rb.y))) * __builtin_amdgcn_rcpf(1.f + __expf(-bflo(ra.y)));
;             acc[m][n][3] *= (1.f + __expf(-bfhi(rb.y))) * __builtin_amdgcn_rcpf(1.f + __expf(-bfhi(ra.y)));
;           }
;           if (m & 1) __builtin_amdgcn_sched_barrier(0);
	v_lshlrev_b32_e32 v96, 16, v160
	v_mul_f32_e32 v96, 0xbfb8aa3b, v96
	v_exp_f32_e32 v132, v96
	v_lshlrev_b32_e32 v96, 16, v134
	v_mul_f32_e32 v96, 0xbfb8aa3b, v96
	v_exp_f32_e32 v96, v96
	s_nop 0
	v_add_f32_e32 v96, 1.0, v96
	v_rcp_f32_e32 v162, v96
	v_and_b32_e32 v96, 0xffff0000, v160
	v_mul_f32_e32 v96, 0xbfb8aa3b, v96
	v_exp_f32_e32 v133, v96
	v_and_b32_e32 v96, 0xffff0000, v134
	v_mul_f32_e32 v96, 0xbfb8aa3b, v96
	v_exp_f32_e32 v96, v96
	v_pk_add_f32 v[132:133], v[132:133], 1.0 op_sel_hi:[1,0]
	v_add_f32_e32 v96, 1.0, v96
	v_rcp_f32_e32 v163, v96
	v_lshlrev_b32_e32 v96, 16, v161
	v_mul_f32_e32 v96, 0xbfb8aa3b, v96
	v_exp_f32_e32 v160, v96
	v_lshlrev_b32_e32 v96, 16, v135
	v_mul_f32_e32 v96, 0xbfb8aa3b, v96
	v_exp_f32_e32 v96, v96
	v_pk_mul_f32 v[132:133], v[162:163], v[132:133]
	v_add_f32_e32 v96, 1.0, v96
	v_rcp_f32_e32 v134, v96
	v_and_b32_e32 v96, 0xffff0000, v161
	v_mul_f32_e32 v96, 0xbfb8aa3b, v96
	v_exp_f32_e32 v161, v96
	v_and_b32_e32 v96, 0xffff0000, v135
	v_mul_f32_e32 v96, 0xbfb8aa3b, v96
	v_exp_f32_e32 v96, v96
	v_pk_add_f32 v[160:161], v[160:161], 1.0 op_sel_hi:[1,0]
	v_pk_mul_f32 v[92:93], v[92:93], v[132:133]
	v_add_f32_e32 v96, 1.0, v96
	v_rcp_f32_e32 v135, v96
	s_nop 0
	v_pk_mul_f32 v[134:135], v[134:135], v[160:161]
	s_nop 0
	v_pk_mul_f32 v[94:95], v[94:95], v[134:135]
	s_mov_b32 s22, 0x90000
	v_add_co_u32_e32 v132, vcc, s22, v98
	s_mov_b32 s22, 0xd7000
	s_nop 0
	v_addc_co_u32_e32 v133, vcc, 0, v99, vcc
	global_load_dwordx2 v[134:135], v[132:133], off offset:1664
	global_load_dwordx2 v[160:161], v[132:133], off offset:3712
	global_load_dwordx2 v[204:205], v[132:133], off offset:1696
	global_load_dwordx2 v[206:207], v[132:133], off offset:3744
	global_load_dwordx2 v[208:209], v[132:133], off offset:1728
	global_load_dwordx2 v[210:211], v[132:133], off offset:3776
	global_load_dwordx2 v[212:213], v[132:133], off offset:1760
	global_load_dwordx2 v[214:215], v[132:133], off offset:3808
	s_waitcnt vmcnt(0)
	v_lshlrev_b32_e32 v96, 16, v160
	v_mul_f32_e32 v96, 0xbfb8aa3b, v96
	v_exp_f32_e32 v162, v96
	v_lshlrev_b32_e32 v96, 16, v134
	v_mul_f32_e32 v96, 0xbfb8aa3b, v96
	v_exp_f32_e32 v96, v96
	s_nop 0
	v_add_f32_e32 v96, 1.0, v96
	v_rcp_f32_e32 v164, v96
	v_and_b32_e32 v96, 0xffff0000, v160
	v_mul_f32_e32 v96, 0xbfb8aa3b, v96
	v_exp_f32_e32 v163, v96
	v_and_b32_e32 v96, 0xffff0000, v134
	v_mul_f32_e32 v96, 0xbfb8aa3b, v96
	v_exp_f32_e32 v96, v96
	v_pk_add_f32 v[162:163], v[162:163], 1.0 op_sel_hi:[1,0]
	v_add_f32_e32 v96, 1.0, v96
	v_rcp_f32_e32 v165, v96
	v_lshlrev_b32_e32 v96, 16, v161
	v_mul_f32_e32 v96, 0xbfb8aa3b, v96
	v_exp_f32_e32 v160, v96
	v_lshlrev_b32_e32 v96, 16, v135
	v_mul_f32_e32 v96, 0xbfb8aa3b, v96
	v_exp_f32_e32 v96, v96
	v_pk_mul_f32 v[162:163], v[164:165], v[162:163]
	v_add_f32_e32 v96, 1.0, v96
	v_rcp_f32_e32 v134, v96
	v_and_b32_e32 v96, 0xffff0000, v161
	v_mul_f32_e32 v96, 0xbfb8aa3b, v96
	v_exp_f32_e32 v161, v96
	v_and_b32_e32 v96, 0xffff0000, v135
	v_mul_f32_e32 v96, 0xbfb8aa3b, v96
	v_exp_f32_e32 v96, v96
	v_pk_add_f32 v[160:161], v[160:161], 1.0 op_sel_hi:[1,0]
	v_pk_mul_f32 v[100:101], v[100:101], v[162:163]
	v_add_f32_e32 v96, 1.0, v96
	v_rcp_f32_e32 v135, v96
	s_nop 0
	v_pk_mul_f32 v[134:135], v[134:135], v[160:161]
	s_nop 0
	v_pk_mul_f32 v[102:103], v[102:103], v[134:135]
	v_mov_b32_e32 v134, v204
	v_mov_b32_e32 v135, v205
	v_mov_b32_e32 v160, v206
	v_mov_b32_e32 v161, v207
	s_waitcnt vmcnt(0)
	v_lshlrev_b32_e32 v96, 16, v160
	v_mul_f32_e32 v96, 0xbfb8aa3b, v96
	v_exp_f32_e32 v162, v96
	v_lshlrev_b32_e32 v96, 16, v134
	v_mul_f32_e32 v96, 0xbfb8aa3b, v96
	v_exp_f32_e32 v96, v96
	s_nop 0
	v_add_f32_e32 v96, 1.0, v96
	v_rcp_f32_e32 v164, v96
	v_and_b32_e32 v96, 0xffff0000, v160
	v_mul_f32_e32 v96, 0xbfb8aa3b, v96
	v_exp_f32_e32 v163, v96
	v_and_b32_e32 v96, 0xffff0000, v134
	v_mul_f32_e32 v96, 0xbfb8aa3b, v96
	v_exp_f32_e32 v96, v96
	v_pk_add_f32 v[162:163], v[162:163], 1.0 op_sel_hi:[1,0]
	v_add_f32_e32 v96, 1.0, v96
	v_rcp_f32_e32 v165, v96
	v_lshlrev_b32_e32 v96, 16, v161
	v_mul_f32_e32 v96, 0xbfb8aa3b, v96
	v_exp_f32_e32 v160, v96
	v_lshlrev_b32_e32 v96, 16, v135
	v_mul_f32_e32 v96, 0xbfb8aa3b, v96
	v_exp_f32_e32 v96, v96
	v_pk_mul_f32 v[162:163], v[164:165], v[162:163]
	v_add_f32_e32 v96, 1.0, v96
	v_rcp_f32_e32 v134, v96
	v_and_b32_e32 v96, 0xffff0000, v161
	v_mul_f32_e32 v96, 0xbfb8aa3b, v96
	v_exp_f32_e32 v161, v96
	v_and_b32_e32 v96, 0xffff0000, v135
	v_mul_f32_e32 v96, 0xbfb8aa3b, v96
	v_exp_f32_e32 v96, v96
	v_pk_add_f32 v[160:161], v[160:161], 1.0 op_sel_hi:[1,0]
	v_pk_mul_f32 v[88:89], v[88:89], v[162:163]
	v_add_f32_e32 v96, 1.0, v96
	v_rcp_f32_e32 v135, v96
	s_nop 0
	v_pk_mul_f32 v[134:135], v[134:135], v[160:161]
	s_nop 0
	v_pk_mul_f32 v[90:91], v[90:91], v[134:135]
	v_mov_b32_e32 v134, v208
	v_mov_b32_e32 v135, v209
	v_mov_b32_e32 v160, v210
	v_mov_b32_e32 v161, v211
	s_waitcnt vmcnt(0)
	v_lshlrev_b32_e32 v96, 16, v160
	v_mul_f32_e32 v96, 0xbfb8aa3b, v96
	v_exp_f32_e32 v162, v96
	v_lshlrev_b32_e32 v96, 16, v134
	v_mul_f32_e32 v96, 0xbfb8aa3b, v96
	v_exp_f32_e32 v96, v96
	s_nop 0
	v_add_f32_e32 v96, 1.0, v96
	v_rcp_f32_e32 v164, v96
	v_and_b32_e32 v96, 0xffff0000, v160
	v_mul_f32_e32 v96, 0xbfb8aa3b, v96
	v_exp_f32_e32 v163, v96
	v_and_b32_e32 v96, 0xffff0000, v134
	v_mul_f32_e32 v96, 0xbfb8aa3b, v96
	v_exp_f32_e32 v96, v96
	v_pk_add_f32 v[162:163], v[162:163], 1.0 op_sel_hi:[1,0]
	v_add_f32_e32 v96, 1.0, v96
	v_rcp_f32_e32 v165, v96
	v_lshlrev_b32_e32 v96, 16, v161
	v_mul_f32_e32 v96, 0xbfb8aa3b, v96
	v_exp_f32_e32 v160, v96
	v_lshlrev_b32_e32 v96, 16, v135
	v_mul_f32_e32 v96, 0xbfb8aa3b, v96
	v_exp_f32_e32 v96, v96
	v_pk_mul_f32 v[162:163], v[164:165], v[162:163]
	v_add_f32_e32 v96, 1.0, v96
	v_rcp_f32_e32 v134, v96
	v_and_b32_e32 v96, 0xffff0000, v161
	v_mul_f32_e32 v96, 0xbfb8aa3b, v96
	v_exp_f32_e32 v161, v96
	v_and_b32_e32 v96, 0xffff0000, v135
	v_mul_f32_e32 v96, 0xbfb8aa3b, v96
	v_exp_f32_e32 v96, v96
	v_pk_add_f32 v[160:161], v[160:161], 1.0 op_sel_hi:[1,0]
	v_pk_mul_f32 v[84:85], v[84:85], v[162:163]
	v_add_f32_e32 v96, 1.0, v96
	v_rcp_f32_e32 v135, v96
	s_nop 0
	v_pk_mul_f32 v[134:135], v[134:135], v[160:161]
	s_nop 0
	v_pk_mul_f32 v[86:87], v[86:87], v[134:135]
	v_mov_b32_e32 v134, v212
	v_mov_b32_e32 v135, v213
	s_nop 0
	v_mov_b32_e32 v132, v214
	v_mov_b32_e32 v133, v215
	s_waitcnt vmcnt(0)
; __device__ __forceinline__ float bflo(unsigned u) { return __uint_as_float(u << 16); }
; __device__ __forceinline__ float bfhi(unsigned u) { return __uint_as_float(u & 0xffff0000u); }
; __device__ void gemm2_phase(const Params& P, int layer, char* smem) {
;     ...
;             const uint2 ra = *(const uint2*)(pp + (size_t)(m * 16) * INC + C_RA + n * 16);
;             const uint2 rb = *(const uint2*)(pp + (size_t)(m * 16) * INC + C_RB + n * 16);
;             acc[m][n][0] *= (1.f + __expf(-bflo(rb.x))) * __builtin_amdgcn_rcpf(1.f + __expf(-bflo(ra.x)));
;             acc[m][n][1] *= (1.f + __expf(-bfhi(rb.x))) * __builtin_amdgcn_rcpf(1.f + __expf(-bfhi(ra.x)));
;             acc[m][n][2] *= (1.f + __expf(-bflo(rb.y))) * __builtin_amdgcn_rcpf(1.f + __expf(-bflo(ra.y)));
;             acc[m][n][3] *= (1.f + __expf(-bfhi(rb.y))) * __builtin_amdgcn_rcpf(1.f + __expf(-bfhi(ra.y)));
;           }
;           if (m & 1) __builtin_amdgcn_sched_barrier(0);
	v_lshlrev_b32_e32 v96, 16, v132
	v_mul_f32_e32 v96, 0xbfb8aa3b, v96
	v_exp_f32_e32 v160, v96
	v_lshlrev_b32_e32 v96, 16, v134
	v_mul_f32_e32 v96, 0xbfb8aa3b, v96
	v_exp_f32_e32 v96, v96
	s_nop 0
	v_add_f32_e32 v96, 1.0, v96
	v_rcp_f32_e32 v162, v96
	v_and_b32_e32 v96, 0xffff0000, v132
	v_mul_f32_e32 v96, 0xbfb8aa3b, v96
	v_exp_f32_e32 v161, v96
	v_and_b32_e32 v96, 0xffff0000, v134
	v_mul_f32_e32 v96, 0xbfb8aa3b, v96
	v_exp_f32_e32 v96, v96
	v_pk_add_f32 v[160:161], v[160:161], 1.0 op_sel_hi:[1,0]
	v_add_f32_e32 v96, 1.0, v96
	v_rcp_f32_e32 v163, v96
	v_lshlrev_b32_e32 v96, 16, v133
	v_mul_f32_e32 v96, 0xbfb8aa3b, v96
	v_exp_f32_e32 v132, v96
	v_lshlrev_b32_e32 v96, 16, v135
	v_mul_f32_e32 v96, 0xbfb8aa3b, v96
	v_exp_f32_e32 v96, v96
	v_pk_mul_f32 v[160:161], v[162:163], v[160:161]
	v_add_f32_e32 v96, 1.0, v96
	v_rcp_f32_e32 v134, v96
	v_and_b32_e32 v96, 0xffff0000, v133
	v_mul_f32_e32 v96, 0xbfb8aa3b, v96
	v_exp_f32_e32 v133, v96
	v_and_b32_e32 v96, 0xffff0000, v135
	v_mul_f32_e32 v96, 0xbfb8aa3b, v96
	v_exp_f32_e32 v96, v96
	v_pk_add_f32 v[132:133], v[132:133], 1.0 op_sel_hi:[1,0]
	v_pk_mul_f32 v[80:81], v[80:81], v[160:161]
	v_add_f32_e32 v96, 1.0, v96
	v_rcp_f32_e32 v135, v96
	s_nop 0
	v_pk_mul_f32 v[132:133], v[134:135], v[132:133]
	s_nop 0
	v_pk_mul_f32 v[82:83], v[82:83], v[132:133]
	v_add_co_u32_e32 v132, vcc, s22, v98
	s_mov_b32 s22, 0xd6000
	s_nop 0
	v_addc_co_u32_e32 v133, vcc, 0, v99, vcc
	v_add_co_u32_e32 v134, vcc, s22, v98
	global_load_dwordx2 v[160:161], v[132:133], off offset:1696
	s_nop 0
	v_addc_co_u32_e32 v135, vcc, 0, v99, vcc
	global_load_dwordx2 v[162:163], v[134:135], off offset:3744
	global_load_dwordx2 v[164:165], v[132:133], off offset:1664
	global_load_dwordx2 v[166:167], v[134:135], off offset:3712
	s_waitcnt vmcnt(1)
	v_lshlrev_b32_e32 v96, 16, v164
	v_mul_f32_e32 v96, 0xbfb8aa3b, v96
	v_exp_f32_e32 v168, v96
	s_waitcnt vmcnt(0)
	v_lshlrev_b32_e32 v96, 16, v166
	v_mul_f32_e32 v96, 0xbfb8aa3b, v96
	v_exp_f32_e32 v96, v96
	s_nop 0
	v_add_f32_e32 v96, 1.0, v96
	v_rcp_f32_e32 v170, v96
	v_and_b32_e32 v96, 0xffff0000, v164
	v_mul_f32_e32 v96, 0xbfb8aa3b, v96
	v_exp_f32_e32 v169, v96
	v_and_b32_e32 v96, 0xffff0000, v166
	v_mul_f32_e32 v96, 0xbfb8aa3b, v96
	v_exp_f32_e32 v96, v96
	v_pk_add_f32 v[168:169], v[168:169], 1.0 op_sel_hi:[1,0]
	v_add_f32_e32 v96, 1.0, v96
	v_rcp_f32_e32 v171, v96
	v_lshlrev_b32_e32 v96, 16, v165
	v_mul_f32_e32 v96, 0xbfb8aa3b, v96
	v_exp_f32_e32 v164, v96
	v_lshlrev_b32_e32 v96, 16, v167
	v_mul_f32_e32 v96, 0xbfb8aa3b, v96
	v_exp_f32_e32 v96, v96
	v_pk_mul_f32 v[168:169], v[168:169], v[170:171]
	v_add_f32_e32 v96, 1.0, v96
	v_rcp_f32_e32 v166, v96
	v_and_b32_e32 v96, 0xffff0000, v165
	v_mul_f32_e32 v96, 0xbfb8aa3b, v96
	v_exp_f32_e32 v165, v96
	v_and_b32_e32 v96, 0xffff0000, v167
	v_mul_f32_e32 v96, 0xbfb8aa3b, v96
	v_exp_f32_e32 v96, v96
	v_pk_add_f32 v[164:165], v[164:165], 1.0 op_sel_hi:[1,0]
	v_pk_mul_f32 v[76:77], v[76:77], v[168:169]
	v_add_f32_e32 v96, 1.0, v96
	v_rcp_f32_e32 v167, v96
	v_lshlrev_b32_e32 v96, 16, v160
	v_mul_f32_e32 v96, 0xbfb8aa3b, v96
	v_pk_mul_f32 v[164:165], v[164:165], v[166:167]
	s_nop 0
	v_pk_mul_f32 v[78:79], v[78:79], v[164:165]
	v_exp_f32_e32 v164, v96
	v_lshlrev_b32_e32 v96, 16, v162
	v_mul_f32_e32 v96, 0xbfb8aa3b, v96
	v_exp_f32_e32 v96, v96
	s_nop 0
	v_add_f32_e32 v96, 1.0, v96
	v_rcp_f32_e32 v166, v96
	v_and_b32_e32 v96, 0xffff0000, v160
	v_mul_f32_e32 v96, 0xbfb8aa3b, v96
	v_exp_f32_e32 v165, v96
	v_and_b32_e32 v96, 0xffff0000, v162
	v_mul_f32_e32 v96, 0xbfb8aa3b, v96
	v_exp_f32_e32 v96, v96
	v_pk_add_f32 v[164:165], v[164:165], 1.0 op_sel_hi:[1,0]
	v_add_f32_e32 v96, 1.0, v96
	v_rcp_f32_e32 v167, v96
	v_lshlrev_b32_e32 v96, 16, v161
	v_mul_f32_e32 v96, 0xbfb8aa3b, v96
	v_exp_f32_e32 v160, v96
	v_lshlrev_b32_e32 v96, 16, v163
	v_mul_f32_e32 v96, 0xbfb8aa3b, v96
	v_exp_f32_e32 v96, v96
	v_pk_mul_f32 v[164:165], v[164:165], v[166:167]
	v_add_f32_e32 v96, 1.0, v96
	v_rcp_f32_e32 v162, v96
	v_and_b32_e32 v96, 0xffff0000, v161
	v_mul_f32_e32 v96, 0xbfb8aa3b, v96
	v_exp_f32_e32 v161, v96
	v_and_b32_e32 v96, 0xffff0000, v163
	v_mul_f32_e32 v96, 0xbfb8aa3b, v96
	v_exp_f32_e32 v96, v96
	v_pk_add_f32 v[160:161], v[160:161], 1.0 op_sel_hi:[1,0]
	v_pk_mul_f32 v[72:73], v[72:73], v[164:165]
	v_add_f32_e32 v96, 1.0, v96
	v_rcp_f32_e32 v163, v96
	s_nop 0
	v_pk_mul_f32 v[160:161], v[160:161], v[162:163]
	s_nop 0
	v_pk_mul_f32 v[74:75], v[74:75], v[160:161]
	global_load_dwordx2 v[160:161], v[134:135], off offset:3776
	global_load_dwordx2 v[162:163], v[132:133], off offset:1728
	s_waitcnt vmcnt(0)
	v_lshlrev_b32_e32 v96, 16, v162
	v_mul_f32_e32 v96, 0xbfb8aa3b, v96
	v_exp_f32_e32 v164, v96
	v_lshlrev_b32_e32 v96, 16, v160
	v_mul_f32_e32 v96, 0xbfb8aa3b, v96
	v_exp_f32_e32 v96, v96
	s_nop 0
	v_add_f32_e32 v96, 1.0, v96
	v_rcp_f32_e32 v166, v96
	v_and_b32_e32 v96, 0xffff0000, v162
	v_mul_f32_e32 v96, 0xbfb8aa3b, v96
	v_exp_f32_e32 v165, v96
	v_and_b32_e32 v96, 0xffff0000, v160
	v_mul_f32_e32 v96, 0xbfb8aa3b, v96
	v_exp_f32_e32 v96, v96
	v_pk_add_f32 v[164:165], v[164:165], 1.0 op_sel_hi:[1,0]
	v_add_f32_e32 v96, 1.0, v96
	v_rcp_f32_e32 v167, v96
	v_lshlrev_b32_e32 v96, 16, v163
	v_mul_f32_e32 v96, 0xbfb8aa3b, v96
	v_exp_f32_e32 v162, v96
	v_lshlrev_b32_e32 v96, 16, v161
	v_mul_f32_e32 v96, 0xbfb8aa3b, v96
	v_exp_f32_e32 v96, v96
	v_pk_mul_f32 v[164:165], v[166:167], v[164:165]
	v_add_f32_e32 v96, 1.0, v96
	v_rcp_f32_e32 v160, v96
	v_and_b32_e32 v96, 0xffff0000, v163
	v_mul_f32_e32 v96, 0xbfb8aa3b, v96
	v_exp_f32_e32 v163, v96
	v_and_b32_e32 v96, 0xffff0000, v161
	v_mul_f32_e32 v96, 0xbfb8aa3b, v96
	v_exp_f32_e32 v96, v96
	v_pk_add_f32 v[162:163], v[162:163], 1.0 op_sel_hi:[1,0]
	v_pk_mul_f32 v[68:69], v[68:69], v[164:165]
	v_add_f32_e32 v96, 1.0, v96
	v_rcp_f32_e32 v161, v96
	s_nop 0
	v_pk_mul_f32 v[160:161], v[160:161], v[162:163]
	s_nop 0
	v_pk_mul_f32 v[70:71], v[70:71], v[160:161]
	global_load_dwordx2 v[134:135], v[134:135], off offset:3808
	s_nop 0
	global_load_dwordx2 v[160:161], v[132:133], off offset:1760
	s_waitcnt vmcnt(0)
; __device__ __forceinline__ float bflo(unsigned u) { return __uint_as_float(u << 16); }
; __device__ __forceinline__ float bfhi(unsigned u) { return __uint_as_float(u & 0xffff0000u); }
; __device__ void gemm2_phase(const Params& P, int layer, char* smem) {
;     ...
;             const uint2 ra = *(const uint2*)(pp + (size_t)(m * 16) * INC + C_RA + n * 16);
;             const uint2 rb = *(const uint2*)(pp + (size_t)(m * 16) * INC + C_RB + n * 16);
;             acc[m][n][0] *= (1.f + __expf(-bflo(rb.x))) * __builtin_amdgcn_rcpf(1.f + __expf(-bflo(ra.x)));
;             acc[m][n][1] *= (1.f + __expf(-bfhi(rb.x))) * __builtin_amdgcn_rcpf(1.f + __expf(-bfhi(ra.x)));
;             acc[m][n][2] *= (1.f + __expf(-bflo(rb.y))) * __builtin_amdgcn_rcpf(1.f + __expf(-bflo(ra.y)));
;             acc[m][n][3] *= (1.f + __expf(-bfhi(rb.y))) * __builtin_amdgcn_rcpf(1.f + __expf(-bfhi(ra.y)));
;           }
;           if (m & 1) __builtin_amdgcn_sched_barrier(0);
	v_lshlrev_b32_e32 v96, 16, v160
	v_mul_f32_e32 v96, 0xbfb8aa3b, v96
	v_exp_f32_e32 v132, v96
	v_lshlrev_b32_e32 v96, 16, v134
	v_mul_f32_e32 v96, 0xbfb8aa3b, v96
	v_exp_f32_e32 v96, v96
	s_nop 0
	v_add_f32_e32 v96, 1.0, v96
	v_rcp_f32_e32 v162, v96
	v_and_b32_e32 v96, 0xffff0000, v160
	v_mul_f32_e32 v96, 0xbfb8aa3b, v96
	v_exp_f32_e32 v133, v96
	v_and_b32_e32 v96, 0xffff0000, v134
	v_mul_f32_e32 v96, 0xbfb8aa3b, v96
	v_exp_f32_e32 v96, v96
	v_pk_add_f32 v[132:133], v[132:133], 1.0 op_sel_hi:[1,0]
	v_add_f32_e32 v96, 1.0, v96
	v_rcp_f32_e32 v163, v96
	v_lshlrev_b32_e32 v96, 16, v161
	v_mul_f32_e32 v96, 0xbfb8aa3b, v96
	v_exp_f32_e32 v160, v96
	v_lshlrev_b32_e32 v96, 16, v135
	v_mul_f32_e32 v96, 0xbfb8aa3b, v96
	v_exp_f32_e32 v96, v96
	v_pk_mul_f32 v[132:133], v[162:163], v[132:133]
	v_add_f32_e32 v96, 1.0, v96
	v_rcp_f32_e32 v134, v96
	v_and_b32_e32 v96, 0xffff0000, v161
	v_mul_f32_e32 v96, 0xbfb8aa3b, v96
	v_exp_f32_e32 v161, v96
	v_and_b32_e32 v96, 0xffff0000, v135
	v_mul_f32_e32 v96, 0xbfb8aa3b, v96
	v_exp_f32_e32 v96, v96
	v_pk_add_f32 v[160:161], v[160:161], 1.0 op_sel_hi:[1,0]
	v_pk_mul_f32 v[60:61], v[60:61], v[132:133]
	v_add_f32_e32 v96, 1.0, v96
	v_rcp_f32_e32 v135, v96
	s_nop 0
	v_pk_mul_f32 v[134:135], v[134:135], v[160:161]
	s_nop 0
	v_pk_mul_f32 v[62:63], v[62:63], v[134:135]
	s_mov_b32 s22, 0x11d000
	v_add_co_u32_e32 v132, vcc, s22, v98
	s_mov_b32 s22, 0x164000
	s_nop 0
	v_addc_co_u32_e32 v133, vcc, 0, v99, vcc
	global_load_dwordx2 v[134:135], v[132:133], off offset:1664
	global_load_dwordx2 v[160:161], v[132:133], off offset:3712
	global_load_dwordx2 v[204:205], v[132:133], off offset:1696
	global_load_dwordx2 v[206:207], v[132:133], off offset:3744
	global_load_dwordx2 v[208:209], v[132:133], off offset:1728
	global_load_dwordx2 v[210:211], v[132:133], off offset:3776
	global_load_dwordx2 v[212:213], v[132:133], off offset:1760
	global_load_dwordx2 v[214:215], v[132:133], off offset:3808
	s_waitcnt vmcnt(0)
	v_lshlrev_b32_e32 v96, 16, v160
	v_mul_f32_e32 v96, 0xbfb8aa3b, v96
	v_exp_f32_e32 v162, v96
	v_lshlrev_b32_e32 v96, 16, v134
	v_mul_f32_e32 v96, 0xbfb8aa3b, v96
	v_exp_f32_e32 v96, v96
	s_nop 0
	v_add_f32_e32 v96, 1.0, v96
	v_rcp_f32_e32 v164, v96
	v_and_b32_e32 v96, 0xffff0000, v160
	v_mul_f32_e32 v96, 0xbfb8aa3b, v96
	v_exp_f32_e32 v163, v96
	v_and_b32_e32 v96, 0xffff0000, v134
	v_mul_f32_e32 v96, 0xbfb8aa3b, v96
	v_exp_f32_e32 v96, v96
	v_pk_add_f32 v[162:163], v[162:163], 1.0 op_sel_hi:[1,0]
	v_add_f32_e32 v96, 1.0, v96
	v_rcp_f32_e32 v165, v96
	v_lshlrev_b32_e32 v96, 16, v161
	v_mul_f32_e32 v96, 0xbfb8aa3b, v96
	v_exp_f32_e32 v160, v96
	v_lshlrev_b32_e32 v96, 16, v135
	v_mul_f32_e32 v96, 0xbfb8aa3b, v96
	v_exp_f32_e32 v96, v96
	v_pk_mul_f32 v[162:163], v[164:165], v[162:163]
	v_add_f32_e32 v96, 1.0, v96
	v_rcp_f32_e32 v134, v96
	v_and_b32_e32 v96, 0xffff0000, v161
	v_mul_f32_e32 v96, 0xbfb8aa3b, v96
	v_exp_f32_e32 v161, v96
	v_and_b32_e32 v96, 0xffff0000, v135
	v_mul_f32_e32 v96, 0xbfb8aa3b, v96
	v_exp_f32_e32 v96, v96
	v_pk_add_f32 v[160:161], v[160:161], 1.0 op_sel_hi:[1,0]
	v_pk_mul_f32 v[64:65], v[64:65], v[162:163]
	v_add_f32_e32 v96, 1.0, v96
	v_rcp_f32_e32 v135, v96
	s_nop 0
	v_pk_mul_f32 v[134:135], v[134:135], v[160:161]
	s_nop 0
	v_pk_mul_f32 v[66:67], v[66:67], v[134:135]
	v_mov_b32_e32 v134, v204
	v_mov_b32_e32 v135, v205
	v_mov_b32_e32 v160, v206
	v_mov_b32_e32 v161, v207
	s_waitcnt vmcnt(0)
	v_lshlrev_b32_e32 v96, 16, v160
	v_mul_f32_e32 v96, 0xbfb8aa3b, v96
	v_exp_f32_e32 v162, v96
	v_lshlrev_b32_e32 v96, 16, v134
	v_mul_f32_e32 v96, 0xbfb8aa3b, v96
	v_exp_f32_e32 v96, v96
	s_nop 0
	v_add_f32_e32 v96, 1.0, v96
	v_rcp_f32_e32 v164, v96
	v_and_b32_e32 v96, 0xffff0000, v160
	v_mul_f32_e32 v96, 0xbfb8aa3b, v96
	v_exp_f32_e32 v163, v96
	v_and_b32_e32 v96, 0xffff0000, v134
	v_mul_f32_e32 v96, 0xbfb8aa3b, v96
	v_exp_f32_e32 v96, v96
	v_pk_add_f32 v[162:163], v[162:163], 1.0 op_sel_hi:[1,0]
	v_add_f32_e32 v96, 1.0, v96
	v_rcp_f32_e32 v165, v96
	v_lshlrev_b32_e32 v96, 16, v161
	v_mul_f32_e32 v96, 0xbfb8aa3b, v96
	v_exp_f32_e32 v160, v96
	v_lshlrev_b32_e32 v96, 16, v135
	v_mul_f32_e32 v96, 0xbfb8aa3b, v96
	v_exp_f32_e32 v96, v96
	v_pk_mul_f32 v[162:163], v[164:165], v[162:163]
	v_add_f32_e32 v96, 1.0, v96
	v_rcp_f32_e32 v134, v96
	v_and_b32_e32 v96, 0xffff0000, v161
	v_mul_f32_e32 v96, 0xbfb8aa3b, v96
	v_exp_f32_e32 v161, v96
	v_and_b32_e32 v96, 0xffff0000, v135
	v_mul_f32_e32 v96, 0xbfb8aa3b, v96
	v_exp_f32_e32 v96, v96
	v_pk_add_f32 v[160:161], v[160:161], 1.0 op_sel_hi:[1,0]
	v_pk_mul_f32 v[56:57], v[56:57], v[162:163]
	v_add_f32_e32 v96, 1.0, v96
	v_rcp_f32_e32 v135, v96
	s_nop 0
	v_pk_mul_f32 v[134:135], v[134:135], v[160:161]
	s_nop 0
	v_pk_mul_f32 v[58:59], v[58:59], v[134:135]
	v_mov_b32_e32 v134, v208
	v_mov_b32_e32 v135, v209
	v_mov_b32_e32 v160, v210
	v_mov_b32_e32 v161, v211
	s_waitcnt vmcnt(0)
	v_lshlrev_b32_e32 v96, 16, v160
	v_mul_f32_e32 v96, 0xbfb8aa3b, v96
	v_exp_f32_e32 v162, v96
	v_lshlrev_b32_e32 v96, 16, v134
	v_mul_f32_e32 v96, 0xbfb8aa3b, v96
	v_exp_f32_e32 v96, v96
	s_nop 0
	v_add_f32_e32 v96, 1.0, v96
	v_rcp_f32_e32 v164, v96
	v_and_b32_e32 v96, 0xffff0000, v160
	v_mul_f32_e32 v96, 0xbfb8aa3b, v96
	v_exp_f32_e32 v163, v96
	v_and_b32_e32 v96, 0xffff0000, v134
	v_mul_f32_e32 v96, 0xbfb8aa3b, v96
	v_exp_f32_e32 v96, v96
	v_pk_add_f32 v[162:163], v[162:163], 1.0 op_sel_hi:[1,0]
	v_add_f32_e32 v96, 1.0, v96
	v_rcp_f32_e32 v165, v96
	v_lshlrev_b32_e32 v96, 16, v161
	v_mul_f32_e32 v96, 0xbfb8aa3b, v96
	v_exp_f32_e32 v160, v96
	v_lshlrev_b32_e32 v96, 16, v135
	v_mul_f32_e32 v96, 0xbfb8aa3b, v96
	v_exp_f32_e32 v96, v96
	v_pk_mul_f32 v[162:163], v[164:165], v[162:163]
	v_add_f32_e32 v96, 1.0, v96
	v_rcp_f32_e32 v134, v96
	v_and_b32_e32 v96, 0xffff0000, v161
	v_mul_f32_e32 v96, 0xbfb8aa3b, v96
	v_exp_f32_e32 v161, v96
	v_and_b32_e32 v96, 0xffff0000, v135
	v_mul_f32_e32 v96, 0xbfb8aa3b, v96
	v_exp_f32_e32 v96, v96
	v_pk_add_f32 v[160:161], v[160:161], 1.0 op_sel_hi:[1,0]
	v_pk_mul_f32 v[52:53], v[52:53], v[162:163]
	v_add_f32_e32 v96, 1.0, v96
	v_rcp_f32_e32 v135, v96
	s_nop 0
	v_pk_mul_f32 v[134:135], v[134:135], v[160:161]
	s_nop 0
	v_pk_mul_f32 v[54:55], v[54:55], v[134:135]
	v_mov_b32_e32 v134, v212
	v_mov_b32_e32 v135, v213
	s_nop 0
	v_mov_b32_e32 v132, v214
	v_mov_b32_e32 v133, v215
	s_waitcnt vmcnt(0)
; __device__ __forceinline__ float bflo(unsigned u) { return __uint_as_float(u << 16); }
; __device__ __forceinline__ float bfhi(unsigned u) { return __uint_as_float(u & 0xffff0000u); }
; __device__ void gemm2_phase(const Params& P, int layer, char* smem) {
;     ...
;             const uint2 ra = *(const uint2*)(pp + (size_t)(m * 16) * INC + C_RA + n * 16);
;             const uint2 rb = *(const uint2*)(pp + (size_t)(m * 16) * INC + C_RB + n * 16);
;             acc[m][n][0] *= (1.f + __expf(-bflo(rb.x))) * __builtin_amdgcn_rcpf(1.f + __expf(-bflo(ra.x)));
;             acc[m][n][1] *= (1.f + __expf(-bfhi(rb.x))) * __builtin_amdgcn_rcpf(1.f + __expf(-bfhi(ra.x)));
;             acc[m][n][2] *= (1.f + __expf(-bflo(rb.y))) * __builtin_amdgcn_rcpf(1.f + __expf(-bflo(ra.y)));
;             acc[m][n][3] *= (1.f + __expf(-bfhi(rb.y))) * __builtin_amdgcn_rcpf(1.f + __expf(-bfhi(ra.y)));
;           }
;           if (m & 1) __builtin_amdgcn_sched_barrier(0);
	v_lshlrev_b32_e32 v96, 16, v132
	v_mul_f32_e32 v96, 0xbfb8aa3b, v96
	v_exp_f32_e32 v160, v96
	v_lshlrev_b32_e32 v96, 16, v134
	v_mul_f32_e32 v96, 0xbfb8aa3b, v96
	v_exp_f32_e32 v96, v96
	s_nop 0
	v_add_f32_e32 v96, 1.0, v96
	v_rcp_f32_e32 v162, v96
	v_and_b32_e32 v96, 0xffff0000, v132
	v_mul_f32_e32 v96, 0xbfb8aa3b, v96
	v_exp_f32_e32 v161, v96
	v_and_b32_e32 v96, 0xffff0000, v134
	v_mul_f32_e32 v96, 0xbfb8aa3b, v96
	v_exp_f32_e32 v96, v96
	v_pk_add_f32 v[160:161], v[160:161], 1.0 op_sel_hi:[1,0]
	v_add_f32_e32 v96, 1.0, v96
	v_rcp_f32_e32 v163, v96
	v_lshlrev_b32_e32 v96, 16, v133
	v_mul_f32_e32 v96, 0xbfb8aa3b, v96
	v_exp_f32_e32 v132, v96
	v_lshlrev_b32_e32 v96, 16, v135
	v_mul_f32_e32 v96, 0xbfb8aa3b, v96
	v_exp_f32_e32 v96, v96
	v_pk_mul_f32 v[160:161], v[162:163], v[160:161]
	v_add_f32_e32 v96, 1.0, v96
	v_rcp_f32_e32 v134, v96
	v_and_b32_e32 v96, 0xffff0000, v133
	v_mul_f32_e32 v96, 0xbfb8aa3b, v96
	v_exp_f32_e32 v133, v96
	v_and_b32_e32 v96, 0xffff0000, v135
	v_mul_f32_e32 v96, 0xbfb8aa3b, v96
	v_exp_f32_e32 v96, v96
	v_pk_add_f32 v[132:133], v[132:133], 1.0 op_sel_hi:[1,0]
	v_pk_mul_f32 v[48:49], v[48:49], v[160:161]
	v_add_f32_e32 v96, 1.0, v96
	v_rcp_f32_e32 v135, v96
	s_nop 0
	v_pk_mul_f32 v[132:133], v[134:135], v[132:133]
	s_nop 0
	v_pk_mul_f32 v[50:51], v[50:51], v[132:133]
	v_add_co_u32_e32 v132, vcc, s22, v98
	s_mov_b32 s22, 0x163000
	s_nop 0
	v_addc_co_u32_e32 v133, vcc, 0, v99, vcc
	v_add_co_u32_e32 v134, vcc, s22, v98
	global_load_dwordx2 v[160:161], v[132:133], off offset:1696
	s_nop 0
	v_addc_co_u32_e32 v135, vcc, 0, v99, vcc
	global_load_dwordx2 v[162:163], v[134:135], off offset:3744
	global_load_dwordx2 v[164:165], v[132:133], off offset:1664
	global_load_dwordx2 v[166:167], v[134:135], off offset:3712
	s_waitcnt vmcnt(1)
	v_lshlrev_b32_e32 v96, 16, v164
	v_mul_f32_e32 v96, 0xbfb8aa3b, v96
	v_exp_f32_e32 v168, v96
	s_waitcnt vmcnt(0)
	v_lshlrev_b32_e32 v96, 16, v166
	v_mul_f32_e32 v96, 0xbfb8aa3b, v96
	v_exp_f32_e32 v96, v96
	s_nop 0
	v_add_f32_e32 v96, 1.0, v96
	v_rcp_f32_e32 v170, v96
	v_and_b32_e32 v96, 0xffff0000, v164
	v_mul_f32_e32 v96, 0xbfb8aa3b, v96
	v_exp_f32_e32 v169, v96
	v_and_b32_e32 v96, 0xffff0000, v166
	v_mul_f32_e32 v96, 0xbfb8aa3b, v96
	v_exp_f32_e32 v96, v96
	v_pk_add_f32 v[168:169], v[168:169], 1.0 op_sel_hi:[1,0]
	v_add_f32_e32 v96, 1.0, v96
	v_rcp_f32_e32 v171, v96
	v_lshlrev_b32_e32 v96, 16, v165
	v_mul_f32_e32 v96, 0xbfb8aa3b, v96
	v_exp_f32_e32 v164, v96
	v_lshlrev_b32_e32 v96, 16, v167
	v_mul_f32_e32 v96, 0xbfb8aa3b, v96
	v_exp_f32_e32 v96, v96
	v_pk_mul_f32 v[168:169], v[168:169], v[170:171]
	v_add_f32_e32 v96, 1.0, v96
	v_rcp_f32_e32 v166, v96
	v_and_b32_e32 v96, 0xffff0000, v165
	v_mul_f32_e32 v96, 0xbfb8aa3b, v96
	v_exp_f32_e32 v165, v96
	v_and_b32_e32 v96, 0xffff0000, v167
	v_mul_f32_e32 v96, 0xbfb8aa3b, v96
	v_exp_f32_e32 v96, v96
	v_pk_add_f32 v[164:165], v[164:165], 1.0 op_sel_hi:[1,0]
	v_pk_mul_f32 v[44:45], v[44:45], v[168:169]
	v_add_f32_e32 v96, 1.0, v96
	v_rcp_f32_e32 v167, v96
	v_lshlrev_b32_e32 v96, 16, v160
	v_mul_f32_e32 v96, 0xbfb8aa3b, v96
	v_pk_mul_f32 v[164:165], v[164:165], v[166:167]
	s_nop 0
	v_pk_mul_f32 v[46:47], v[46:47], v[164:165]
	v_exp_f32_e32 v164, v96
	v_lshlrev_b32_e32 v96, 16, v162
	v_mul_f32_e32 v96, 0xbfb8aa3b, v96
	v_exp_f32_e32 v96, v96
	s_nop 0
	v_add_f32_e32 v96, 1.0, v96
	v_rcp_f32_e32 v166, v96
	v_and_b32_e32 v96, 0xffff0000, v160
	v_mul_f32_e32 v96, 0xbfb8aa3b, v96
	v_exp_f32_e32 v165, v96
	v_and_b32_e32 v96, 0xffff0000, v162
	v_mul_f32_e32 v96, 0xbfb8aa3b, v96
	v_exp_f32_e32 v96, v96
	v_pk_add_f32 v[164:165], v[164:165], 1.0 op_sel_hi:[1,0]
	v_add_f32_e32 v96, 1.0, v96
	v_rcp_f32_e32 v167, v96
	v_lshlrev_b32_e32 v96, 16, v161
	v_mul_f32_e32 v96, 0xbfb8aa3b, v96
	v_exp_f32_e32 v160, v96
	v_lshlrev_b32_e32 v96, 16, v163
	v_mul_f32_e32 v96, 0xbfb8aa3b, v96
	v_exp_f32_e32 v96, v96
	v_pk_mul_f32 v[164:165], v[164:165], v[166:167]
	v_add_f32_e32 v96, 1.0, v96
	v_rcp_f32_e32 v162, v96
	v_and_b32_e32 v96, 0xffff0000, v161
	v_mul_f32_e32 v96, 0xbfb8aa3b, v96
	v_exp_f32_e32 v161, v96
	v_and_b32_e32 v96, 0xffff0000, v163
	v_mul_f32_e32 v96, 0xbfb8aa3b, v96
	v_exp_f32_e32 v96, v96
	v_pk_add_f32 v[160:161], v[160:161], 1.0 op_sel_hi:[1,0]
	v_pk_mul_f32 v[40:41], v[40:41], v[164:165]
	v_add_f32_e32 v96, 1.0, v96
	v_rcp_f32_e32 v163, v96
	s_nop 0
	v_pk_mul_f32 v[160:161], v[160:161], v[162:163]
	s_nop 0
	v_pk_mul_f32 v[42:43], v[42:43], v[160:161]
	global_load_dwordx2 v[160:161], v[134:135], off offset:3776
	global_load_dwordx2 v[162:163], v[132:133], off offset:1728
	s_waitcnt vmcnt(0)
	v_lshlrev_b32_e32 v96, 16, v162
	v_mul_f32_e32 v96, 0xbfb8aa3b, v96
	v_exp_f32_e32 v164, v96
	v_lshlrev_b32_e32 v96, 16, v160
	v_mul_f32_e32 v96, 0xbfb8aa3b, v96
	v_exp_f32_e32 v96, v96
	s_nop 0
	v_add_f32_e32 v96, 1.0, v96
	v_rcp_f32_e32 v166, v96
	v_and_b32_e32 v96, 0xffff0000, v162
	v_mul_f32_e32 v96, 0xbfb8aa3b, v96
	v_exp_f32_e32 v165, v96
	v_and_b32_e32 v96, 0xffff0000, v160
	v_mul_f32_e32 v96, 0xbfb8aa3b, v96
	v_exp_f32_e32 v96, v96
	v_pk_add_f32 v[164:165], v[164:165], 1.0 op_sel_hi:[1,0]
	v_add_f32_e32 v96, 1.0, v96
	v_rcp_f32_e32 v167, v96
	v_lshlrev_b32_e32 v96, 16, v163
	v_mul_f32_e32 v96, 0xbfb8aa3b, v96
	v_exp_f32_e32 v162, v96
	v_lshlrev_b32_e32 v96, 16, v161
	v_mul_f32_e32 v96, 0xbfb8aa3b, v96
	v_exp_f32_e32 v96, v96
	v_pk_mul_f32 v[164:165], v[166:167], v[164:165]
	v_add_f32_e32 v96, 1.0, v96
	v_rcp_f32_e32 v160, v96
	v_and_b32_e32 v96, 0xffff0000, v163
	v_mul_f32_e32 v96, 0xbfb8aa3b, v96
	v_exp_f32_e32 v163, v96
	v_and_b32_e32 v96, 0xffff0000, v161
	v_mul_f32_e32 v96, 0xbfb8aa3b, v96
	v_exp_f32_e32 v96, v96
	v_pk_add_f32 v[162:163], v[162:163], 1.0 op_sel_hi:[1,0]
	v_pk_mul_f32 v[36:37], v[36:37], v[164:165]
	v_add_f32_e32 v96, 1.0, v96
	v_rcp_f32_e32 v161, v96
	s_nop 0
	v_pk_mul_f32 v[160:161], v[160:161], v[162:163]
	s_nop 0
	v_pk_mul_f32 v[38:39], v[38:39], v[160:161]
	global_load_dwordx2 v[134:135], v[134:135], off offset:3808
	s_nop 0
	global_load_dwordx2 v[160:161], v[132:133], off offset:1760
	s_waitcnt vmcnt(0)
; __device__ __forceinline__ float bflo(unsigned u) { return __uint_as_float(u << 16); }
; __device__ __forceinline__ float bfhi(unsigned u) { return __uint_as_float(u & 0xffff0000u); }
; __device__ void gemm2_phase(const Params& P, int layer, char* smem) {
;     ...
;             const uint2 ra = *(const uint2*)(pp + (size_t)(m * 16) * INC + C_RA + n * 16);
;             const uint2 rb = *(const uint2*)(pp + (size_t)(m * 16) * INC + C_RB + n * 16);
;             acc[m][n][0] *= (1.f + __expf(-bflo(rb.x))) * __builtin_amdgcn_rcpf(1.f + __expf(-bflo(ra.x)));
;             acc[m][n][1] *= (1.f + __expf(-bfhi(rb.x))) * __builtin_amdgcn_rcpf(1.f + __expf(-bfhi(ra.x)));
;             acc[m][n][2] *= (1.f + __expf(-bflo(rb.y))) * __builtin_amdgcn_rcpf(1.f + __expf(-bflo(ra.y)));
;             acc[m][n][3] *= (1.f + __expf(-bfhi(rb.y))) * __builtin_amdgcn_rcpf(1.f + __expf(-bfhi(ra.y)));
;           }
;           if (m & 1) __builtin_amdgcn_sched_barrier(0);
	v_lshlrev_b32_e32 v96, 16, v160
	v_mul_f32_e32 v96, 0xbfb8aa3b, v96
	v_exp_f32_e32 v132, v96
	v_lshlrev_b32_e32 v96, 16, v134
	v_mul_f32_e32 v96, 0xbfb8aa3b, v96
	v_exp_f32_e32 v96, v96
	s_nop 0
	v_add_f32_e32 v96, 1.0, v96
	v_rcp_f32_e32 v162, v96
	v_and_b32_e32 v96, 0xffff0000, v160
	v_mul_f32_e32 v96, 0xbfb8aa3b, v96
	v_exp_f32_e32 v133, v96
	v_and_b32_e32 v96, 0xffff0000, v134
	v_mul_f32_e32 v96, 0xbfb8aa3b, v96
	v_exp_f32_e32 v96, v96
	v_pk_add_f32 v[132:133], v[132:133], 1.0 op_sel_hi:[1,0]
	v_add_f32_e32 v96, 1.0, v96
	v_rcp_f32_e32 v163, v96
	v_lshlrev_b32_e32 v96, 16, v161
	v_mul_f32_e32 v96, 0xbfb8aa3b, v96
	v_exp_f32_e32 v160, v96
	v_lshlrev_b32_e32 v96, 16, v135
	v_mul_f32_e32 v96, 0xbfb8aa3b, v96
	v_exp_f32_e32 v96, v96
	v_pk_mul_f32 v[132:133], v[162:163], v[132:133]
	v_add_f32_e32 v96, 1.0, v96
	v_rcp_f32_e32 v134, v96
	v_and_b32_e32 v96, 0xffff0000, v161
	v_mul_f32_e32 v96, 0xbfb8aa3b, v96
	v_exp_f32_e32 v161, v96
	v_and_b32_e32 v96, 0xffff0000, v135
	v_mul_f32_e32 v96, 0xbfb8aa3b, v96
	v_exp_f32_e32 v96, v96
	v_pk_add_f32 v[160:161], v[160:161], 1.0 op_sel_hi:[1,0]
	v_pk_mul_f32 v[28:29], v[28:29], v[132:133]
	v_add_f32_e32 v96, 1.0, v96
	v_rcp_f32_e32 v135, v96
	s_nop 0
	v_pk_mul_f32 v[134:135], v[134:135], v[160:161]
	s_nop 0
	v_pk_mul_f32 v[30:31], v[30:31], v[134:135]
	s_mov_b32 s22, 0x1aa000
	v_add_co_u32_e32 v132, vcc, s22, v98
	s_mov_b32 s22, 0x1f1000
	s_nop 0
	v_addc_co_u32_e32 v133, vcc, 0, v99, vcc
	global_load_dwordx2 v[134:135], v[132:133], off offset:1664
	global_load_dwordx2 v[160:161], v[132:133], off offset:3712
	global_load_dwordx2 v[204:205], v[132:133], off offset:1696
	global_load_dwordx2 v[206:207], v[132:133], off offset:3744
	global_load_dwordx2 v[208:209], v[132:133], off offset:1728
	global_load_dwordx2 v[210:211], v[132:133], off offset:3776
	global_load_dwordx2 v[212:213], v[132:133], off offset:1760
	global_load_dwordx2 v[214:215], v[132:133], off offset:3808
	s_waitcnt vmcnt(0)
	v_lshlrev_b32_e32 v96, 16, v160
	v_mul_f32_e32 v96, 0xbfb8aa3b, v96
	v_exp_f32_e32 v162, v96
	v_lshlrev_b32_e32 v96, 16, v134
	v_mul_f32_e32 v96, 0xbfb8aa3b, v96
	v_exp_f32_e32 v96, v96
	s_nop 0
	v_add_f32_e32 v96, 1.0, v96
	v_rcp_f32_e32 v164, v96
	v_and_b32_e32 v96, 0xffff0000, v160
	v_mul_f32_e32 v96, 0xbfb8aa3b, v96
	v_exp_f32_e32 v163, v96
	v_and_b32_e32 v96, 0xffff0000, v134
	v_mul_f32_e32 v96, 0xbfb8aa3b, v96
	v_exp_f32_e32 v96, v96
	v_pk_add_f32 v[162:163], v[162:163], 1.0 op_sel_hi:[1,0]
	v_add_f32_e32 v96, 1.0, v96
	v_rcp_f32_e32 v165, v96
	v_lshlrev_b32_e32 v96, 16, v161
	v_mul_f32_e32 v96, 0xbfb8aa3b, v96
	v_exp_f32_e32 v160, v96
	v_lshlrev_b32_e32 v96, 16, v135
	v_mul_f32_e32 v96, 0xbfb8aa3b, v96
	v_exp_f32_e32 v96, v96
	v_pk_mul_f32 v[162:163], v[164:165], v[162:163]
	v_add_f32_e32 v96, 1.0, v96
	v_rcp_f32_e32 v134, v96
	v_and_b32_e32 v96, 0xffff0000, v161
	v_mul_f32_e32 v96, 0xbfb8aa3b, v96
	v_exp_f32_e32 v161, v96
	v_and_b32_e32 v96, 0xffff0000, v135
	v_mul_f32_e32 v96, 0xbfb8aa3b, v96
	v_exp_f32_e32 v96, v96
	v_pk_add_f32 v[160:161], v[160:161], 1.0 op_sel_hi:[1,0]
	v_pk_mul_f32 v[32:33], v[32:33], v[162:163]
	v_add_f32_e32 v96, 1.0, v96
	v_rcp_f32_e32 v135, v96
	s_nop 0
	v_pk_mul_f32 v[134:135], v[134:135], v[160:161]
	s_nop 0
	v_pk_mul_f32 v[34:35], v[34:35], v[134:135]
	v_mov_b32_e32 v134, v204
	v_mov_b32_e32 v135, v205
	v_mov_b32_e32 v160, v206
	v_mov_b32_e32 v161, v207
	s_waitcnt vmcnt(0)
	v_lshlrev_b32_e32 v96, 16, v160
	v_mul_f32_e32 v96, 0xbfb8aa3b, v96
	v_exp_f32_e32 v162, v96
	v_lshlrev_b32_e32 v96, 16, v134
	v_mul_f32_e32 v96, 0xbfb8aa3b, v96
	v_exp_f32_e32 v96, v96
	s_nop 0
	v_add_f32_e32 v96, 1.0, v96
	v_rcp_f32_e32 v164, v96
	v_and_b32_e32 v96, 0xffff0000, v160
	v_mul_f32_e32 v96, 0xbfb8aa3b, v96
	v_exp_f32_e32 v163, v96
	v_and_b32_e32 v96, 0xffff0000, v134
	v_mul_f32_e32 v96, 0xbfb8aa3b, v96
	v_exp_f32_e32 v96, v96
	v_pk_add_f32 v[162:163], v[162:163], 1.0 op_sel_hi:[1,0]
	v_add_f32_e32 v96, 1.0, v96
	v_rcp_f32_e32 v165, v96
	v_lshlrev_b32_e32 v96, 16, v161
	v_mul_f32_e32 v96, 0xbfb8aa3b, v96
	v_exp_f32_e32 v160, v96
	v_lshlrev_b32_e32 v96, 16, v135
	v_mul_f32_e32 v96, 0xbfb8aa3b, v96
	v_exp_f32_e32 v96, v96
	v_pk_mul_f32 v[162:163], v[164:165], v[162:163]
	v_add_f32_e32 v96, 1.0, v96
	v_rcp_f32_e32 v134, v96
	v_and_b32_e32 v96, 0xffff0000, v161
	v_mul_f32_e32 v96, 0xbfb8aa3b, v96
	v_exp_f32_e32 v161, v96
	v_and_b32_e32 v96, 0xffff0000, v135
	v_mul_f32_e32 v96, 0xbfb8aa3b, v96
	v_exp_f32_e32 v96, v96
	v_pk_add_f32 v[160:161], v[160:161], 1.0 op_sel_hi:[1,0]
	v_pk_mul_f32 v[24:25], v[24:25], v[162:163]
	v_add_f32_e32 v96, 1.0, v96
	v_rcp_f32_e32 v135, v96
	s_nop 0
	v_pk_mul_f32 v[134:135], v[134:135], v[160:161]
	s_nop 0
	v_pk_mul_f32 v[26:27], v[26:27], v[134:135]
	v_mov_b32_e32 v134, v208
	v_mov_b32_e32 v135, v209
	v_mov_b32_e32 v160, v210
	v_mov_b32_e32 v161, v211
	s_waitcnt vmcnt(0)
	v_lshlrev_b32_e32 v96, 16, v160
	v_mul_f32_e32 v96, 0xbfb8aa3b, v96
	v_exp_f32_e32 v162, v96
	v_lshlrev_b32_e32 v96, 16, v134
	v_mul_f32_e32 v96, 0xbfb8aa3b, v96
	v_exp_f32_e32 v96, v96
	s_nop 0
	v_add_f32_e32 v96, 1.0, v96
	v_rcp_f32_e32 v164, v96
	v_and_b32_e32 v96, 0xffff0000, v160
	v_mul_f32_e32 v96, 0xbfb8aa3b, v96
	v_exp_f32_e32 v163, v96
	v_and_b32_e32 v96, 0xffff0000, v134
	v_mul_f32_e32 v96, 0xbfb8aa3b, v96
	v_exp_f32_e32 v96, v96
	v_pk_add_f32 v[162:163], v[162:163], 1.0 op_sel_hi:[1,0]
	v_add_f32_e32 v96, 1.0, v96
	v_rcp_f32_e32 v165, v96
	v_lshlrev_b32_e32 v96, 16, v161
	v_mul_f32_e32 v96, 0xbfb8aa3b, v96
	v_exp_f32_e32 v160, v96
	v_lshlrev_b32_e32 v96, 16, v135
	v_mul_f32_e32 v96, 0xbfb8aa3b, v96
	v_exp_f32_e32 v96, v96
	v_pk_mul_f32 v[162:163], v[164:165], v[162:163]
	v_add_f32_e32 v96, 1.0, v96
	v_rcp_f32_e32 v134, v96
	v_and_b32_e32 v96, 0xffff0000, v161
	v_mul_f32_e32 v96, 0xbfb8aa3b, v96
	v_exp_f32_e32 v161, v96
	v_and_b32_e32 v96, 0xffff0000, v135
	v_mul_f32_e32 v96, 0xbfb8aa3b, v96
	v_exp_f32_e32 v96, v96
	v_pk_add_f32 v[160:161], v[160:161], 1.0 op_sel_hi:[1,0]
	v_pk_mul_f32 v[20:21], v[20:21], v[162:163]
	v_add_f32_e32 v96, 1.0, v96
	v_rcp_f32_e32 v135, v96
	s_nop 0
	v_pk_mul_f32 v[134:135], v[134:135], v[160:161]
	s_nop 0
	v_pk_mul_f32 v[22:23], v[22:23], v[134:135]
	v_mov_b32_e32 v134, v212
	v_mov_b32_e32 v135, v213
	s_nop 0
	v_mov_b32_e32 v132, v214
	v_mov_b32_e32 v133, v215
	s_waitcnt vmcnt(0)
; __device__ __forceinline__ float bflo(unsigned u) { return __uint_as_float(u << 16); }
; __device__ __forceinline__ float bfhi(unsigned u) { return __uint_as_float(u & 0xffff0000u); }
; __device__ void gemm2_phase(const Params& P, int layer, char* smem) {
;     ...
;             const uint2 ra = *(const uint2*)(pp + (size_t)(m * 16) * INC + C_RA + n * 16);
;             const uint2 rb = *(const uint2*)(pp + (size_t)(m * 16) * INC + C_RB + n * 16);
;             acc[m][n][0] *= (1.f + __expf(-bflo(rb.x))) * __builtin_amdgcn_rcpf(1.f + __expf(-bflo(ra.x)));
;             acc[m][n][1] *= (1.f + __expf(-bfhi(rb.x))) * __builtin_amdgcn_rcpf(1.f + __expf(-bfhi(ra.x)));
;             acc[m][n][2] *= (1.f + __expf(-bflo(rb.y))) * __builtin_amdgcn_rcpf(1.f + __expf(-bflo(ra.y)));
;             acc[m][n][3] *= (1.f + __expf(-bfhi(rb.y))) * __builtin_amdgcn_rcpf(1.f + __expf(-bfhi(ra.y)));
;           }
;           if (m & 1) __builtin_amdgcn_sched_barrier(0);
	v_lshlrev_b32_e32 v96, 16, v132
	v_mul_f32_e32 v96, 0xbfb8aa3b, v96
	v_exp_f32_e32 v160, v96
	v_lshlrev_b32_e32 v96, 16, v134
	v_mul_f32_e32 v96, 0xbfb8aa3b, v96
	v_exp_f32_e32 v96, v96
	s_nop 0
	v_add_f32_e32 v96, 1.0, v96
	v_rcp_f32_e32 v162, v96
	v_and_b32_e32 v96, 0xffff0000, v132
	v_mul_f32_e32 v96, 0xbfb8aa3b, v96
	v_exp_f32_e32 v161, v96
	v_and_b32_e32 v96, 0xffff0000, v134
	v_mul_f32_e32 v96, 0xbfb8aa3b, v96
	v_exp_f32_e32 v96, v96
	v_pk_add_f32 v[160:161], v[160:161], 1.0 op_sel_hi:[1,0]
	v_add_f32_e32 v96, 1.0, v96
	v_rcp_f32_e32 v163, v96
	v_lshlrev_b32_e32 v96, 16, v133
	v_mul_f32_e32 v96, 0xbfb8aa3b, v96
	v_exp_f32_e32 v132, v96
	v_lshlrev_b32_e32 v96, 16, v135
	v_mul_f32_e32 v96, 0xbfb8aa3b, v96
	v_exp_f32_e32 v96, v96
	v_pk_mul_f32 v[160:161], v[162:163], v[160:161]
	v_add_f32_e32 v96, 1.0, v96
	v_rcp_f32_e32 v134, v96
	v_and_b32_e32 v96, 0xffff0000, v133
	v_mul_f32_e32 v96, 0xbfb8aa3b, v96
	v_exp_f32_e32 v133, v96
	v_and_b32_e32 v96, 0xffff0000, v135
	v_mul_f32_e32 v96, 0xbfb8aa3b, v96
	v_exp_f32_e32 v96, v96
	v_pk_add_f32 v[132:133], v[132:133], 1.0 op_sel_hi:[1,0]
	v_pk_mul_f32 v[4:5], v[4:5], v[160:161]
	v_add_f32_e32 v96, 1.0, v96
	v_rcp_f32_e32 v135, v96
	s_nop 0
	v_pk_mul_f32 v[132:133], v[134:135], v[132:133]
	s_nop 0
	v_pk_mul_f32 v[6:7], v[6:7], v[132:133]
	v_add_co_u32_e32 v132, vcc, s22, v98
	s_mov_b32 s22, 0x1f0000
	s_nop 0
	v_addc_co_u32_e32 v133, vcc, 0, v99, vcc
	v_add_co_u32_e32 v98, vcc, s22, v98
	global_load_dwordx2 v[134:135], v[132:133], off offset:1696
	s_nop 0
	v_addc_co_u32_e32 v99, vcc, 0, v99, vcc
	global_load_dwordx2 v[160:161], v[98:99], off offset:3744
	global_load_dwordx2 v[162:163], v[132:133], off offset:1664
	global_load_dwordx2 v[164:165], v[98:99], off offset:3712
	s_waitcnt vmcnt(1)
	v_lshlrev_b32_e32 v96, 16, v162
	v_mul_f32_e32 v96, 0xbfb8aa3b, v96
	v_exp_f32_e32 v166, v96
	s_waitcnt vmcnt(0)
	v_lshlrev_b32_e32 v96, 16, v164
	v_mul_f32_e32 v96, 0xbfb8aa3b, v96
	v_exp_f32_e32 v96, v96
	s_nop 0
	v_add_f32_e32 v96, 1.0, v96
	v_rcp_f32_e32 v168, v96
	v_and_b32_e32 v96, 0xffff0000, v162
	v_mul_f32_e32 v96, 0xbfb8aa3b, v96
	v_exp_f32_e32 v167, v96
	v_and_b32_e32 v96, 0xffff0000, v164
	v_mul_f32_e32 v96, 0xbfb8aa3b, v96
	v_exp_f32_e32 v96, v96
	v_pk_add_f32 v[166:167], v[166:167], 1.0 op_sel_hi:[1,0]
	v_add_f32_e32 v96, 1.0, v96
	v_rcp_f32_e32 v169, v96
	v_lshlrev_b32_e32 v96, 16, v163
	v_mul_f32_e32 v96, 0xbfb8aa3b, v96
	v_exp_f32_e32 v162, v96
	v_lshlrev_b32_e32 v96, 16, v165
	v_mul_f32_e32 v96, 0xbfb8aa3b, v96
	v_exp_f32_e32 v96, v96
	v_pk_mul_f32 v[166:167], v[166:167], v[168:169]
	v_add_f32_e32 v96, 1.0, v96
	v_rcp_f32_e32 v164, v96
	v_and_b32_e32 v96, 0xffff0000, v163
	v_mul_f32_e32 v96, 0xbfb8aa3b, v96
	v_exp_f32_e32 v163, v96
	v_and_b32_e32 v96, 0xffff0000, v165
	v_mul_f32_e32 v96, 0xbfb8aa3b, v96
	v_exp_f32_e32 v96, v96
	v_pk_add_f32 v[162:163], v[162:163], 1.0 op_sel_hi:[1,0]
	v_pk_mul_f32 v[16:17], v[16:17], v[166:167]
	v_add_f32_e32 v96, 1.0, v96
	v_rcp_f32_e32 v165, v96
	v_lshlrev_b32_e32 v96, 16, v134
	v_mul_f32_e32 v96, 0xbfb8aa3b, v96
	v_pk_mul_f32 v[162:163], v[162:163], v[164:165]
	s_nop 0
	v_pk_mul_f32 v[18:19], v[18:19], v[162:163]
	v_exp_f32_e32 v162, v96
	v_lshlrev_b32_e32 v96, 16, v160
	v_mul_f32_e32 v96, 0xbfb8aa3b, v96
	v_exp_f32_e32 v96, v96
	s_nop 0
	v_add_f32_e32 v96, 1.0, v96
	v_rcp_f32_e32 v164, v96
	v_and_b32_e32 v96, 0xffff0000, v134
	v_mul_f32_e32 v96, 0xbfb8aa3b, v96
	v_exp_f32_e32 v163, v96
	v_and_b32_e32 v96, 0xffff0000, v160
	v_mul_f32_e32 v96, 0xbfb8aa3b, v96
	v_exp_f32_e32 v96, v96
	v_pk_add_f32 v[162:163], v[162:163], 1.0 op_sel_hi:[1,0]
	v_add_f32_e32 v96, 1.0, v96
	v_rcp_f32_e32 v165, v96
	v_lshlrev_b32_e32 v96, 16, v135
	v_mul_f32_e32 v96, 0xbfb8aa3b, v96
	v_exp_f32_e32 v134, v96
	v_lshlrev_b32_e32 v96, 16, v161
	v_mul_f32_e32 v96, 0xbfb8aa3b, v96
	v_exp_f32_e32 v96, v96
	v_pk_mul_f32 v[162:163], v[162:163], v[164:165]
	v_add_f32_e32 v96, 1.0, v96
	v_rcp_f32_e32 v160, v96
	v_and_b32_e32 v96, 0xffff0000, v135
	v_mul_f32_e32 v96, 0xbfb8aa3b, v96
	v_exp_f32_e32 v135, v96
	v_and_b32_e32 v96, 0xffff0000, v161
	v_mul_f32_e32 v96, 0xbfb8aa3b, v96
	v_exp_f32_e32 v96, v96
	v_pk_add_f32 v[134:135], v[134:135], 1.0 op_sel_hi:[1,0]
	v_pk_mul_f32 v[12:13], v[12:13], v[162:163]
	v_add_f32_e32 v96, 1.0, v96
	v_rcp_f32_e32 v161, v96
	s_nop 0
	v_pk_mul_f32 v[134:135], v[134:135], v[160:161]
	s_nop 0
	v_pk_mul_f32 v[14:15], v[14:15], v[134:135]
	global_load_dwordx2 v[134:135], v[98:99], off offset:3776
	global_load_dwordx2 v[160:161], v[132:133], off offset:1728
	s_waitcnt vmcnt(0)
; __device__ __forceinline__ float bflo(unsigned u) { return __uint_as_float(u << 16); }
; __device__ __forceinline__ float bfhi(unsigned u) { return __uint_as_float(u & 0xffff0000u); }
; __device__ void gemm2_phase(const Params& P, int layer, char* smem) {
;     ...
;     for (int pass = 0; pass < 2; pass++) {
;     ...
;             const uint2 ra = *(const uint2*)(pp + (size_t)(m * 16) * INC + C_RA + n * 16);
;             const uint2 rb = *(const uint2*)(pp + (size_t)(m * 16) * INC + C_RB + n * 16);
;             acc[m][n][0] *= (1.f + __expf(-bflo(rb.x))) * __builtin_amdgcn_rcpf(1.f + __expf(-bflo(ra.x)));
;             acc[m][n][1] *= (1.f + __expf(-bfhi(rb.x))) * __builtin_amdgcn_rcpf(1.f + __expf(-bfhi(ra.x)));
;             acc[m][n][2] *= (1.f + __expf(-bflo(rb.y))) * __builtin_amdgcn_rcpf(1.f + __expf(-bflo(ra.y)));
;             acc[m][n][3] *= (1.f + __expf(-bfhi(rb.y))) * __builtin_amdgcn_rcpf(1.f + __expf(-bfhi(ra.y)));
;           }
;           if (m & 1) __builtin_amdgcn_sched_barrier(0);
	v_lshlrev_b32_e32 v96, 16, v160
	v_mul_f32_e32 v96, 0xbfb8aa3b, v96
	v_exp_f32_e32 v162, v96
	v_lshlrev_b32_e32 v96, 16, v134
	v_mul_f32_e32 v96, 0xbfb8aa3b, v96
	v_exp_f32_e32 v96, v96
	s_nop 0
	v_add_f32_e32 v96, 1.0, v96
	v_rcp_f32_e32 v164, v96
	v_and_b32_e32 v96, 0xffff0000, v160
	v_mul_f32_e32 v96, 0xbfb8aa3b, v96
	v_exp_f32_e32 v163, v96
	v_and_b32_e32 v96, 0xffff0000, v134
	v_mul_f32_e32 v96, 0xbfb8aa3b, v96
	v_exp_f32_e32 v96, v96
	v_pk_add_f32 v[162:163], v[162:163], 1.0 op_sel_hi:[1,0]
	v_add_f32_e32 v96, 1.0, v96
	v_rcp_f32_e32 v165, v96
	v_lshlrev_b32_e32 v96, 16, v161
	v_mul_f32_e32 v96, 0xbfb8aa3b, v96
	v_exp_f32_e32 v160, v96
	v_lshlrev_b32_e32 v96, 16, v135
	v_mul_f32_e32 v96, 0xbfb8aa3b, v96
	v_exp_f32_e32 v96, v96
	v_pk_mul_f32 v[162:163], v[164:165], v[162:163]
	v_add_f32_e32 v96, 1.0, v96
	v_rcp_f32_e32 v134, v96
	v_and_b32_e32 v96, 0xffff0000, v161
	v_mul_f32_e32 v96, 0xbfb8aa3b, v96
	v_exp_f32_e32 v161, v96
	v_and_b32_e32 v96, 0xffff0000, v135
	v_mul_f32_e32 v96, 0xbfb8aa3b, v96
	v_exp_f32_e32 v96, v96
	v_pk_add_f32 v[160:161], v[160:161], 1.0 op_sel_hi:[1,0]
	v_pk_mul_f32 v[8:9], v[8:9], v[162:163]
	v_add_f32_e32 v96, 1.0, v96
	v_rcp_f32_e32 v135, v96
	s_nop 0
	v_pk_mul_f32 v[134:135], v[134:135], v[160:161]
	s_nop 0
	v_pk_mul_f32 v[10:11], v[10:11], v[134:135]
	global_load_dwordx2 v[134:135], v[98:99], off offset:3808
	s_nop 0
	global_load_dwordx2 v[132:133], v[132:133], off offset:1760
	s_waitcnt vmcnt(0)
	v_lshlrev_b32_e32 v96, 16, v132
	v_mul_f32_e32 v96, 0xbfb8aa3b, v96
	v_exp_f32_e32 v98, v96
	v_lshlrev_b32_e32 v96, 16, v134
	v_mul_f32_e32 v96, 0xbfb8aa3b, v96
	v_exp_f32_e32 v96, v96
	s_nop 0
	v_add_f32_e32 v96, 1.0, v96
	v_rcp_f32_e32 v160, v96
	v_and_b32_e32 v96, 0xffff0000, v132
	v_mul_f32_e32 v96, 0xbfb8aa3b, v96
	v_exp_f32_e32 v99, v96
	v_and_b32_e32 v96, 0xffff0000, v134
	v_mul_f32_e32 v96, 0xbfb8aa3b, v96
	v_exp_f32_e32 v96, v96
	v_pk_add_f32 v[98:99], v[98:99], 1.0 op_sel_hi:[1,0]
	v_add_f32_e32 v96, 1.0, v96
	v_rcp_f32_e32 v161, v96
	v_lshlrev_b32_e32 v96, 16, v133
	v_mul_f32_e32 v96, 0xbfb8aa3b, v96
	v_exp_f32_e32 v132, v96
	v_lshlrev_b32_e32 v96, 16, v135
	v_mul_f32_e32 v96, 0xbfb8aa3b, v96
	v_exp_f32_e32 v96, v96
	v_pk_mul_f32 v[98:99], v[160:161], v[98:99]
	v_add_f32_e32 v96, 1.0, v96
	v_rcp_f32_e32 v134, v96
	v_and_b32_e32 v96, 0xffff0000, v133
	v_mul_f32_e32 v96, 0xbfb8aa3b, v96
	v_exp_f32_e32 v133, v96
	v_and_b32_e32 v96, 0xffff0000, v135
	v_mul_f32_e32 v96, 0xbfb8aa3b, v96
	v_exp_f32_e32 v96, v96
	v_pk_add_f32 v[132:133], v[132:133], 1.0 op_sel_hi:[1,0]
	v_pk_mul_f32 v[0:1], v[0:1], v[98:99]
	v_add_f32_e32 v96, 1.0, v96
	v_rcp_f32_e32 v135, v96
	s_nop 0
	v_pk_mul_f32 v[132:133], v[134:135], v[132:133]
	s_nop 0
	v_pk_mul_f32 v[2:3], v[2:3], v[132:133]
	s_branch .LBB0_594
